# v31: v25 + the 52 redundant post-barrier lgkmcnt(0) waits hipcc left at the head of each MFMA block in the GEMM K-loops removed
# baseline (speedup 1.0000x reference)
; #define PG8_STAGE(bufoff, gbase, voff) do { _Pragma("unroll") for (int _i = 0; _i < 2; ++_i) \
;         __builtin_amdgcn_global_load_lds((const unsigned*)((const char*)(gbase) + (voff)[_i]), (PG8_LAS unsigned*)(lds + (bufoff) + ldsw + _i * 8192), 16, 0, 0); } while (0)
; #define PG8_LDA(dst, b, h) do { _Pragma("unroll") for (int m = 0; m < 4; ++m) _Pragma("unroll") for (int k = 0; k < 2; ++k) dst[m][k] = *(const PG8_LAS bf16x8*)(lds + PG8_SA(b, h) + aoff + m * 2048 + k * 1024); } while (0)
; #define PG8_LDB(dst, b, h) do { _Pragma("unroll") for (int n = 0; n < 2; ++n) _Pragma("unroll") for (int k = 0; k < 2; ++k) dst[n][k] = *(const PG8_LAS bf16x8*)(lds + PG8_SB(b, h) + boff + n * 2048 + k * 1024); } while (0)
; #define PG8_MMA(ai, bj, At, Bt) do { __builtin_amdgcn_s_setprio(1); _Pragma("unroll") for (int m = 0; m < 4; ++m) _Pragma("unroll") for (int n = 0; n < 2; ++n) _Pragma("unroll") for (int k = 0; k < 2; ++k) \
;         acc[ai][bj][m][n] = __builtin_amdgcn_mfma_f32_16x16x32_bf16(Bt[n][k], At[m][k], acc[ai][bj][m][n], 0, 0, 0); __builtin_amdgcn_s_setprio(0); } while (0)
; #define PG8_WAIT_V(n) asm volatile("s_waitcnt vmcnt(" #n ")" ::: "memory")
; #define PG8_WAIT_L(n) asm volatile("s_waitcnt lgkmcnt(" #n ")" ::: "memory")
; #define PG8_BAR __builtin_amdgcn_s_barrier()
; #define PG8_SCHED __builtin_amdgcn_sched_barrier(0)
; template <class Epi, class Sched, bool ALIGN_EPI = false, bool SP2 = false>
; __device__ __forceinline__ void gemm_phase(PG8_LAS unsigned char* lds, const Gemm g, const Sched& S, const Epi& E) {
;     ...
;             const bool last = (t == nt - 2);
;             const char* a1 = cA + (size_t)(t + 1) * kstep;
;             const char* a2 = last ? nA : cA + (size_t)(t + 2) * kstep; const char* b2 = last ? nB : cB + (size_t)(t + 2) * kstep;
;             const char* a3 = a2 + kstep; const char* b3 = b2 + kstep;
;             if (last && has_next) S.a_ready(nxt);
;             if constexpr (SP2) {
;             PG8_LDB(B0, 0, 0); PG8_LDB(B1, 0, 1); PG8_SCHED; PG8_LDA(At, 0, 0); PG8_STAGE(PG8_SA(1, 1), a1 + hstepA, voffA);
;             PG8_WAIT_V(8); PG8_WAIT_L(0); PG8_BAR; PG8_MMA(0, 0, At, B0); PG8_MMA(0, 1, At, B1); PG8_BAR; PG8_SCHED;
;             PG8_LDA(At, 0, 1); PG8_STAGE(PG8_SB(0, 0), b2, voffB); PG8_STAGE(PG8_SB(0, 1), b2 + hstepB, voffB); PG8_STAGE(PG8_SA(0, 0), a2, voffA);
.LBB0_304:
	s_add_u32 s20, s18, 0xfffc0080
	s_addc_u32 s21, s19, -1
	s_add_i32 s25, 0, 0x10000
	s_cmp_eq_u32 s24, 12
	s_cselect_b32 s31, s6, s21
	s_cselect_b32 s30, s7, s20
	v_add_u32_e32 v64, s25, v175
	s_cselect_b32 s21, s11, s23
	s_cselect_b32 s20, s13, s22
	s_add_i32 s41, 0, 0x14000
	ds_read_b128 v[130:133], v64
	ds_read_b128 v[134:137], v64 offset:1024
	ds_read_b128 v[138:141], v64 offset:2048
	ds_read_b128 v[142:145], v64 offset:3072
	v_add_u32_e32 v64, s41, v175
	ds_read_b128 v[158:161], v64
	ds_read_b128 v[162:165], v64 offset:1024
	ds_read_b128 v[166:169], v64 offset:2048
	ds_read_b128 v[178:181], v64 offset:3072
	v_lshl_add_u64 v[172:173], s[18:19], 0, v[154:155]
	s_add_i32 m0, s63, 0xc000
	ds_read_b128 v[184:187], v183
	ds_read_b128 v[188:191], v183 offset:1024
	ds_read_b128 v[192:195], v183 offset:2048
	ds_read_b128 v[210:213], v183 offset:3072
	ds_read_b128 v[214:217], v183 offset:4096
	ds_read_b128 v[218:221], v183 offset:5120
	ds_read_b128 v[242:245], v183 offset:6144
	ds_read_b128 v[246:249], v183 offset:7168
	global_load_lds_dwordx4 v[172:173], off
	v_lshl_add_u64 v[172:173], s[18:19], 0, v[156:157]
	s_add_i32 m0, s63, 0xe000
	s_nop 0
	global_load_lds_dwordx4 v[172:173], off
	s_waitcnt vmcnt(8)
	s_waitcnt lgkmcnt(0)
	s_barrier
	s_setprio 1
	v_mfma_f32_16x16x32_bf16 v[126:129], v[130:133], v[184:187], v[126:129]
	v_mfma_f32_16x16x32_bf16 v[122:125], v[138:141], v[184:187], v[122:125]
	v_mfma_f32_16x16x32_bf16 v[110:113], v[130:133], v[192:195], v[110:113]
	v_mfma_f32_16x16x32_bf16 v[106:109], v[138:141], v[192:195], v[106:109]
	v_mfma_f32_16x16x32_bf16 v[94:97], v[130:133], v[214:217], v[94:97]
	v_mfma_f32_16x16x32_bf16 v[90:93], v[138:141], v[214:217], v[90:93]
	v_mfma_f32_16x16x32_bf16 v[78:81], v[130:133], v[242:245], v[78:81]
	v_mfma_f32_16x16x32_bf16 v[74:77], v[138:141], v[242:245], v[74:77]
	v_mfma_f32_16x16x32_bf16 v[126:129], v[134:137], v[188:191], v[126:129]
	v_mfma_f32_16x16x32_bf16 v[122:125], v[142:145], v[188:191], v[122:125]
	v_mfma_f32_16x16x32_bf16 v[110:113], v[134:137], v[210:213], v[110:113]
	v_mfma_f32_16x16x32_bf16 v[106:109], v[142:145], v[210:213], v[106:109]
	v_mfma_f32_16x16x32_bf16 v[94:97], v[134:137], v[218:221], v[94:97]
	v_mfma_f32_16x16x32_bf16 v[90:93], v[142:145], v[218:221], v[90:93]
	v_mfma_f32_16x16x32_bf16 v[78:81], v[134:137], v[246:249], v[78:81]
	v_mfma_f32_16x16x32_bf16 v[74:77], v[142:145], v[246:249], v[74:77]
	s_setprio 0
	s_setprio 1
	v_mfma_f32_16x16x32_bf16 v[118:121], v[158:161], v[184:187], v[118:121]
	v_mfma_f32_16x16x32_bf16 v[114:117], v[166:169], v[184:187], v[114:117]
	v_mfma_f32_16x16x32_bf16 v[102:105], v[158:161], v[192:195], v[102:105]
	v_mfma_f32_16x16x32_bf16 v[98:101], v[166:169], v[192:195], v[98:101]
	v_mfma_f32_16x16x32_bf16 v[86:89], v[158:161], v[214:217], v[86:89]
	v_mfma_f32_16x16x32_bf16 v[82:85], v[166:169], v[214:217], v[82:85]
	v_mfma_f32_16x16x32_bf16 v[70:73], v[158:161], v[242:245], v[70:73]
	v_mfma_f32_16x16x32_bf16 v[66:69], v[166:169], v[242:245], v[66:69]
	v_mfma_f32_16x16x32_bf16 v[118:121], v[162:165], v[188:191], v[118:121]
	v_mfma_f32_16x16x32_bf16 v[114:117], v[178:181], v[188:191], v[114:117]
	v_mfma_f32_16x16x32_bf16 v[102:105], v[162:165], v[210:213], v[102:105]
	v_mfma_f32_16x16x32_bf16 v[98:101], v[178:181], v[210:213], v[98:101]
	v_mfma_f32_16x16x32_bf16 v[86:89], v[162:165], v[218:221], v[86:89]
	v_mfma_f32_16x16x32_bf16 v[82:85], v[178:181], v[218:221], v[82:85]
	v_mfma_f32_16x16x32_bf16 v[70:73], v[162:165], v[246:249], v[70:73]
	v_mfma_f32_16x16x32_bf16 v[66:69], v[178:181], v[246:249], v[66:69]
	s_setprio 0
	s_barrier
	s_add_i32 s25, s25, s45
	v_lshl_add_u64 v[172:173], s[20:21], 0, v[150:151]
	s_mov_b32 m0, s25
	ds_read_b128 v[184:187], v183 offset:16384
	ds_read_b128 v[188:191], v183 offset:17408
	ds_read_b128 v[192:195], v183 offset:18432
	ds_read_b128 v[210:213], v183 offset:19456
	ds_read_b128 v[214:217], v183 offset:20480
	ds_read_b128 v[218:221], v183 offset:21504
	ds_read_b128 v[242:245], v183 offset:22528
	ds_read_b128 v[246:249], v183 offset:23552
	global_load_lds_dwordx4 v[172:173], off
	s_add_i32 m0, s25, 0x2000
	s_add_u32 s60, s20, 0x40000
	v_lshl_add_u64 v[222:223], s[20:21], 0, v[146:147]
	s_addc_u32 s61, s21, 0
	s_add_i32 s25, s41, s45
	global_load_lds_dwordx4 v[222:223], off
	v_lshl_add_u64 v[250:251], s[60:61], 0, v[150:151]
	s_mov_b32 m0, s25
	v_lshl_add_u64 v[252:253], s[30:31], 0, v[148:149]
	global_load_lds_dwordx4 v[250:251], off
	v_lshl_add_u64 v[250:251], s[60:61], 0, v[146:147]
	s_add_i32 m0, s25, 0x2000
	s_nop 0
	global_load_lds_dwordx4 v[250:251], off
	v_lshl_add_u64 v[250:251], s[30:31], 0, v[152:153]
	s_mov_b32 m0, s63
	s_nop 0
	global_load_lds_dwordx4 v[250:251], off
	s_mov_b32 m0, s64
	s_nop 0
	global_load_lds_dwordx4 v[252:253], off
	s_waitcnt vmcnt(8)
	s_waitcnt lgkmcnt(0)
	s_barrier
; #define PG8_STAGE(bufoff, gbase, voff) do { _Pragma("unroll") for (int _i = 0; _i < 2; ++_i) \
;         __builtin_amdgcn_global_load_lds((const unsigned*)((const char*)(gbase) + (voff)[_i]), (PG8_LAS unsigned*)(lds + (bufoff) + ldsw + _i * 8192), 16, 0, 0); } while (0)
; #define PG8_LDA(dst, b, h) do { _Pragma("unroll") for (int m = 0; m < 4; ++m) _Pragma("unroll") for (int k = 0; k < 2; ++k) dst[m][k] = *(const PG8_LAS bf16x8*)(lds + PG8_SA(b, h) + aoff + m * 2048 + k * 1024); } while (0)
; #define PG8_LDB(dst, b, h) do { _Pragma("unroll") for (int n = 0; n < 2; ++n) _Pragma("unroll") for (int k = 0; k < 2; ++k) dst[n][k] = *(const PG8_LAS bf16x8*)(lds + PG8_SB(b, h) + boff + n * 2048 + k * 1024); } while (0)
; #define PG8_MMA(ai, bj, At, Bt) do { __builtin_amdgcn_s_setprio(1); _Pragma("unroll") for (int m = 0; m < 4; ++m) _Pragma("unroll") for (int n = 0; n < 2; ++n) _Pragma("unroll") for (int k = 0; k < 2; ++k) \
;         acc[ai][bj][m][n] = __builtin_amdgcn_mfma_f32_16x16x32_bf16(Bt[n][k], At[m][k], acc[ai][bj][m][n], 0, 0, 0); __builtin_amdgcn_s_setprio(0); } while (0)
; #define PG8_WAIT_V(n) asm volatile("s_waitcnt vmcnt(" #n ")" ::: "memory")
; #define PG8_WAIT_L(n) asm volatile("s_waitcnt lgkmcnt(" #n ")" ::: "memory")
; #define PG8_BAR __builtin_amdgcn_s_barrier()
; #define PG8_SCHED __builtin_amdgcn_sched_barrier(0)
; template <class Epi, class Sched, bool ALIGN_EPI = false, bool SP2 = false>
; __device__ __forceinline__ void gemm_phase(PG8_LAS unsigned char* lds, const Gemm g, const Sched& S, const Epi& E) {
;     ...
;             PG8_WAIT_V(8); PG8_WAIT_L(0); PG8_BAR; PG8_MMA(1, 0, At, B0); PG8_MMA(1, 1, At, B1); PG8_BAR; PG8_SCHED;
;             PG8_LDB(B0, 1, 0); PG8_LDB(B1, 1, 1); PG8_SCHED; PG8_LDA(At, 1, 0); PG8_STAGE(PG8_SA(0, 1), a2 + hstepA, voffA);
;             PG8_WAIT_V(8); PG8_WAIT_L(0); PG8_BAR; PG8_MMA(0, 0, At, B0); PG8_MMA(0, 1, At, B1); PG8_BAR; PG8_SCHED;
	s_setprio 1
	v_mfma_f32_16x16x32_bf16 v[60:63], v[130:133], v[184:187], v[60:63]
	v_mfma_f32_16x16x32_bf16 v[56:59], v[138:141], v[184:187], v[56:59]
	v_mfma_f32_16x16x32_bf16 v[44:47], v[130:133], v[192:195], v[44:47]
	v_mfma_f32_16x16x32_bf16 v[40:43], v[138:141], v[192:195], v[40:43]
	v_mfma_f32_16x16x32_bf16 v[28:31], v[130:133], v[214:217], v[28:31]
	v_mfma_f32_16x16x32_bf16 v[24:27], v[138:141], v[214:217], v[24:27]
	v_mfma_f32_16x16x32_bf16 v[12:15], v[130:133], v[242:245], v[12:15]
	v_mfma_f32_16x16x32_bf16 v[8:11], v[138:141], v[242:245], v[8:11]
	v_mfma_f32_16x16x32_bf16 v[60:63], v[134:137], v[188:191], v[60:63]
	v_mfma_f32_16x16x32_bf16 v[56:59], v[142:145], v[188:191], v[56:59]
	v_mfma_f32_16x16x32_bf16 v[44:47], v[134:137], v[210:213], v[44:47]
	v_mfma_f32_16x16x32_bf16 v[40:43], v[142:145], v[210:213], v[40:43]
	v_mfma_f32_16x16x32_bf16 v[28:31], v[134:137], v[218:221], v[28:31]
	v_mfma_f32_16x16x32_bf16 v[24:27], v[142:145], v[218:221], v[24:27]
	v_mfma_f32_16x16x32_bf16 v[12:15], v[134:137], v[246:249], v[12:15]
	v_mfma_f32_16x16x32_bf16 v[8:11], v[142:145], v[246:249], v[8:11]
	s_setprio 0
	s_setprio 1
	v_mfma_f32_16x16x32_bf16 v[52:55], v[158:161], v[184:187], v[52:55]
	v_mfma_f32_16x16x32_bf16 v[48:51], v[166:169], v[184:187], v[48:51]
	v_mfma_f32_16x16x32_bf16 v[36:39], v[158:161], v[192:195], v[36:39]
	v_mfma_f32_16x16x32_bf16 v[32:35], v[166:169], v[192:195], v[32:35]
	v_mfma_f32_16x16x32_bf16 v[20:23], v[158:161], v[214:217], v[20:23]
	v_mfma_f32_16x16x32_bf16 v[16:19], v[166:169], v[214:217], v[16:19]
	v_mfma_f32_16x16x32_bf16 v[4:7], v[158:161], v[242:245], v[4:7]
	v_mfma_f32_16x16x32_bf16 v[0:3], v[166:169], v[242:245], v[0:3]
	v_mfma_f32_16x16x32_bf16 v[52:55], v[162:165], v[188:191], v[52:55]
	v_mfma_f32_16x16x32_bf16 v[48:51], v[178:181], v[188:191], v[48:51]
	v_mfma_f32_16x16x32_bf16 v[36:39], v[162:165], v[210:213], v[36:39]
	v_mfma_f32_16x16x32_bf16 v[32:35], v[178:181], v[210:213], v[32:35]
	v_mfma_f32_16x16x32_bf16 v[20:23], v[162:165], v[218:221], v[20:23]
	v_mfma_f32_16x16x32_bf16 v[16:19], v[178:181], v[218:221], v[16:19]
	v_mfma_f32_16x16x32_bf16 v[4:7], v[162:165], v[246:249], v[4:7]
	v_mfma_f32_16x16x32_bf16 v[0:3], v[178:181], v[246:249], v[0:3]
	s_setprio 0
	s_barrier
	s_add_i32 s25, 0, 0x18000
	v_add_u32_e32 v64, s25, v175
	s_add_i32 s41, 0, 0x1c000
	ds_read_b128 v[130:133], v64
	ds_read_b128 v[134:137], v64 offset:1024
	ds_read_b128 v[138:141], v64 offset:2048
	ds_read_b128 v[142:145], v64 offset:3072
	v_add_u32_e32 v64, s41, v175
	ds_read_b128 v[158:161], v64
	ds_read_b128 v[162:165], v64 offset:1024
	ds_read_b128 v[166:169], v64 offset:2048
	ds_read_b128 v[178:181], v64 offset:3072
	s_add_u32 s30, s30, 0x40000
	s_addc_u32 s31, s31, 0
	s_mov_b32 m0, s65
	v_lshl_add_u64 v[230:231], s[30:31], 0, v[152:153]
	ds_read_b128 v[184:187], v183 offset:32768
	ds_read_b128 v[188:191], v183 offset:33792
	ds_read_b128 v[192:195], v183 offset:34816
	ds_read_b128 v[210:213], v183 offset:35840
	ds_read_b128 v[214:217], v183 offset:36864
	ds_read_b128 v[218:221], v183 offset:37888
	ds_read_b128 v[242:245], v183 offset:38912
	ds_read_b128 v[246:249], v183 offset:39936
	global_load_lds_dwordx4 v[230:231], off
	v_lshl_add_u64 v[230:231], s[30:31], 0, v[148:149]
	s_mov_b32 m0, s68
	s_nop 0
	global_load_lds_dwordx4 v[230:231], off
	s_waitcnt vmcnt(8)
	s_waitcnt lgkmcnt(0)
	s_barrier
	s_setprio 1
	v_mfma_f32_16x16x32_bf16 v[126:129], v[130:133], v[184:187], v[126:129]
	v_mfma_f32_16x16x32_bf16 v[122:125], v[138:141], v[184:187], v[122:125]
	v_mfma_f32_16x16x32_bf16 v[110:113], v[130:133], v[192:195], v[110:113]
	v_mfma_f32_16x16x32_bf16 v[106:109], v[138:141], v[192:195], v[106:109]
	v_mfma_f32_16x16x32_bf16 v[94:97], v[130:133], v[214:217], v[94:97]
	v_mfma_f32_16x16x32_bf16 v[90:93], v[138:141], v[214:217], v[90:93]
	v_mfma_f32_16x16x32_bf16 v[78:81], v[130:133], v[242:245], v[78:81]
	v_mfma_f32_16x16x32_bf16 v[74:77], v[138:141], v[242:245], v[74:77]
	v_mfma_f32_16x16x32_bf16 v[126:129], v[134:137], v[188:191], v[126:129]
	v_mfma_f32_16x16x32_bf16 v[122:125], v[142:145], v[188:191], v[122:125]
	v_mfma_f32_16x16x32_bf16 v[110:113], v[134:137], v[210:213], v[110:113]
	v_mfma_f32_16x16x32_bf16 v[106:109], v[142:145], v[210:213], v[106:109]
	v_mfma_f32_16x16x32_bf16 v[94:97], v[134:137], v[218:221], v[94:97]
	v_mfma_f32_16x16x32_bf16 v[90:93], v[142:145], v[218:221], v[90:93]
	v_mfma_f32_16x16x32_bf16 v[78:81], v[134:137], v[246:249], v[78:81]
	v_mfma_f32_16x16x32_bf16 v[74:77], v[142:145], v[246:249], v[74:77]
	s_setprio 0
	s_setprio 1
	v_mfma_f32_16x16x32_bf16 v[118:121], v[158:161], v[184:187], v[118:121]
	v_mfma_f32_16x16x32_bf16 v[114:117], v[166:169], v[184:187], v[114:117]
	v_mfma_f32_16x16x32_bf16 v[102:105], v[158:161], v[192:195], v[102:105]
	v_mfma_f32_16x16x32_bf16 v[98:101], v[166:169], v[192:195], v[98:101]
	v_mfma_f32_16x16x32_bf16 v[86:89], v[158:161], v[214:217], v[86:89]
	v_mfma_f32_16x16x32_bf16 v[82:85], v[166:169], v[214:217], v[82:85]
	v_mfma_f32_16x16x32_bf16 v[70:73], v[158:161], v[242:245], v[70:73]
	v_mfma_f32_16x16x32_bf16 v[66:69], v[166:169], v[242:245], v[66:69]
	v_mfma_f32_16x16x32_bf16 v[118:121], v[162:165], v[188:191], v[118:121]
	v_mfma_f32_16x16x32_bf16 v[114:117], v[178:181], v[188:191], v[114:117]
	v_mfma_f32_16x16x32_bf16 v[102:105], v[162:165], v[210:213], v[102:105]
	v_mfma_f32_16x16x32_bf16 v[98:101], v[178:181], v[210:213], v[98:101]
	v_mfma_f32_16x16x32_bf16 v[86:89], v[162:165], v[218:221], v[86:89]
	v_mfma_f32_16x16x32_bf16 v[82:85], v[178:181], v[218:221], v[82:85]
	v_mfma_f32_16x16x32_bf16 v[70:73], v[162:165], v[246:249], v[70:73]
	v_mfma_f32_16x16x32_bf16 v[66:69], v[178:181], v[246:249], v[66:69]
	s_setprio 0
	s_barrier
; #define PG8_STAGE(bufoff, gbase, voff) do { _Pragma("unroll") for (int _i = 0; _i < 2; ++_i) \
;         __builtin_amdgcn_global_load_lds((const unsigned*)((const char*)(gbase) + (voff)[_i]), (PG8_LAS unsigned*)(lds + (bufoff) + ldsw + _i * 8192), 16, 0, 0); } while (0)
; #define PG8_LDA(dst, b, h) do { _Pragma("unroll") for (int m = 0; m < 4; ++m) _Pragma("unroll") for (int k = 0; k < 2; ++k) dst[m][k] = *(const PG8_LAS bf16x8*)(lds + PG8_SA(b, h) + aoff + m * 2048 + k * 1024); } while (0)
; #define PG8_MMA(ai, bj, At, Bt) do { __builtin_amdgcn_s_setprio(1); _Pragma("unroll") for (int m = 0; m < 4; ++m) _Pragma("unroll") for (int n = 0; n < 2; ++n) _Pragma("unroll") for (int k = 0; k < 2; ++k) \
;         acc[ai][bj][m][n] = __builtin_amdgcn_mfma_f32_16x16x32_bf16(Bt[n][k], At[m][k], acc[ai][bj][m][n], 0, 0, 0); __builtin_amdgcn_s_setprio(0); } while (0)
; #define PG8_WAIT_V(n) asm volatile("s_waitcnt vmcnt(" #n ")" ::: "memory")
; #define PG8_WAIT_L(n) asm volatile("s_waitcnt lgkmcnt(" #n ")" ::: "memory")
; #define PG8_BAR __builtin_amdgcn_s_barrier()
; #define PG8_SCHED __builtin_amdgcn_sched_barrier(0)
; template <class Epi, class Sched, bool ALIGN_EPI = false, bool SP2 = false>
; __device__ __forceinline__ void gemm_phase(PG8_LAS unsigned char* lds, const Gemm g, const Sched& S, const Epi& E) {
;     ...
;             PG8_LDA(At, 1, 1); PG8_STAGE(PG8_SB(1, 0), b3, voffB); PG8_STAGE(PG8_SB(1, 1), b3 + hstepB, voffB); PG8_STAGE(PG8_SA(1, 0), a3, voffA);
;             PG8_WAIT_V(8); PG8_WAIT_L(0); PG8_BAR; PG8_MMA(1, 0, At, B0); PG8_MMA(1, 1, At, B1); PG8_BAR; PG8_SCHED;
;     ...
;         }
;         if constexpr (ALIGN_EPI) { if (wr == 0) PG8_BAR; }
	s_add_i32 s25, s25, s45
	v_lshl_add_u64 v[172:173], v[172:173], 0, s[48:49]
	s_mov_b32 m0, s25
	ds_read_b128 v[184:187], v183 offset:49152
	ds_read_b128 v[188:191], v183 offset:50176
	ds_read_b128 v[192:195], v183 offset:51200
	ds_read_b128 v[210:213], v183 offset:52224
	ds_read_b128 v[214:217], v183 offset:53248
	ds_read_b128 v[218:221], v183 offset:54272
	ds_read_b128 v[242:245], v183 offset:55296
	ds_read_b128 v[246:249], v183 offset:56320
	global_load_lds_dwordx4 v[172:173], off
	s_add_i32 m0, s25, 0x2000
	s_add_u32 s20, s20, 0x40080
	v_lshl_add_u64 v[172:173], v[222:223], 0, s[48:49]
	s_addc_u32 s21, s21, 0
	s_add_i32 s25, s41, s45
	global_load_lds_dwordx4 v[172:173], off
	v_lshl_add_u64 v[172:173], s[20:21], 0, v[150:151]
	s_mov_b32 m0, s25
	s_nop 0
	global_load_lds_dwordx4 v[172:173], off
	v_lshl_add_u64 v[172:173], s[20:21], 0, v[146:147]
	s_add_i32 m0, s25, 0x2000
	s_nop 0
	global_load_lds_dwordx4 v[172:173], off
	v_lshl_add_u64 v[172:173], v[250:251], 0, s[48:49]
	s_mov_b32 m0, s69
	s_nop 0
	global_load_lds_dwordx4 v[172:173], off
	v_lshl_add_u64 v[172:173], v[252:253], 0, s[48:49]
	s_mov_b32 m0, s70
	s_nop 0
	global_load_lds_dwordx4 v[172:173], off
	s_waitcnt vmcnt(8)
	s_waitcnt lgkmcnt(0)
	s_barrier
	s_setprio 1
	v_mfma_f32_16x16x32_bf16 v[60:63], v[130:133], v[184:187], v[60:63]
	v_mfma_f32_16x16x32_bf16 v[56:59], v[138:141], v[184:187], v[56:59]
	v_mfma_f32_16x16x32_bf16 v[44:47], v[130:133], v[192:195], v[44:47]
	v_mfma_f32_16x16x32_bf16 v[40:43], v[138:141], v[192:195], v[40:43]
	v_mfma_f32_16x16x32_bf16 v[28:31], v[130:133], v[214:217], v[28:31]
	v_mfma_f32_16x16x32_bf16 v[24:27], v[138:141], v[214:217], v[24:27]
	v_mfma_f32_16x16x32_bf16 v[12:15], v[130:133], v[242:245], v[12:15]
	v_mfma_f32_16x16x32_bf16 v[8:11], v[138:141], v[242:245], v[8:11]
	v_mfma_f32_16x16x32_bf16 v[60:63], v[134:137], v[188:191], v[60:63]
	v_mfma_f32_16x16x32_bf16 v[56:59], v[142:145], v[188:191], v[56:59]
	v_mfma_f32_16x16x32_bf16 v[44:47], v[134:137], v[210:213], v[44:47]
	v_mfma_f32_16x16x32_bf16 v[40:43], v[142:145], v[210:213], v[40:43]
	v_mfma_f32_16x16x32_bf16 v[28:31], v[134:137], v[218:221], v[28:31]
	v_mfma_f32_16x16x32_bf16 v[24:27], v[142:145], v[218:221], v[24:27]
	v_mfma_f32_16x16x32_bf16 v[12:15], v[134:137], v[246:249], v[12:15]
	v_mfma_f32_16x16x32_bf16 v[8:11], v[142:145], v[246:249], v[8:11]
	s_setprio 0
	s_setprio 1
	v_mfma_f32_16x16x32_bf16 v[52:55], v[158:161], v[184:187], v[52:55]
	v_mfma_f32_16x16x32_bf16 v[48:51], v[166:169], v[184:187], v[48:51]
	v_mfma_f32_16x16x32_bf16 v[36:39], v[158:161], v[192:195], v[36:39]
	v_mfma_f32_16x16x32_bf16 v[32:35], v[166:169], v[192:195], v[32:35]
	v_mfma_f32_16x16x32_bf16 v[20:23], v[158:161], v[214:217], v[20:23]
	v_mfma_f32_16x16x32_bf16 v[16:19], v[166:169], v[214:217], v[16:19]
	v_mfma_f32_16x16x32_bf16 v[4:7], v[158:161], v[242:245], v[4:7]
	v_mfma_f32_16x16x32_bf16 v[0:3], v[166:169], v[242:245], v[0:3]
	v_mfma_f32_16x16x32_bf16 v[52:55], v[162:165], v[188:191], v[52:55]
	v_mfma_f32_16x16x32_bf16 v[48:51], v[178:181], v[188:191], v[48:51]
	v_mfma_f32_16x16x32_bf16 v[36:39], v[162:165], v[210:213], v[36:39]
	v_mfma_f32_16x16x32_bf16 v[32:35], v[178:181], v[210:213], v[32:35]
	v_mfma_f32_16x16x32_bf16 v[20:23], v[162:165], v[218:221], v[20:23]
	v_mfma_f32_16x16x32_bf16 v[16:19], v[178:181], v[218:221], v[16:19]
	v_mfma_f32_16x16x32_bf16 v[4:7], v[162:165], v[246:249], v[4:7]
	v_mfma_f32_16x16x32_bf16 v[0:3], v[178:181], v[246:249], v[0:3]
	s_setprio 0
	s_barrier
	s_add_i32 s24, s24, 2
	s_add_u32 s18, s18, 0x100
	s_addc_u32 s19, s19, 0
	s_add_u32 s22, s22, 0x100
	s_addc_u32 s23, s23, 0
	s_cmp_gt_u32 s24, 13
	s_cbranch_scc0 .LBB0_304
	s_and_b64 vcc, exec, s[8:9]
	s_cbranch_vccz .LBB0_307
	s_barrier

; #define PG8_STAGE(bufoff, gbase, voff) do { _Pragma("unroll") for (int _i = 0; _i < 2; ++_i) \
;         __builtin_amdgcn_global_load_lds((const unsigned*)((const char*)(gbase) + (voff)[_i]), (PG8_LAS unsigned*)(lds + (bufoff) + ldsw + _i * 8192), 16, 0, 0); } while (0)
; #define PG8_LDA(dst, b, h) do { _Pragma("unroll") for (int m = 0; m < 4; ++m) _Pragma("unroll") for (int k = 0; k < 2; ++k) dst[m][k] = *(const PG8_LAS bf16x8*)(lds + PG8_SA(b, h) + aoff + m * 2048 + k * 1024); } while (0)
; #define PG8_LDB(dst, b, h) do { _Pragma("unroll") for (int n = 0; n < 2; ++n) _Pragma("unroll") for (int k = 0; k < 2; ++k) dst[n][k] = *(const PG8_LAS bf16x8*)(lds + PG8_SB(b, h) + boff + n * 2048 + k * 1024); } while (0)
; #define PG8_MMA(ai, bj, At, Bt) do { __builtin_amdgcn_s_setprio(1); _Pragma("unroll") for (int m = 0; m < 4; ++m) _Pragma("unroll") for (int n = 0; n < 2; ++n) _Pragma("unroll") for (int k = 0; k < 2; ++k) \
;         acc[ai][bj][m][n] = __builtin_amdgcn_mfma_f32_16x16x32_bf16(Bt[n][k], At[m][k], acc[ai][bj][m][n], 0, 0, 0); __builtin_amdgcn_s_setprio(0); } while (0)
; #define PG8_WAIT_V(n) asm volatile("s_waitcnt vmcnt(" #n ")" ::: "memory")
; #define PG8_WAIT_L(n) asm volatile("s_waitcnt lgkmcnt(" #n ")" ::: "memory")
; #define PG8_BAR __builtin_amdgcn_s_barrier()
; #define PG8_SCHED __builtin_amdgcn_sched_barrier(0)
; template <class Epi, class Sched, bool ALIGN_EPI = false, bool SP2 = false>
; __device__ __forceinline__ void gemm_phase(PG8_LAS unsigned char* lds, const Gemm g, const Sched& S, const Epi& E) {
;     ...
;             const bool last = (t == nt - 2);
;             const char* a1 = cA + (size_t)(t + 1) * kstep;
;             const char* a2 = last ? nA : cA + (size_t)(t + 2) * kstep; const char* b2 = last ? nB : cB + (size_t)(t + 2) * kstep;
;             const char* a3 = a2 + kstep; const char* b3 = b2 + kstep;
;             if (last && has_next) S.a_ready(nxt);
;             if constexpr (SP2) {
;             PG8_LDB(B0, 0, 0); PG8_LDB(B1, 0, 1); PG8_SCHED; PG8_LDA(At, 0, 0); PG8_STAGE(PG8_SA(1, 1), a1 + hstepA, voffA);
;             PG8_WAIT_V(8); PG8_WAIT_L(0); PG8_BAR; PG8_MMA(0, 0, At, B0); PG8_MMA(0, 1, At, B1); PG8_BAR; PG8_SCHED;
;             PG8_LDA(At, 0, 1); PG8_STAGE(PG8_SB(0, 0), b2, voffB); PG8_STAGE(PG8_SB(0, 1), b2 + hstepB, voffB); PG8_STAGE(PG8_SA(0, 0), a2, voffA);
.LBB0_329:
	s_add_u32 s30, s20, 0xfffc0080
	s_addc_u32 s31, s21, -1
	s_add_i32 s41, 0, 0x10000
	s_cmp_eq_u32 s60, 12
	s_cselect_b32 s39, s6, s31
	s_cselect_b32 s38, s7, s30
	v_add_u32_e32 v147, s41, v64
	s_cselect_b32 s31, s11, s25
	s_cselect_b32 s30, s13, s24
	s_add_i32 s61, 0, 0x14000
	ds_read_b128 v[154:157], v147
	ds_read_b128 v[158:161], v147 offset:1024
	ds_read_b128 v[162:165], v147 offset:2048
	ds_read_b128 v[166:169], v147 offset:3072
	v_add_u32_e32 v147, s61, v64
	ds_read_b128 v[170:173], v147
	ds_read_b128 v[174:177], v147 offset:1024
	ds_read_b128 v[178:181], v147 offset:2048
	ds_read_b128 v[182:185], v147 offset:3072
	v_lshl_add_u64 v[150:151], s[20:21], 0, v[142:143]
	s_add_i32 m0, s15, 0xc000
	ds_read_b128 v[186:189], v139
	ds_read_b128 v[190:193], v139 offset:1024
	ds_read_b128 v[210:213], v139 offset:2048
	ds_read_b128 v[214:217], v139 offset:3072
	ds_read_b128 v[218:221], v139 offset:4096
	ds_read_b128 v[242:245], v139 offset:5120
	ds_read_b128 v[246:249], v139 offset:6144
	ds_read_b128 v[250:253], v139 offset:7168
	global_load_lds_dwordx4 v[150:151], off
	v_lshl_add_u64 v[150:151], s[20:21], 0, v[144:145]
	s_add_i32 m0, s15, 0xe000
	s_nop 0
	global_load_lds_dwordx4 v[150:151], off
	s_waitcnt vmcnt(8)
	s_waitcnt lgkmcnt(0)
	s_barrier
	s_setprio 1
	v_mfma_f32_16x16x32_bf16 v[126:129], v[154:157], v[186:189], v[126:129]
	v_mfma_f32_16x16x32_bf16 v[122:125], v[162:165], v[186:189], v[122:125]
	v_mfma_f32_16x16x32_bf16 v[118:121], v[154:157], v[210:213], v[118:121]
	v_mfma_f32_16x16x32_bf16 v[110:113], v[162:165], v[210:213], v[110:113]
	v_mfma_f32_16x16x32_bf16 v[102:105], v[154:157], v[218:221], v[102:105]
	v_mfma_f32_16x16x32_bf16 v[94:97], v[162:165], v[218:221], v[94:97]
	v_mfma_f32_16x16x32_bf16 v[86:89], v[154:157], v[246:249], v[86:89]
	v_mfma_f32_16x16x32_bf16 v[78:81], v[162:165], v[246:249], v[78:81]
	v_mfma_f32_16x16x32_bf16 v[126:129], v[158:161], v[190:193], v[126:129]
	v_mfma_f32_16x16x32_bf16 v[122:125], v[166:169], v[190:193], v[122:125]
	v_mfma_f32_16x16x32_bf16 v[118:121], v[158:161], v[214:217], v[118:121]
	v_mfma_f32_16x16x32_bf16 v[110:113], v[166:169], v[214:217], v[110:113]
	v_mfma_f32_16x16x32_bf16 v[102:105], v[158:161], v[242:245], v[102:105]
	v_mfma_f32_16x16x32_bf16 v[94:97], v[166:169], v[242:245], v[94:97]
	v_mfma_f32_16x16x32_bf16 v[86:89], v[158:161], v[250:253], v[86:89]
	v_mfma_f32_16x16x32_bf16 v[78:81], v[166:169], v[250:253], v[78:81]
	s_setprio 0
	s_setprio 1
	v_mfma_f32_16x16x32_bf16 v[114:117], v[170:173], v[186:189], v[114:117]
	v_mfma_f32_16x16x32_bf16 v[106:109], v[178:181], v[186:189], v[106:109]
	v_mfma_f32_16x16x32_bf16 v[98:101], v[170:173], v[210:213], v[98:101]
	v_mfma_f32_16x16x32_bf16 v[90:93], v[178:181], v[210:213], v[90:93]
	v_mfma_f32_16x16x32_bf16 v[82:85], v[170:173], v[218:221], v[82:85]
	v_mfma_f32_16x16x32_bf16 v[74:77], v[178:181], v[218:221], v[74:77]
	v_mfma_f32_16x16x32_bf16 v[70:73], v[170:173], v[246:249], v[70:73]
	v_mfma_f32_16x16x32_bf16 v[66:69], v[178:181], v[246:249], v[66:69]
	v_mfma_f32_16x16x32_bf16 v[114:117], v[174:177], v[190:193], v[114:117]
	v_mfma_f32_16x16x32_bf16 v[106:109], v[182:185], v[190:193], v[106:109]
	v_mfma_f32_16x16x32_bf16 v[98:101], v[174:177], v[214:217], v[98:101]
	v_mfma_f32_16x16x32_bf16 v[90:93], v[182:185], v[214:217], v[90:93]
	v_mfma_f32_16x16x32_bf16 v[82:85], v[174:177], v[242:245], v[82:85]
	v_mfma_f32_16x16x32_bf16 v[74:77], v[182:185], v[242:245], v[74:77]
	v_mfma_f32_16x16x32_bf16 v[70:73], v[174:177], v[250:253], v[70:73]
	v_mfma_f32_16x16x32_bf16 v[66:69], v[182:185], v[250:253], v[66:69]
	s_setprio 0
	s_barrier
	s_add_i32 s41, s41, s63
	v_lshl_add_u64 v[150:151], s[30:31], 0, v[132:133]
	s_mov_b32 m0, s41
	ds_read_b128 v[186:189], v139 offset:16384
	ds_read_b128 v[190:193], v139 offset:17408
	ds_read_b128 v[210:213], v139 offset:18432
	ds_read_b128 v[214:217], v139 offset:19456
	ds_read_b128 v[218:221], v139 offset:20480
	ds_read_b128 v[242:245], v139 offset:21504
	ds_read_b128 v[246:249], v139 offset:22528
	ds_read_b128 v[250:253], v139 offset:23552
	global_load_lds_dwordx4 v[150:151], off
	s_add_i32 m0, s41, 0x2000
	s_add_u32 s80, s30, 0x40000
	v_lshl_add_u64 v[194:195], s[30:31], 0, v[136:137]
	s_addc_u32 s81, s31, 0
	s_add_i32 s41, s61, s63
	global_load_lds_dwordx4 v[194:195], off
	v_lshl_add_u64 v[222:223], s[80:81], 0, v[132:133]
	s_mov_b32 m0, s41
	v_lshl_add_u64 v[230:231], s[38:39], 0, v[134:135]
	global_load_lds_dwordx4 v[222:223], off
	v_lshl_add_u64 v[222:223], s[80:81], 0, v[136:137]
	s_add_i32 m0, s41, 0x2000
	s_nop 0
	global_load_lds_dwordx4 v[222:223], off
	v_lshl_add_u64 v[222:223], s[38:39], 0, v[130:131]
	s_mov_b32 m0, s15
	s_nop 0
	global_load_lds_dwordx4 v[222:223], off
	s_mov_b32 m0, s64
	s_nop 0
	global_load_lds_dwordx4 v[230:231], off
	s_waitcnt vmcnt(8)
	s_waitcnt lgkmcnt(0)
	s_barrier
; #define PG8_STAGE(bufoff, gbase, voff) do { _Pragma("unroll") for (int _i = 0; _i < 2; ++_i) \
;         __builtin_amdgcn_global_load_lds((const unsigned*)((const char*)(gbase) + (voff)[_i]), (PG8_LAS unsigned*)(lds + (bufoff) + ldsw + _i * 8192), 16, 0, 0); } while (0)
; #define PG8_LDA(dst, b, h) do { _Pragma("unroll") for (int m = 0; m < 4; ++m) _Pragma("unroll") for (int k = 0; k < 2; ++k) dst[m][k] = *(const PG8_LAS bf16x8*)(lds + PG8_SA(b, h) + aoff + m * 2048 + k * 1024); } while (0)
; #define PG8_LDB(dst, b, h) do { _Pragma("unroll") for (int n = 0; n < 2; ++n) _Pragma("unroll") for (int k = 0; k < 2; ++k) dst[n][k] = *(const PG8_LAS bf16x8*)(lds + PG8_SB(b, h) + boff + n * 2048 + k * 1024); } while (0)
; #define PG8_MMA(ai, bj, At, Bt) do { __builtin_amdgcn_s_setprio(1); _Pragma("unroll") for (int m = 0; m < 4; ++m) _Pragma("unroll") for (int n = 0; n < 2; ++n) _Pragma("unroll") for (int k = 0; k < 2; ++k) \
;         acc[ai][bj][m][n] = __builtin_amdgcn_mfma_f32_16x16x32_bf16(Bt[n][k], At[m][k], acc[ai][bj][m][n], 0, 0, 0); __builtin_amdgcn_s_setprio(0); } while (0)
; #define PG8_WAIT_V(n) asm volatile("s_waitcnt vmcnt(" #n ")" ::: "memory")
; #define PG8_WAIT_L(n) asm volatile("s_waitcnt lgkmcnt(" #n ")" ::: "memory")
; #define PG8_BAR __builtin_amdgcn_s_barrier()
; #define PG8_SCHED __builtin_amdgcn_sched_barrier(0)
; template <class Epi, class Sched, bool ALIGN_EPI = false, bool SP2 = false>
; __device__ __forceinline__ void gemm_phase(PG8_LAS unsigned char* lds, const Gemm g, const Sched& S, const Epi& E) {
;     ...
;             PG8_WAIT_V(8); PG8_WAIT_L(0); PG8_BAR; PG8_MMA(1, 0, At, B0); PG8_MMA(1, 1, At, B1); PG8_BAR; PG8_SCHED;
;             PG8_LDB(B0, 1, 0); PG8_LDB(B1, 1, 1); PG8_SCHED; PG8_LDA(At, 1, 0); PG8_STAGE(PG8_SA(0, 1), a2 + hstepA, voffA);
;             PG8_WAIT_V(8); PG8_WAIT_L(0); PG8_BAR; PG8_MMA(0, 0, At, B0); PG8_MMA(0, 1, At, B1); PG8_BAR; PG8_SCHED;
	s_setprio 1
	v_mfma_f32_16x16x32_bf16 v[60:63], v[154:157], v[186:189], v[60:63]
	v_mfma_f32_16x16x32_bf16 v[56:59], v[162:165], v[186:189], v[56:59]
	v_mfma_f32_16x16x32_bf16 v[52:55], v[154:157], v[210:213], v[52:55]
	v_mfma_f32_16x16x32_bf16 v[44:47], v[162:165], v[210:213], v[44:47]
	v_mfma_f32_16x16x32_bf16 v[36:39], v[154:157], v[218:221], v[36:39]
	v_mfma_f32_16x16x32_bf16 v[28:31], v[162:165], v[218:221], v[28:31]
	v_mfma_f32_16x16x32_bf16 v[20:23], v[154:157], v[246:249], v[20:23]
	v_mfma_f32_16x16x32_bf16 v[12:15], v[162:165], v[246:249], v[12:15]
	v_mfma_f32_16x16x32_bf16 v[60:63], v[158:161], v[190:193], v[60:63]
	v_mfma_f32_16x16x32_bf16 v[56:59], v[166:169], v[190:193], v[56:59]
	v_mfma_f32_16x16x32_bf16 v[52:55], v[158:161], v[214:217], v[52:55]
	v_mfma_f32_16x16x32_bf16 v[44:47], v[166:169], v[214:217], v[44:47]
	v_mfma_f32_16x16x32_bf16 v[36:39], v[158:161], v[242:245], v[36:39]
	v_mfma_f32_16x16x32_bf16 v[28:31], v[166:169], v[242:245], v[28:31]
	v_mfma_f32_16x16x32_bf16 v[20:23], v[158:161], v[250:253], v[20:23]
	v_mfma_f32_16x16x32_bf16 v[12:15], v[166:169], v[250:253], v[12:15]
	s_setprio 0
	s_setprio 1
	v_mfma_f32_16x16x32_bf16 v[48:51], v[170:173], v[186:189], v[48:51]
	v_mfma_f32_16x16x32_bf16 v[40:43], v[178:181], v[186:189], v[40:43]
	v_mfma_f32_16x16x32_bf16 v[32:35], v[170:173], v[210:213], v[32:35]
	v_mfma_f32_16x16x32_bf16 v[24:27], v[178:181], v[210:213], v[24:27]
	v_mfma_f32_16x16x32_bf16 v[16:19], v[170:173], v[218:221], v[16:19]
	v_mfma_f32_16x16x32_bf16 v[8:11], v[178:181], v[218:221], v[8:11]
	v_mfma_f32_16x16x32_bf16 v[4:7], v[170:173], v[246:249], v[4:7]
	v_mfma_f32_16x16x32_bf16 v[0:3], v[178:181], v[246:249], v[0:3]
	v_mfma_f32_16x16x32_bf16 v[48:51], v[174:177], v[190:193], v[48:51]
	v_mfma_f32_16x16x32_bf16 v[40:43], v[182:185], v[190:193], v[40:43]
	v_mfma_f32_16x16x32_bf16 v[32:35], v[174:177], v[214:217], v[32:35]
	v_mfma_f32_16x16x32_bf16 v[24:27], v[182:185], v[214:217], v[24:27]
	v_mfma_f32_16x16x32_bf16 v[16:19], v[174:177], v[242:245], v[16:19]
	v_mfma_f32_16x16x32_bf16 v[8:11], v[182:185], v[242:245], v[8:11]
	v_mfma_f32_16x16x32_bf16 v[4:7], v[174:177], v[250:253], v[4:7]
	v_mfma_f32_16x16x32_bf16 v[0:3], v[182:185], v[250:253], v[0:3]
	s_setprio 0
	s_barrier
	s_add_i32 s41, 0, 0x18000
	v_add_u32_e32 v147, s41, v64
	s_add_i32 s61, 0, 0x1c000
	ds_read_b128 v[154:157], v147
	ds_read_b128 v[158:161], v147 offset:1024
	ds_read_b128 v[162:165], v147 offset:2048
	ds_read_b128 v[166:169], v147 offset:3072
	v_add_u32_e32 v147, s61, v64
	ds_read_b128 v[170:173], v147
	ds_read_b128 v[174:177], v147 offset:1024
	ds_read_b128 v[178:181], v147 offset:2048
	ds_read_b128 v[182:185], v147 offset:3072
	s_add_u32 s38, s38, 0x40000
	s_addc_u32 s39, s39, 0
	s_mov_b32 m0, s65
	v_lshl_add_u64 v[232:233], s[38:39], 0, v[130:131]
	ds_read_b128 v[186:189], v139 offset:32768
	ds_read_b128 v[190:193], v139 offset:33792
	ds_read_b128 v[210:213], v139 offset:34816
	ds_read_b128 v[214:217], v139 offset:35840
	ds_read_b128 v[218:221], v139 offset:36864
	ds_read_b128 v[242:245], v139 offset:37888
	ds_read_b128 v[246:249], v139 offset:38912
	ds_read_b128 v[250:253], v139 offset:39936
	global_load_lds_dwordx4 v[232:233], off
	v_lshl_add_u64 v[232:233], s[38:39], 0, v[134:135]
	s_mov_b32 m0, s68
	s_nop 0
	global_load_lds_dwordx4 v[232:233], off
	s_waitcnt vmcnt(8)
	s_waitcnt lgkmcnt(0)
	s_barrier
	s_setprio 1
	v_mfma_f32_16x16x32_bf16 v[126:129], v[154:157], v[186:189], v[126:129]
	v_mfma_f32_16x16x32_bf16 v[122:125], v[162:165], v[186:189], v[122:125]
	v_mfma_f32_16x16x32_bf16 v[118:121], v[154:157], v[210:213], v[118:121]
	v_mfma_f32_16x16x32_bf16 v[110:113], v[162:165], v[210:213], v[110:113]
	v_mfma_f32_16x16x32_bf16 v[102:105], v[154:157], v[218:221], v[102:105]
	v_mfma_f32_16x16x32_bf16 v[94:97], v[162:165], v[218:221], v[94:97]
	v_mfma_f32_16x16x32_bf16 v[86:89], v[154:157], v[246:249], v[86:89]
	v_mfma_f32_16x16x32_bf16 v[78:81], v[162:165], v[246:249], v[78:81]
	v_mfma_f32_16x16x32_bf16 v[126:129], v[158:161], v[190:193], v[126:129]
	v_mfma_f32_16x16x32_bf16 v[122:125], v[166:169], v[190:193], v[122:125]
	v_mfma_f32_16x16x32_bf16 v[118:121], v[158:161], v[214:217], v[118:121]
	v_mfma_f32_16x16x32_bf16 v[110:113], v[166:169], v[214:217], v[110:113]
	v_mfma_f32_16x16x32_bf16 v[102:105], v[158:161], v[242:245], v[102:105]
	v_mfma_f32_16x16x32_bf16 v[94:97], v[166:169], v[242:245], v[94:97]
	v_mfma_f32_16x16x32_bf16 v[86:89], v[158:161], v[250:253], v[86:89]
	v_mfma_f32_16x16x32_bf16 v[78:81], v[166:169], v[250:253], v[78:81]
	s_setprio 0
	s_setprio 1
	v_mfma_f32_16x16x32_bf16 v[114:117], v[170:173], v[186:189], v[114:117]
	v_mfma_f32_16x16x32_bf16 v[106:109], v[178:181], v[186:189], v[106:109]
	v_mfma_f32_16x16x32_bf16 v[98:101], v[170:173], v[210:213], v[98:101]
	v_mfma_f32_16x16x32_bf16 v[90:93], v[178:181], v[210:213], v[90:93]
	v_mfma_f32_16x16x32_bf16 v[82:85], v[170:173], v[218:221], v[82:85]
	v_mfma_f32_16x16x32_bf16 v[74:77], v[178:181], v[218:221], v[74:77]
	v_mfma_f32_16x16x32_bf16 v[70:73], v[170:173], v[246:249], v[70:73]
	v_mfma_f32_16x16x32_bf16 v[66:69], v[178:181], v[246:249], v[66:69]
	v_mfma_f32_16x16x32_bf16 v[114:117], v[174:177], v[190:193], v[114:117]
	v_mfma_f32_16x16x32_bf16 v[106:109], v[182:185], v[190:193], v[106:109]
	v_mfma_f32_16x16x32_bf16 v[98:101], v[174:177], v[214:217], v[98:101]
	v_mfma_f32_16x16x32_bf16 v[90:93], v[182:185], v[214:217], v[90:93]
	v_mfma_f32_16x16x32_bf16 v[82:85], v[174:177], v[242:245], v[82:85]
	v_mfma_f32_16x16x32_bf16 v[74:77], v[182:185], v[242:245], v[74:77]
	v_mfma_f32_16x16x32_bf16 v[70:73], v[174:177], v[250:253], v[70:73]
	v_mfma_f32_16x16x32_bf16 v[66:69], v[182:185], v[250:253], v[66:69]
	s_setprio 0
	s_barrier
; #define PG8_STAGE(bufoff, gbase, voff) do { _Pragma("unroll") for (int _i = 0; _i < 2; ++_i) \
;         __builtin_amdgcn_global_load_lds((const unsigned*)((const char*)(gbase) + (voff)[_i]), (PG8_LAS unsigned*)(lds + (bufoff) + ldsw + _i * 8192), 16, 0, 0); } while (0)
; #define PG8_LDA(dst, b, h) do { _Pragma("unroll") for (int m = 0; m < 4; ++m) _Pragma("unroll") for (int k = 0; k < 2; ++k) dst[m][k] = *(const PG8_LAS bf16x8*)(lds + PG8_SA(b, h) + aoff + m * 2048 + k * 1024); } while (0)
; #define PG8_MMA(ai, bj, At, Bt) do { __builtin_amdgcn_s_setprio(1); _Pragma("unroll") for (int m = 0; m < 4; ++m) _Pragma("unroll") for (int n = 0; n < 2; ++n) _Pragma("unroll") for (int k = 0; k < 2; ++k) \
;         acc[ai][bj][m][n] = __builtin_amdgcn_mfma_f32_16x16x32_bf16(Bt[n][k], At[m][k], acc[ai][bj][m][n], 0, 0, 0); __builtin_amdgcn_s_setprio(0); } while (0)
; #define PG8_WAIT_V(n) asm volatile("s_waitcnt vmcnt(" #n ")" ::: "memory")
; #define PG8_WAIT_L(n) asm volatile("s_waitcnt lgkmcnt(" #n ")" ::: "memory")
; #define PG8_BAR __builtin_amdgcn_s_barrier()
; #define PG8_SCHED __builtin_amdgcn_sched_barrier(0)
; template <class Epi, class Sched, bool ALIGN_EPI = false, bool SP2 = false>
; __device__ __forceinline__ void gemm_phase(PG8_LAS unsigned char* lds, const Gemm g, const Sched& S, const Epi& E) {
;     ...
;             PG8_LDA(At, 1, 1); PG8_STAGE(PG8_SB(1, 0), b3, voffB); PG8_STAGE(PG8_SB(1, 1), b3 + hstepB, voffB); PG8_STAGE(PG8_SA(1, 0), a3, voffA);
;             PG8_WAIT_V(8); PG8_WAIT_L(0); PG8_BAR; PG8_MMA(1, 0, At, B0); PG8_MMA(1, 1, At, B1); PG8_BAR; PG8_SCHED;
;     ...
;         }
;         if constexpr (ALIGN_EPI) { if (wr == 0) PG8_BAR; }
;         if constexpr (!Epi::AFTER_DRAIN) { E(acc, cur, wr, wc, fr, fq); S.done(cur); }
	s_add_i32 s38, s41, s63
	v_lshl_add_u64 v[150:151], v[150:151], 0, s[48:49]
	s_mov_b32 m0, s38
	ds_read_b128 v[186:189], v139 offset:49152
	ds_read_b128 v[190:193], v139 offset:50176
	ds_read_b128 v[210:213], v139 offset:51200
	ds_read_b128 v[214:217], v139 offset:52224
	ds_read_b128 v[218:221], v139 offset:53248
	ds_read_b128 v[242:245], v139 offset:54272
	ds_read_b128 v[246:249], v139 offset:55296
	ds_read_b128 v[250:253], v139 offset:56320
	global_load_lds_dwordx4 v[150:151], off
	s_add_i32 m0, s38, 0x2000
	s_add_u32 s30, s30, 0x40080
	v_lshl_add_u64 v[150:151], v[194:195], 0, s[48:49]
	s_addc_u32 s31, s31, 0
	s_add_i32 s38, s61, s63
	global_load_lds_dwordx4 v[150:151], off
	v_lshl_add_u64 v[150:151], s[30:31], 0, v[132:133]
	s_mov_b32 m0, s38
	s_nop 0
	global_load_lds_dwordx4 v[150:151], off
	v_lshl_add_u64 v[150:151], s[30:31], 0, v[136:137]
	s_add_i32 m0, s38, 0x2000
	s_nop 0
	global_load_lds_dwordx4 v[150:151], off
	v_lshl_add_u64 v[150:151], v[222:223], 0, s[48:49]
	s_mov_b32 m0, s69
	s_nop 0
	global_load_lds_dwordx4 v[150:151], off
	v_lshl_add_u64 v[150:151], v[230:231], 0, s[48:49]
	s_mov_b32 m0, s70
	s_nop 0
	global_load_lds_dwordx4 v[150:151], off
	s_waitcnt vmcnt(8)
	s_waitcnt lgkmcnt(0)
	s_barrier
	s_setprio 1
	v_mfma_f32_16x16x32_bf16 v[60:63], v[154:157], v[186:189], v[60:63]
	v_mfma_f32_16x16x32_bf16 v[56:59], v[162:165], v[186:189], v[56:59]
	v_mfma_f32_16x16x32_bf16 v[52:55], v[154:157], v[210:213], v[52:55]
	v_mfma_f32_16x16x32_bf16 v[44:47], v[162:165], v[210:213], v[44:47]
	v_mfma_f32_16x16x32_bf16 v[36:39], v[154:157], v[218:221], v[36:39]
	v_mfma_f32_16x16x32_bf16 v[28:31], v[162:165], v[218:221], v[28:31]
	v_mfma_f32_16x16x32_bf16 v[20:23], v[154:157], v[246:249], v[20:23]
	v_mfma_f32_16x16x32_bf16 v[12:15], v[162:165], v[246:249], v[12:15]
	v_mfma_f32_16x16x32_bf16 v[60:63], v[158:161], v[190:193], v[60:63]
	v_mfma_f32_16x16x32_bf16 v[56:59], v[166:169], v[190:193], v[56:59]
	v_mfma_f32_16x16x32_bf16 v[52:55], v[158:161], v[214:217], v[52:55]
	v_mfma_f32_16x16x32_bf16 v[44:47], v[166:169], v[214:217], v[44:47]
	v_mfma_f32_16x16x32_bf16 v[36:39], v[158:161], v[242:245], v[36:39]
	v_mfma_f32_16x16x32_bf16 v[28:31], v[166:169], v[242:245], v[28:31]
	v_mfma_f32_16x16x32_bf16 v[20:23], v[158:161], v[250:253], v[20:23]
	v_mfma_f32_16x16x32_bf16 v[12:15], v[166:169], v[250:253], v[12:15]
	s_setprio 0
	s_setprio 1
	v_mfma_f32_16x16x32_bf16 v[48:51], v[170:173], v[186:189], v[48:51]
	v_mfma_f32_16x16x32_bf16 v[40:43], v[178:181], v[186:189], v[40:43]
	v_mfma_f32_16x16x32_bf16 v[32:35], v[170:173], v[210:213], v[32:35]
	v_mfma_f32_16x16x32_bf16 v[24:27], v[178:181], v[210:213], v[24:27]
	v_mfma_f32_16x16x32_bf16 v[16:19], v[170:173], v[218:221], v[16:19]
	v_mfma_f32_16x16x32_bf16 v[8:11], v[178:181], v[218:221], v[8:11]
	v_mfma_f32_16x16x32_bf16 v[4:7], v[170:173], v[246:249], v[4:7]
	v_mfma_f32_16x16x32_bf16 v[0:3], v[178:181], v[246:249], v[0:3]
	v_mfma_f32_16x16x32_bf16 v[48:51], v[174:177], v[190:193], v[48:51]
	v_mfma_f32_16x16x32_bf16 v[40:43], v[182:185], v[190:193], v[40:43]
	v_mfma_f32_16x16x32_bf16 v[32:35], v[174:177], v[214:217], v[32:35]
	v_mfma_f32_16x16x32_bf16 v[24:27], v[182:185], v[214:217], v[24:27]
	v_mfma_f32_16x16x32_bf16 v[16:19], v[174:177], v[242:245], v[16:19]
	v_mfma_f32_16x16x32_bf16 v[8:11], v[182:185], v[242:245], v[8:11]
	v_mfma_f32_16x16x32_bf16 v[4:7], v[174:177], v[250:253], v[4:7]
	v_mfma_f32_16x16x32_bf16 v[0:3], v[182:185], v[250:253], v[0:3]
	s_setprio 0
	s_barrier
	s_add_i32 s60, s60, 2
	s_add_u32 s20, s20, 0x100
	s_addc_u32 s21, s21, 0
	s_add_u32 s24, s24, 0x100
	s_addc_u32 s25, s25, 0
	s_cmp_gt_u32 s60, 13
	s_cbranch_scc0 .LBB0_329
	s_and_b64 vcc, exec, s[4:5]
	s_cbranch_vccnz .LBB0_334
	s_cmp_gt_i32 s73, 3
	s_mov_b64 s[6:7], -1
	s_cbranch_scc1 .LBB0_335

; #define PG8_STAGE(bufoff, gbase, voff) do { _Pragma("unroll") for (int _i = 0; _i < 2; ++_i) \
;         __builtin_amdgcn_global_load_lds((const unsigned*)((const char*)(gbase) + (voff)[_i]), (PG8_LAS unsigned*)(lds + (bufoff) + ldsw + _i * 8192), 16, 0, 0); } while (0)
; #define PG8_LDA(dst, b, h) do { _Pragma("unroll") for (int m = 0; m < 4; ++m) _Pragma("unroll") for (int k = 0; k < 2; ++k) dst[m][k] = *(const PG8_LAS bf16x8*)(lds + PG8_SA(b, h) + aoff + m * 2048 + k * 1024); } while (0)
; #define PG8_LDB(dst, b, h) do { _Pragma("unroll") for (int n = 0; n < 2; ++n) _Pragma("unroll") for (int k = 0; k < 2; ++k) dst[n][k] = *(const PG8_LAS bf16x8*)(lds + PG8_SB(b, h) + boff + n * 2048 + k * 1024); } while (0)
; #define PG8_MMA(ai, bj, At, Bt) do { __builtin_amdgcn_s_setprio(1); _Pragma("unroll") for (int m = 0; m < 4; ++m) _Pragma("unroll") for (int n = 0; n < 2; ++n) _Pragma("unroll") for (int k = 0; k < 2; ++k) \
;         acc[ai][bj][m][n] = __builtin_amdgcn_mfma_f32_16x16x32_bf16(Bt[n][k], At[m][k], acc[ai][bj][m][n], 0, 0, 0); __builtin_amdgcn_s_setprio(0); } while (0)
; #define PG8_WAIT_V(n) asm volatile("s_waitcnt vmcnt(" #n ")" ::: "memory")
; #define PG8_WAIT_L(n) asm volatile("s_waitcnt lgkmcnt(" #n ")" ::: "memory")
; #define PG8_BAR __builtin_amdgcn_s_barrier()
; #define PG8_SCHED __builtin_amdgcn_sched_barrier(0)
; template <class Epi, class Sched, bool ALIGN_EPI = false, bool SP2 = false>
; __device__ __forceinline__ void gemm_phase(PG8_LAS unsigned char* lds, const Gemm g, const Sched& S, const Epi& E) {
;     ...
;             const bool last = (t == nt - 2);
;             const char* a1 = cA + (size_t)(t + 1) * kstep;
;             const char* a2 = last ? nA : cA + (size_t)(t + 2) * kstep; const char* b2 = last ? nB : cB + (size_t)(t + 2) * kstep;
;             const char* a3 = a2 + kstep; const char* b3 = b2 + kstep;
;             if (last && has_next) S.a_ready(nxt);
;             if constexpr (SP2) {
;             PG8_LDB(B0, 0, 0); PG8_LDB(B1, 0, 1); PG8_SCHED; PG8_LDA(At, 0, 0); PG8_STAGE(PG8_SA(1, 1), a1 + hstepA, voffA);
;             PG8_WAIT_V(8); PG8_WAIT_L(0); PG8_BAR; PG8_MMA(0, 0, At, B0); PG8_MMA(0, 1, At, B1); PG8_BAR; PG8_SCHED;
;             PG8_LDA(At, 0, 1); PG8_STAGE(PG8_SB(0, 0), b2, voffB); PG8_STAGE(PG8_SB(0, 1), b2 + hstepB, voffB); PG8_STAGE(PG8_SA(0, 0), a2, voffA);
.LBB0_408:
	s_add_u32 s8, s6, 0xf9950080
	s_addc_u32 s9, s7, -1
	s_cmp_lg_u32 s43, 40
	s_cselect_b32 s8, s8, 0
	s_cselect_b32 s9, s9, 0
	s_add_u32 s10, s4, s8
	s_addc_u32 s11, s5, s9
	s_add_i32 s41, 0, 0x10000
	s_add_u32 s8, s2, s8
	v_add_u32_e32 v139, s41, v137
	s_addc_u32 s9, s3, s9
	s_add_i32 s60, 0, 0x14000
	ds_read_b128 v[140:143], v139
	ds_read_b128 v[144:147], v139 offset:1024
	ds_read_b128 v[148:151], v139 offset:2048
	ds_read_b128 v[152:155], v139 offset:3072
	v_add_u32_e32 v139, s60, v137
	ds_read_b128 v[156:159], v139
	ds_read_b128 v[160:163], v139 offset:1024
	ds_read_b128 v[164:167], v139 offset:2048
	ds_read_b128 v[168:171], v139 offset:3072
	v_lshl_add_u64 v[176:177], v[132:133], 0, s[6:7]
	s_add_i32 m0, s22, 0xc000
	ds_read_b128 v[172:175], v138
	ds_read_b128 v[180:183], v138 offset:1024
	ds_read_b128 v[184:187], v138 offset:2048
	ds_read_b128 v[188:191], v138 offset:3072
	ds_read_b128 v[210:213], v138 offset:4096
	ds_read_b128 v[214:217], v138 offset:5120
	ds_read_b128 v[218:221], v138 offset:6144
	ds_read_b128 v[242:245], v138 offset:7168
	global_load_lds_dwordx4 v[176:177], off
	v_lshl_add_u64 v[176:177], v[134:135], 0, s[6:7]
	s_add_i32 m0, s22, 0xe000
	s_nop 0
	global_load_lds_dwordx4 v[176:177], off
	s_waitcnt vmcnt(8)
	s_waitcnt lgkmcnt(0)
	s_barrier
	s_setprio 1
	v_mfma_f32_16x16x32_bf16 v[126:129], v[140:143], v[172:175], v[126:129]
	v_mfma_f32_16x16x32_bf16 v[122:125], v[148:151], v[172:175], v[122:125]
	v_mfma_f32_16x16x32_bf16 v[110:113], v[140:143], v[184:187], v[110:113]
	v_mfma_f32_16x16x32_bf16 v[106:109], v[148:151], v[184:187], v[106:109]
	v_mfma_f32_16x16x32_bf16 v[94:97], v[140:143], v[210:213], v[94:97]
	v_mfma_f32_16x16x32_bf16 v[90:93], v[148:151], v[210:213], v[90:93]
	v_mfma_f32_16x16x32_bf16 v[78:81], v[140:143], v[218:221], v[78:81]
	v_mfma_f32_16x16x32_bf16 v[74:77], v[148:151], v[218:221], v[74:77]
	v_mfma_f32_16x16x32_bf16 v[126:129], v[144:147], v[180:183], v[126:129]
	v_mfma_f32_16x16x32_bf16 v[122:125], v[152:155], v[180:183], v[122:125]
	v_mfma_f32_16x16x32_bf16 v[110:113], v[144:147], v[188:191], v[110:113]
	v_mfma_f32_16x16x32_bf16 v[106:109], v[152:155], v[188:191], v[106:109]
	v_mfma_f32_16x16x32_bf16 v[94:97], v[144:147], v[214:217], v[94:97]
	v_mfma_f32_16x16x32_bf16 v[90:93], v[152:155], v[214:217], v[90:93]
	v_mfma_f32_16x16x32_bf16 v[78:81], v[144:147], v[242:245], v[78:81]
	v_mfma_f32_16x16x32_bf16 v[74:77], v[152:155], v[242:245], v[74:77]
	s_setprio 0
	s_setprio 1
	v_mfma_f32_16x16x32_bf16 v[118:121], v[156:159], v[172:175], v[118:121]
	v_mfma_f32_16x16x32_bf16 v[114:117], v[164:167], v[172:175], v[114:117]
	v_mfma_f32_16x16x32_bf16 v[102:105], v[156:159], v[184:187], v[102:105]
	v_mfma_f32_16x16x32_bf16 v[98:101], v[164:167], v[184:187], v[98:101]
	v_mfma_f32_16x16x32_bf16 v[86:89], v[156:159], v[210:213], v[86:89]
	v_mfma_f32_16x16x32_bf16 v[82:85], v[164:167], v[210:213], v[82:85]
	v_mfma_f32_16x16x32_bf16 v[70:73], v[156:159], v[218:221], v[70:73]
	v_mfma_f32_16x16x32_bf16 v[66:69], v[164:167], v[218:221], v[66:69]
	v_mfma_f32_16x16x32_bf16 v[118:121], v[160:163], v[180:183], v[118:121]
	v_mfma_f32_16x16x32_bf16 v[114:117], v[168:171], v[180:183], v[114:117]
	v_mfma_f32_16x16x32_bf16 v[102:105], v[160:163], v[188:191], v[102:105]
	v_mfma_f32_16x16x32_bf16 v[98:101], v[168:171], v[188:191], v[98:101]
	v_mfma_f32_16x16x32_bf16 v[86:89], v[160:163], v[214:217], v[86:89]
	v_mfma_f32_16x16x32_bf16 v[82:85], v[168:171], v[214:217], v[82:85]
	v_mfma_f32_16x16x32_bf16 v[70:73], v[160:163], v[242:245], v[70:73]
	v_mfma_f32_16x16x32_bf16 v[66:69], v[168:171], v[242:245], v[66:69]
	s_setprio 0
	s_barrier
	s_add_i32 s41, s41, s21
	v_lshl_add_u64 v[176:177], s[8:9], 0, v[64:65]
	s_mov_b32 m0, s41
	ds_read_b128 v[172:175], v138 offset:16384
	ds_read_b128 v[180:183], v138 offset:17408
	ds_read_b128 v[184:187], v138 offset:18432
	ds_read_b128 v[188:191], v138 offset:19456
	ds_read_b128 v[210:213], v138 offset:20480
	ds_read_b128 v[214:217], v138 offset:21504
	ds_read_b128 v[218:221], v138 offset:22528
	ds_read_b128 v[242:245], v138 offset:23552
	global_load_lds_dwordx4 v[176:177], off
	s_add_i32 m0, s41, 0x2000
	s_add_u32 s44, s8, 0xb0000
	v_lshl_add_u64 v[222:223], s[8:9], 0, v[130:131]
	s_addc_u32 s45, s9, 0
	s_add_i32 s41, s60, s21
	global_load_lds_dwordx4 v[222:223], off
	v_lshl_add_u64 v[230:231], s[44:45], 0, v[64:65]
	s_mov_b32 m0, s41
	v_lshl_add_u64 v[232:233], s[10:11], 0, v[130:131]
	global_load_lds_dwordx4 v[230:231], off
	v_lshl_add_u64 v[230:231], s[44:45], 0, v[130:131]
	s_add_i32 m0, s41, 0x2000
	s_nop 0
	global_load_lds_dwordx4 v[230:231], off
	v_lshl_add_u64 v[230:231], s[10:11], 0, v[64:65]
	s_mov_b32 m0, s22
	s_nop 0
	global_load_lds_dwordx4 v[230:231], off
	s_mov_b32 m0, s23
	s_nop 0
	global_load_lds_dwordx4 v[232:233], off
	s_waitcnt vmcnt(8)
	s_waitcnt lgkmcnt(0)
	s_barrier
; #define PG8_STAGE(bufoff, gbase, voff) do { _Pragma("unroll") for (int _i = 0; _i < 2; ++_i) \
;         __builtin_amdgcn_global_load_lds((const unsigned*)((const char*)(gbase) + (voff)[_i]), (PG8_LAS unsigned*)(lds + (bufoff) + ldsw + _i * 8192), 16, 0, 0); } while (0)
; #define PG8_LDA(dst, b, h) do { _Pragma("unroll") for (int m = 0; m < 4; ++m) _Pragma("unroll") for (int k = 0; k < 2; ++k) dst[m][k] = *(const PG8_LAS bf16x8*)(lds + PG8_SA(b, h) + aoff + m * 2048 + k * 1024); } while (0)
; #define PG8_LDB(dst, b, h) do { _Pragma("unroll") for (int n = 0; n < 2; ++n) _Pragma("unroll") for (int k = 0; k < 2; ++k) dst[n][k] = *(const PG8_LAS bf16x8*)(lds + PG8_SB(b, h) + boff + n * 2048 + k * 1024); } while (0)
; #define PG8_MMA(ai, bj, At, Bt) do { __builtin_amdgcn_s_setprio(1); _Pragma("unroll") for (int m = 0; m < 4; ++m) _Pragma("unroll") for (int n = 0; n < 2; ++n) _Pragma("unroll") for (int k = 0; k < 2; ++k) \
;         acc[ai][bj][m][n] = __builtin_amdgcn_mfma_f32_16x16x32_bf16(Bt[n][k], At[m][k], acc[ai][bj][m][n], 0, 0, 0); __builtin_amdgcn_s_setprio(0); } while (0)
; #define PG8_WAIT_V(n) asm volatile("s_waitcnt vmcnt(" #n ")" ::: "memory")
; #define PG8_WAIT_L(n) asm volatile("s_waitcnt lgkmcnt(" #n ")" ::: "memory")
; #define PG8_BAR __builtin_amdgcn_s_barrier()
; #define PG8_SCHED __builtin_amdgcn_sched_barrier(0)
; template <class Epi, class Sched, bool ALIGN_EPI = false, bool SP2 = false>
; __device__ __forceinline__ void gemm_phase(PG8_LAS unsigned char* lds, const Gemm g, const Sched& S, const Epi& E) {
;     ...
;             PG8_WAIT_V(8); PG8_WAIT_L(0); PG8_BAR; PG8_MMA(1, 0, At, B0); PG8_MMA(1, 1, At, B1); PG8_BAR; PG8_SCHED;
;             PG8_LDB(B0, 1, 0); PG8_LDB(B1, 1, 1); PG8_SCHED; PG8_LDA(At, 1, 0); PG8_STAGE(PG8_SA(0, 1), a2 + hstepA, voffA);
;             PG8_WAIT_V(8); PG8_WAIT_L(0); PG8_BAR; PG8_MMA(0, 0, At, B0); PG8_MMA(0, 1, At, B1); PG8_BAR; PG8_SCHED;
	s_setprio 1
	v_mfma_f32_16x16x32_bf16 v[60:63], v[140:143], v[172:175], v[60:63]
	v_mfma_f32_16x16x32_bf16 v[56:59], v[148:151], v[172:175], v[56:59]
	v_mfma_f32_16x16x32_bf16 v[44:47], v[140:143], v[184:187], v[44:47]
	v_mfma_f32_16x16x32_bf16 v[40:43], v[148:151], v[184:187], v[40:43]
	v_mfma_f32_16x16x32_bf16 v[28:31], v[140:143], v[210:213], v[28:31]
	v_mfma_f32_16x16x32_bf16 v[24:27], v[148:151], v[210:213], v[24:27]
	v_mfma_f32_16x16x32_bf16 v[12:15], v[140:143], v[218:221], v[12:15]
	v_mfma_f32_16x16x32_bf16 v[8:11], v[148:151], v[218:221], v[8:11]
	v_mfma_f32_16x16x32_bf16 v[60:63], v[144:147], v[180:183], v[60:63]
	v_mfma_f32_16x16x32_bf16 v[56:59], v[152:155], v[180:183], v[56:59]
	v_mfma_f32_16x16x32_bf16 v[44:47], v[144:147], v[188:191], v[44:47]
	v_mfma_f32_16x16x32_bf16 v[40:43], v[152:155], v[188:191], v[40:43]
	v_mfma_f32_16x16x32_bf16 v[28:31], v[144:147], v[214:217], v[28:31]
	v_mfma_f32_16x16x32_bf16 v[24:27], v[152:155], v[214:217], v[24:27]
	v_mfma_f32_16x16x32_bf16 v[12:15], v[144:147], v[242:245], v[12:15]
	v_mfma_f32_16x16x32_bf16 v[8:11], v[152:155], v[242:245], v[8:11]
	s_setprio 0
	s_setprio 1
	v_mfma_f32_16x16x32_bf16 v[52:55], v[156:159], v[172:175], v[52:55]
	v_mfma_f32_16x16x32_bf16 v[48:51], v[164:167], v[172:175], v[48:51]
	v_mfma_f32_16x16x32_bf16 v[36:39], v[156:159], v[184:187], v[36:39]
	v_mfma_f32_16x16x32_bf16 v[32:35], v[164:167], v[184:187], v[32:35]
	v_mfma_f32_16x16x32_bf16 v[20:23], v[156:159], v[210:213], v[20:23]
	v_mfma_f32_16x16x32_bf16 v[16:19], v[164:167], v[210:213], v[16:19]
	v_mfma_f32_16x16x32_bf16 v[4:7], v[156:159], v[218:221], v[4:7]
	v_mfma_f32_16x16x32_bf16 v[0:3], v[164:167], v[218:221], v[0:3]
	v_mfma_f32_16x16x32_bf16 v[52:55], v[160:163], v[180:183], v[52:55]
	v_mfma_f32_16x16x32_bf16 v[48:51], v[168:171], v[180:183], v[48:51]
	v_mfma_f32_16x16x32_bf16 v[36:39], v[160:163], v[188:191], v[36:39]
	v_mfma_f32_16x16x32_bf16 v[32:35], v[168:171], v[188:191], v[32:35]
	v_mfma_f32_16x16x32_bf16 v[20:23], v[160:163], v[214:217], v[20:23]
	v_mfma_f32_16x16x32_bf16 v[16:19], v[168:171], v[214:217], v[16:19]
	v_mfma_f32_16x16x32_bf16 v[4:7], v[160:163], v[242:245], v[4:7]
	v_mfma_f32_16x16x32_bf16 v[0:3], v[168:171], v[242:245], v[0:3]
	s_setprio 0
	s_barrier
	s_add_i32 s41, 0, 0x18000
	v_add_u32_e32 v139, s41, v137
	s_add_i32 s44, 0, 0x1c000
	ds_read_b128 v[140:143], v139
	ds_read_b128 v[144:147], v139 offset:1024
	ds_read_b128 v[148:151], v139 offset:2048
	ds_read_b128 v[152:155], v139 offset:3072
	v_add_u32_e32 v139, s44, v137
	ds_read_b128 v[156:159], v139
	ds_read_b128 v[160:163], v139 offset:1024
	ds_read_b128 v[164:167], v139 offset:2048
	ds_read_b128 v[168:171], v139 offset:3072
	s_add_u32 s10, s10, 0xb0000
	s_addc_u32 s11, s11, 0
	s_mov_b32 m0, s24
	v_lshl_add_u64 v[246:247], s[10:11], 0, v[64:65]
	ds_read_b128 v[172:175], v138 offset:32768
	ds_read_b128 v[180:183], v138 offset:33792
	ds_read_b128 v[184:187], v138 offset:34816
	ds_read_b128 v[188:191], v138 offset:35840
	ds_read_b128 v[210:213], v138 offset:36864
	ds_read_b128 v[214:217], v138 offset:37888
	ds_read_b128 v[218:221], v138 offset:38912
	ds_read_b128 v[242:245], v138 offset:39936
	global_load_lds_dwordx4 v[246:247], off
	v_lshl_add_u64 v[246:247], s[10:11], 0, v[130:131]
	s_mov_b32 m0, s25
	s_nop 0
	global_load_lds_dwordx4 v[246:247], off
	s_waitcnt vmcnt(8)
	s_waitcnt lgkmcnt(0)
	s_barrier
	s_setprio 1
	v_mfma_f32_16x16x32_bf16 v[126:129], v[140:143], v[172:175], v[126:129]
	v_mfma_f32_16x16x32_bf16 v[122:125], v[148:151], v[172:175], v[122:125]
	v_mfma_f32_16x16x32_bf16 v[110:113], v[140:143], v[184:187], v[110:113]
	v_mfma_f32_16x16x32_bf16 v[106:109], v[148:151], v[184:187], v[106:109]
	v_mfma_f32_16x16x32_bf16 v[94:97], v[140:143], v[210:213], v[94:97]
	v_mfma_f32_16x16x32_bf16 v[90:93], v[148:151], v[210:213], v[90:93]
	v_mfma_f32_16x16x32_bf16 v[78:81], v[140:143], v[218:221], v[78:81]
	v_mfma_f32_16x16x32_bf16 v[74:77], v[148:151], v[218:221], v[74:77]
	v_mfma_f32_16x16x32_bf16 v[126:129], v[144:147], v[180:183], v[126:129]
	v_mfma_f32_16x16x32_bf16 v[122:125], v[152:155], v[180:183], v[122:125]
	v_mfma_f32_16x16x32_bf16 v[110:113], v[144:147], v[188:191], v[110:113]
	v_mfma_f32_16x16x32_bf16 v[106:109], v[152:155], v[188:191], v[106:109]
	v_mfma_f32_16x16x32_bf16 v[94:97], v[144:147], v[214:217], v[94:97]
	v_mfma_f32_16x16x32_bf16 v[90:93], v[152:155], v[214:217], v[90:93]
	v_mfma_f32_16x16x32_bf16 v[78:81], v[144:147], v[242:245], v[78:81]
	v_mfma_f32_16x16x32_bf16 v[74:77], v[152:155], v[242:245], v[74:77]
	s_setprio 0
	s_setprio 1
	v_mfma_f32_16x16x32_bf16 v[118:121], v[156:159], v[172:175], v[118:121]
	v_mfma_f32_16x16x32_bf16 v[114:117], v[164:167], v[172:175], v[114:117]
	v_mfma_f32_16x16x32_bf16 v[102:105], v[156:159], v[184:187], v[102:105]
	v_mfma_f32_16x16x32_bf16 v[98:101], v[164:167], v[184:187], v[98:101]
	v_mfma_f32_16x16x32_bf16 v[86:89], v[156:159], v[210:213], v[86:89]
	v_mfma_f32_16x16x32_bf16 v[82:85], v[164:167], v[210:213], v[82:85]
	v_mfma_f32_16x16x32_bf16 v[70:73], v[156:159], v[218:221], v[70:73]
	v_mfma_f32_16x16x32_bf16 v[66:69], v[164:167], v[218:221], v[66:69]
	v_mfma_f32_16x16x32_bf16 v[118:121], v[160:163], v[180:183], v[118:121]
	v_mfma_f32_16x16x32_bf16 v[114:117], v[168:171], v[180:183], v[114:117]
	v_mfma_f32_16x16x32_bf16 v[102:105], v[160:163], v[188:191], v[102:105]
	v_mfma_f32_16x16x32_bf16 v[98:101], v[168:171], v[188:191], v[98:101]
	v_mfma_f32_16x16x32_bf16 v[86:89], v[160:163], v[214:217], v[86:89]
	v_mfma_f32_16x16x32_bf16 v[82:85], v[168:171], v[214:217], v[82:85]
	v_mfma_f32_16x16x32_bf16 v[70:73], v[160:163], v[242:245], v[70:73]
	v_mfma_f32_16x16x32_bf16 v[66:69], v[168:171], v[242:245], v[66:69]
	s_setprio 0
	s_barrier
; #define PG8_STAGE(bufoff, gbase, voff) do { _Pragma("unroll") for (int _i = 0; _i < 2; ++_i) \
;         __builtin_amdgcn_global_load_lds((const unsigned*)((const char*)(gbase) + (voff)[_i]), (PG8_LAS unsigned*)(lds + (bufoff) + ldsw + _i * 8192), 16, 0, 0); } while (0)
; #define PG8_LDA(dst, b, h) do { _Pragma("unroll") for (int m = 0; m < 4; ++m) _Pragma("unroll") for (int k = 0; k < 2; ++k) dst[m][k] = *(const PG8_LAS bf16x8*)(lds + PG8_SA(b, h) + aoff + m * 2048 + k * 1024); } while (0)
; #define PG8_MMA(ai, bj, At, Bt) do { __builtin_amdgcn_s_setprio(1); _Pragma("unroll") for (int m = 0; m < 4; ++m) _Pragma("unroll") for (int n = 0; n < 2; ++n) _Pragma("unroll") for (int k = 0; k < 2; ++k) \
;         acc[ai][bj][m][n] = __builtin_amdgcn_mfma_f32_16x16x32_bf16(Bt[n][k], At[m][k], acc[ai][bj][m][n], 0, 0, 0); __builtin_amdgcn_s_setprio(0); } while (0)
; #define PG8_WAIT_V(n) asm volatile("s_waitcnt vmcnt(" #n ")" ::: "memory")
; #define PG8_WAIT_L(n) asm volatile("s_waitcnt lgkmcnt(" #n ")" ::: "memory")
; #define PG8_BAR __builtin_amdgcn_s_barrier()
; #define PG8_SCHED __builtin_amdgcn_sched_barrier(0)
; template <class Epi, class Sched, bool ALIGN_EPI = false, bool SP2 = false>
; __device__ __forceinline__ void gemm_phase(PG8_LAS unsigned char* lds, const Gemm g, const Sched& S, const Epi& E) {
;     ...
;             PG8_LDA(At, 1, 1); PG8_STAGE(PG8_SB(1, 0), b3, voffB); PG8_STAGE(PG8_SB(1, 1), b3 + hstepB, voffB); PG8_STAGE(PG8_SA(1, 0), a3, voffA);
;             PG8_WAIT_V(8); PG8_WAIT_L(0); PG8_BAR; PG8_MMA(1, 0, At, B0); PG8_MMA(1, 1, At, B1); PG8_BAR; PG8_SCHED;
;     ...
;     PG8_WAIT_V(0);
;     if constexpr (!ALIGN_EPI) { if (wr == 0) PG8_BAR; }
	s_add_i32 s10, s41, s21
	v_lshl_add_u64 v[176:177], v[176:177], 0, s[48:49]
	s_mov_b32 m0, s10
	ds_read_b128 v[172:175], v138 offset:49152
	ds_read_b128 v[180:183], v138 offset:50176
	ds_read_b128 v[184:187], v138 offset:51200
	ds_read_b128 v[188:191], v138 offset:52224
	ds_read_b128 v[210:213], v138 offset:53248
	ds_read_b128 v[214:217], v138 offset:54272
	ds_read_b128 v[218:221], v138 offset:55296
	ds_read_b128 v[242:245], v138 offset:56320
	global_load_lds_dwordx4 v[176:177], off
	s_add_i32 m0, s10, 0x2000
	s_add_u32 s8, s8, 0xb0080
	v_lshl_add_u64 v[176:177], v[222:223], 0, s[48:49]
	s_addc_u32 s9, s9, 0
	s_add_i32 s10, s44, s21
	global_load_lds_dwordx4 v[176:177], off
	v_lshl_add_u64 v[176:177], s[8:9], 0, v[64:65]
	s_mov_b32 m0, s10
	s_nop 0
	global_load_lds_dwordx4 v[176:177], off
	v_lshl_add_u64 v[176:177], s[8:9], 0, v[130:131]
	s_add_i32 m0, s10, 0x2000
	s_nop 0
	global_load_lds_dwordx4 v[176:177], off
	v_lshl_add_u64 v[176:177], v[230:231], 0, s[48:49]
	s_mov_b32 m0, s31
	s_nop 0
	global_load_lds_dwordx4 v[176:177], off
	v_lshl_add_u64 v[176:177], v[232:233], 0, s[48:49]
	s_mov_b32 m0, s34
	s_nop 0
	global_load_lds_dwordx4 v[176:177], off
	s_waitcnt vmcnt(8)
	s_waitcnt lgkmcnt(0)
	s_barrier
	s_setprio 1
	v_mfma_f32_16x16x32_bf16 v[60:63], v[140:143], v[172:175], v[60:63]
	v_mfma_f32_16x16x32_bf16 v[56:59], v[148:151], v[172:175], v[56:59]
	v_mfma_f32_16x16x32_bf16 v[44:47], v[140:143], v[184:187], v[44:47]
	v_mfma_f32_16x16x32_bf16 v[40:43], v[148:151], v[184:187], v[40:43]
	v_mfma_f32_16x16x32_bf16 v[28:31], v[140:143], v[210:213], v[28:31]
	v_mfma_f32_16x16x32_bf16 v[24:27], v[148:151], v[210:213], v[24:27]
	v_mfma_f32_16x16x32_bf16 v[12:15], v[140:143], v[218:221], v[12:15]
	v_mfma_f32_16x16x32_bf16 v[8:11], v[148:151], v[218:221], v[8:11]
	v_mfma_f32_16x16x32_bf16 v[60:63], v[144:147], v[180:183], v[60:63]
	v_mfma_f32_16x16x32_bf16 v[56:59], v[152:155], v[180:183], v[56:59]
	v_mfma_f32_16x16x32_bf16 v[44:47], v[144:147], v[188:191], v[44:47]
	v_mfma_f32_16x16x32_bf16 v[40:43], v[152:155], v[188:191], v[40:43]
	v_mfma_f32_16x16x32_bf16 v[28:31], v[144:147], v[214:217], v[28:31]
	v_mfma_f32_16x16x32_bf16 v[24:27], v[152:155], v[214:217], v[24:27]
	v_mfma_f32_16x16x32_bf16 v[12:15], v[144:147], v[242:245], v[12:15]
	v_mfma_f32_16x16x32_bf16 v[8:11], v[152:155], v[242:245], v[8:11]
	s_setprio 0
	s_setprio 1
	v_mfma_f32_16x16x32_bf16 v[52:55], v[156:159], v[172:175], v[52:55]
	v_mfma_f32_16x16x32_bf16 v[48:51], v[164:167], v[172:175], v[48:51]
	v_mfma_f32_16x16x32_bf16 v[36:39], v[156:159], v[184:187], v[36:39]
	v_mfma_f32_16x16x32_bf16 v[32:35], v[164:167], v[184:187], v[32:35]
	v_mfma_f32_16x16x32_bf16 v[20:23], v[156:159], v[210:213], v[20:23]
	v_mfma_f32_16x16x32_bf16 v[16:19], v[164:167], v[210:213], v[16:19]
	v_mfma_f32_16x16x32_bf16 v[4:7], v[156:159], v[218:221], v[4:7]
	v_mfma_f32_16x16x32_bf16 v[0:3], v[164:167], v[218:221], v[0:3]
	v_mfma_f32_16x16x32_bf16 v[52:55], v[160:163], v[180:183], v[52:55]
	v_mfma_f32_16x16x32_bf16 v[48:51], v[168:171], v[180:183], v[48:51]
	v_mfma_f32_16x16x32_bf16 v[36:39], v[160:163], v[188:191], v[36:39]
	v_mfma_f32_16x16x32_bf16 v[32:35], v[168:171], v[188:191], v[32:35]
	v_mfma_f32_16x16x32_bf16 v[20:23], v[160:163], v[214:217], v[20:23]
	v_mfma_f32_16x16x32_bf16 v[16:19], v[168:171], v[214:217], v[16:19]
	v_mfma_f32_16x16x32_bf16 v[4:7], v[160:163], v[242:245], v[4:7]
	v_mfma_f32_16x16x32_bf16 v[0:3], v[168:171], v[242:245], v[0:3]
	s_setprio 0
	s_barrier
	s_add_i32 s43, s43, 2
	s_add_u32 s6, s6, 0x100
	s_addc_u32 s7, s7, 0
	s_cmp_lt_u32 s43, 42
	s_cbranch_scc1 .LBB0_408
	s_waitcnt vmcnt(0)
	s_cmpk_gt_u32 s19, 0xff
	s_cbranch_scc1 .LBB0_411
	s_barrier

; #define PG8_STAGE(bufoff, gbase, voff) do { _Pragma("unroll") for (int _i = 0; _i < 2; ++_i) \
;         __builtin_amdgcn_global_load_lds((const unsigned*)((const char*)(gbase) + (voff)[_i]), (PG8_LAS unsigned*)(lds + (bufoff) + ldsw + _i * 8192), 16, 0, 0); } while (0)
; #define PG8_LDA(dst, b, h) do { _Pragma("unroll") for (int m = 0; m < 4; ++m) _Pragma("unroll") for (int k = 0; k < 2; ++k) dst[m][k] = *(const PG8_LAS bf16x8*)(lds + PG8_SA(b, h) + aoff + m * 2048 + k * 1024); } while (0)
; #define PG8_LDB(dst, b, h) do { _Pragma("unroll") for (int n = 0; n < 2; ++n) _Pragma("unroll") for (int k = 0; k < 2; ++k) dst[n][k] = *(const PG8_LAS bf16x8*)(lds + PG8_SB(b, h) + boff + n * 2048 + k * 1024); } while (0)
; #define PG8_MMA(ai, bj, At, Bt) do { __builtin_amdgcn_s_setprio(1); _Pragma("unroll") for (int m = 0; m < 4; ++m) _Pragma("unroll") for (int n = 0; n < 2; ++n) _Pragma("unroll") for (int k = 0; k < 2; ++k) \
;         acc[ai][bj][m][n] = __builtin_amdgcn_mfma_f32_16x16x32_bf16(Bt[n][k], At[m][k], acc[ai][bj][m][n], 0, 0, 0); __builtin_amdgcn_s_setprio(0); } while (0)
; #define PG8_WAIT_V(n) asm volatile("s_waitcnt vmcnt(" #n ")" ::: "memory")
; #define PG8_WAIT_L(n) asm volatile("s_waitcnt lgkmcnt(" #n ")" ::: "memory")
; #define PG8_BAR __builtin_amdgcn_s_barrier()
; #define PG8_SCHED __builtin_amdgcn_sched_barrier(0)
; template <class Epi, class Sched, bool ALIGN_EPI = false, bool SP2 = false>
; __device__ __forceinline__ void gemm_phase(PG8_LAS unsigned char* lds, const Gemm g, const Sched& S, const Epi& E) {
;     ...
;             const bool last = (t == nt - 2);
;             const char* a1 = cA + (size_t)(t + 1) * kstep;
;             const char* a2 = last ? nA : cA + (size_t)(t + 2) * kstep; const char* b2 = last ? nB : cB + (size_t)(t + 2) * kstep;
;             const char* a3 = a2 + kstep; const char* b3 = b2 + kstep;
;             if (last && has_next) S.a_ready(nxt);
;             if constexpr (SP2) {
;             PG8_LDB(B0, 0, 0); PG8_LDB(B1, 0, 1); PG8_SCHED; PG8_LDA(At, 0, 0); PG8_STAGE(PG8_SA(1, 1), a1 + hstepA, voffA);
;             PG8_WAIT_V(8); PG8_WAIT_L(0); PG8_BAR; PG8_MMA(0, 0, At, B0); PG8_MMA(0, 1, At, B1); PG8_BAR; PG8_SCHED;
;             PG8_LDA(At, 0, 1); PG8_STAGE(PG8_SB(0, 0), b2, voffB); PG8_STAGE(PG8_SB(0, 1), b2 + hstepB, voffB); PG8_STAGE(PG8_SA(0, 0), a2, voffA);
.LBB0_502:
	s_add_u32 s8, s6, 0xfffc0080
	s_addc_u32 s9, s7, -1
	s_add_i32 s41, 0, 0x10000
	s_cmp_eq_u32 s31, 12
	s_cselect_b32 s45, s5, s9
	s_cselect_b32 s44, s17, s8
	s_cselect_b32 s9, s22, s25
	s_cselect_b32 s8, s23, s24
	s_add_i32 s43, 0, 0x14000
	v_add_u32_e32 v102, s41, v191
	v_add_u32_e32 v170, s43, v191
	ds_read_b128 v[66:69], v102
	ds_read_b128 v[70:73], v102 offset:1024
	ds_read_b128 v[98:101], v102 offset:2048
	ds_read_b128 v[102:105], v102 offset:3072
	ds_read_b128 v[138:141], v170
	ds_read_b128 v[142:145], v170 offset:1024
	ds_read_b128 v[166:169], v170 offset:2048
	ds_read_b128 v[170:173], v170 offset:3072
	v_lshl_add_u64 v[194:195], s[6:7], 0, v[162:163]
	s_add_i32 m0, s19, 0xc000
	ds_read_b128 v[174:177], v193
	ds_read_b128 v[178:181], v193 offset:1024
	ds_read_b128 v[182:185], v193 offset:2048
	ds_read_b128 v[186:189], v193 offset:3072
	ds_read_b128 v[210:213], v193 offset:4096
	ds_read_b128 v[214:217], v193 offset:5120
	ds_read_b128 v[218:221], v193 offset:6144
	ds_read_b128 v[242:245], v193 offset:7168
	global_load_lds_dwordx4 v[194:195], off
	v_lshl_add_u64 v[194:195], s[6:7], 0, v[164:165]
	s_add_i32 m0, s19, 0xe000
	s_nop 0
	global_load_lds_dwordx4 v[194:195], off
	s_waitcnt vmcnt(8)
	s_waitcnt lgkmcnt(0)
	s_barrier
	s_setprio 1
	v_mfma_f32_16x16x32_bf16 v[150:153], v[66:69], v[174:177], v[150:153]
	v_mfma_f32_16x16x32_bf16 v[146:149], v[98:101], v[174:177], v[146:149]
	v_mfma_f32_16x16x32_bf16 v[126:129], v[66:69], v[182:185], v[126:129]
	v_mfma_f32_16x16x32_bf16 v[122:125], v[98:101], v[182:185], v[122:125]
	v_mfma_f32_16x16x32_bf16 v[110:113], v[66:69], v[210:213], v[110:113]
	v_mfma_f32_16x16x32_bf16 v[106:109], v[98:101], v[210:213], v[106:109]
	v_mfma_f32_16x16x32_bf16 v[86:89], v[66:69], v[218:221], v[86:89]
	v_mfma_f32_16x16x32_bf16 v[82:85], v[98:101], v[218:221], v[82:85]
	v_mfma_f32_16x16x32_bf16 v[150:153], v[70:73], v[178:181], v[150:153]
	v_mfma_f32_16x16x32_bf16 v[146:149], v[102:105], v[178:181], v[146:149]
	v_mfma_f32_16x16x32_bf16 v[126:129], v[70:73], v[186:189], v[126:129]
	v_mfma_f32_16x16x32_bf16 v[122:125], v[102:105], v[186:189], v[122:125]
	v_mfma_f32_16x16x32_bf16 v[110:113], v[70:73], v[214:217], v[110:113]
	v_mfma_f32_16x16x32_bf16 v[106:109], v[102:105], v[214:217], v[106:109]
	v_mfma_f32_16x16x32_bf16 v[86:89], v[70:73], v[242:245], v[86:89]
	v_mfma_f32_16x16x32_bf16 v[82:85], v[102:105], v[242:245], v[82:85]
	s_setprio 0
	s_setprio 1
	v_mfma_f32_16x16x32_bf16 v[134:137], v[138:141], v[174:177], v[134:137]
	v_mfma_f32_16x16x32_bf16 v[130:133], v[166:169], v[174:177], v[130:133]
	v_mfma_f32_16x16x32_bf16 v[118:121], v[138:141], v[182:185], v[118:121]
	v_mfma_f32_16x16x32_bf16 v[114:117], v[166:169], v[182:185], v[114:117]
	v_mfma_f32_16x16x32_bf16 v[94:97], v[138:141], v[210:213], v[94:97]
	v_mfma_f32_16x16x32_bf16 v[90:93], v[166:169], v[210:213], v[90:93]
	v_mfma_f32_16x16x32_bf16 v[78:81], v[138:141], v[218:221], v[78:81]
	v_mfma_f32_16x16x32_bf16 v[74:77], v[166:169], v[218:221], v[74:77]
	v_mfma_f32_16x16x32_bf16 v[134:137], v[142:145], v[178:181], v[134:137]
	v_mfma_f32_16x16x32_bf16 v[130:133], v[170:173], v[178:181], v[130:133]
	v_mfma_f32_16x16x32_bf16 v[118:121], v[142:145], v[186:189], v[118:121]
	v_mfma_f32_16x16x32_bf16 v[114:117], v[170:173], v[186:189], v[114:117]
	v_mfma_f32_16x16x32_bf16 v[94:97], v[142:145], v[214:217], v[94:97]
	v_mfma_f32_16x16x32_bf16 v[90:93], v[170:173], v[214:217], v[90:93]
	v_mfma_f32_16x16x32_bf16 v[78:81], v[142:145], v[242:245], v[78:81]
	v_mfma_f32_16x16x32_bf16 v[74:77], v[170:173], v[242:245], v[74:77]
	s_setprio 0
	s_barrier
	s_add_i32 s41, s41, s94
	v_lshl_add_u64 v[194:195], s[8:9], 0, v[156:157]
	s_mov_b32 m0, s41
	ds_read_b128 v[174:177], v193 offset:16384
	ds_read_b128 v[178:181], v193 offset:17408
	ds_read_b128 v[182:185], v193 offset:18432
	ds_read_b128 v[186:189], v193 offset:19456
	ds_read_b128 v[210:213], v193 offset:20480
	ds_read_b128 v[214:217], v193 offset:21504
	ds_read_b128 v[218:221], v193 offset:22528
	ds_read_b128 v[242:245], v193 offset:23552
	global_load_lds_dwordx4 v[194:195], off
	s_add_i32 m0, s41, 0x2000
	s_add_u32 s60, s8, 0x40000
	v_lshl_add_u64 v[222:223], s[8:9], 0, v[160:161]
	s_addc_u32 s61, s9, 0
	s_add_i32 s41, s43, s94
	global_load_lds_dwordx4 v[222:223], off
	v_lshl_add_u64 v[230:231], s[60:61], 0, v[156:157]
	s_mov_b32 m0, s41
	v_lshl_add_u64 v[232:233], s[44:45], 0, v[158:159]
	global_load_lds_dwordx4 v[230:231], off
	v_lshl_add_u64 v[230:231], s[60:61], 0, v[160:161]
	s_add_i32 m0, s41, 0x2000
	s_nop 0
	global_load_lds_dwordx4 v[230:231], off
	v_lshl_add_u64 v[230:231], s[44:45], 0, v[154:155]
	s_mov_b32 m0, s19
	s_nop 0
	global_load_lds_dwordx4 v[230:231], off
	s_mov_b32 m0, s95
	s_nop 0
	global_load_lds_dwordx4 v[232:233], off
	s_waitcnt vmcnt(8)
	s_waitcnt lgkmcnt(0)
	s_barrier
; #define PG8_STAGE(bufoff, gbase, voff) do { _Pragma("unroll") for (int _i = 0; _i < 2; ++_i) \
;         __builtin_amdgcn_global_load_lds((const unsigned*)((const char*)(gbase) + (voff)[_i]), (PG8_LAS unsigned*)(lds + (bufoff) + ldsw + _i * 8192), 16, 0, 0); } while (0)
; #define PG8_LDA(dst, b, h) do { _Pragma("unroll") for (int m = 0; m < 4; ++m) _Pragma("unroll") for (int k = 0; k < 2; ++k) dst[m][k] = *(const PG8_LAS bf16x8*)(lds + PG8_SA(b, h) + aoff + m * 2048 + k * 1024); } while (0)
; #define PG8_LDB(dst, b, h) do { _Pragma("unroll") for (int n = 0; n < 2; ++n) _Pragma("unroll") for (int k = 0; k < 2; ++k) dst[n][k] = *(const PG8_LAS bf16x8*)(lds + PG8_SB(b, h) + boff + n * 2048 + k * 1024); } while (0)
; #define PG8_MMA(ai, bj, At, Bt) do { __builtin_amdgcn_s_setprio(1); _Pragma("unroll") for (int m = 0; m < 4; ++m) _Pragma("unroll") for (int n = 0; n < 2; ++n) _Pragma("unroll") for (int k = 0; k < 2; ++k) \
;         acc[ai][bj][m][n] = __builtin_amdgcn_mfma_f32_16x16x32_bf16(Bt[n][k], At[m][k], acc[ai][bj][m][n], 0, 0, 0); __builtin_amdgcn_s_setprio(0); } while (0)
; #define PG8_WAIT_V(n) asm volatile("s_waitcnt vmcnt(" #n ")" ::: "memory")
; #define PG8_WAIT_L(n) asm volatile("s_waitcnt lgkmcnt(" #n ")" ::: "memory")
; #define PG8_BAR __builtin_amdgcn_s_barrier()
; #define PG8_SCHED __builtin_amdgcn_sched_barrier(0)
; template <class Epi, class Sched, bool ALIGN_EPI = false, bool SP2 = false>
; __device__ __forceinline__ void gemm_phase(PG8_LAS unsigned char* lds, const Gemm g, const Sched& S, const Epi& E) {
;     ...
;             PG8_WAIT_V(8); PG8_WAIT_L(0); PG8_BAR; PG8_MMA(1, 0, At, B0); PG8_MMA(1, 1, At, B1); PG8_BAR; PG8_SCHED;
;             PG8_LDB(B0, 1, 0); PG8_LDB(B1, 1, 1); PG8_SCHED; PG8_LDA(At, 1, 0); PG8_STAGE(PG8_SA(0, 1), a2 + hstepA, voffA);
;             PG8_WAIT_V(8); PG8_WAIT_L(0); PG8_BAR; PG8_MMA(0, 0, At, B0); PG8_MMA(0, 1, At, B1); PG8_BAR; PG8_SCHED;
	s_setprio 1
	v_mfma_f32_16x16x32_bf16 v[60:63], v[66:69], v[174:177], v[60:63]
	v_mfma_f32_16x16x32_bf16 v[56:59], v[98:101], v[174:177], v[56:59]
	v_mfma_f32_16x16x32_bf16 v[44:47], v[66:69], v[182:185], v[44:47]
	v_mfma_f32_16x16x32_bf16 v[40:43], v[98:101], v[182:185], v[40:43]
	v_mfma_f32_16x16x32_bf16 v[28:31], v[66:69], v[210:213], v[28:31]
	v_mfma_f32_16x16x32_bf16 v[24:27], v[98:101], v[210:213], v[24:27]
	v_mfma_f32_16x16x32_bf16 v[12:15], v[66:69], v[218:221], v[12:15]
	v_mfma_f32_16x16x32_bf16 v[8:11], v[98:101], v[218:221], v[8:11]
	v_mfma_f32_16x16x32_bf16 v[60:63], v[70:73], v[178:181], v[60:63]
	v_mfma_f32_16x16x32_bf16 v[56:59], v[102:105], v[178:181], v[56:59]
	v_mfma_f32_16x16x32_bf16 v[44:47], v[70:73], v[186:189], v[44:47]
	v_mfma_f32_16x16x32_bf16 v[40:43], v[102:105], v[186:189], v[40:43]
	v_mfma_f32_16x16x32_bf16 v[28:31], v[70:73], v[214:217], v[28:31]
	v_mfma_f32_16x16x32_bf16 v[24:27], v[102:105], v[214:217], v[24:27]
	v_mfma_f32_16x16x32_bf16 v[12:15], v[70:73], v[242:245], v[12:15]
	v_mfma_f32_16x16x32_bf16 v[8:11], v[102:105], v[242:245], v[8:11]
	s_setprio 0
	s_setprio 1
	v_mfma_f32_16x16x32_bf16 v[52:55], v[138:141], v[174:177], v[52:55]
	v_mfma_f32_16x16x32_bf16 v[48:51], v[166:169], v[174:177], v[48:51]
	v_mfma_f32_16x16x32_bf16 v[36:39], v[138:141], v[182:185], v[36:39]
	v_mfma_f32_16x16x32_bf16 v[32:35], v[166:169], v[182:185], v[32:35]
	v_mfma_f32_16x16x32_bf16 v[20:23], v[138:141], v[210:213], v[20:23]
	v_mfma_f32_16x16x32_bf16 v[16:19], v[166:169], v[210:213], v[16:19]
	v_mfma_f32_16x16x32_bf16 v[4:7], v[138:141], v[218:221], v[4:7]
	v_mfma_f32_16x16x32_bf16 v[0:3], v[166:169], v[218:221], v[0:3]
	v_mfma_f32_16x16x32_bf16 v[52:55], v[142:145], v[178:181], v[52:55]
	v_mfma_f32_16x16x32_bf16 v[48:51], v[170:173], v[178:181], v[48:51]
	v_mfma_f32_16x16x32_bf16 v[36:39], v[142:145], v[186:189], v[36:39]
	v_mfma_f32_16x16x32_bf16 v[32:35], v[170:173], v[186:189], v[32:35]
	v_mfma_f32_16x16x32_bf16 v[20:23], v[142:145], v[214:217], v[20:23]
	v_mfma_f32_16x16x32_bf16 v[16:19], v[170:173], v[214:217], v[16:19]
	v_mfma_f32_16x16x32_bf16 v[4:7], v[142:145], v[242:245], v[4:7]
	v_mfma_f32_16x16x32_bf16 v[0:3], v[170:173], v[242:245], v[0:3]
	s_setprio 0
	s_barrier
	s_add_i32 s41, 0, 0x18000
	s_add_i32 s43, 0, 0x1c000
	v_add_u32_e32 v102, s41, v191
	v_add_u32_e32 v170, s43, v191
	ds_read_b128 v[66:69], v102
	ds_read_b128 v[70:73], v102 offset:1024
	ds_read_b128 v[98:101], v102 offset:2048
	ds_read_b128 v[102:105], v102 offset:3072
	ds_read_b128 v[138:141], v170
	ds_read_b128 v[142:145], v170 offset:1024
	ds_read_b128 v[166:169], v170 offset:2048
	ds_read_b128 v[170:173], v170 offset:3072
	s_add_u32 s44, s44, 0x40000
	s_addc_u32 s45, s45, 0
	s_mov_b32 m0, s97
	v_lshl_add_u64 v[246:247], s[44:45], 0, v[154:155]
	ds_read_b128 v[174:177], v193 offset:32768
	ds_read_b128 v[178:181], v193 offset:33792
	ds_read_b128 v[182:185], v193 offset:34816
	ds_read_b128 v[186:189], v193 offset:35840
	ds_read_b128 v[210:213], v193 offset:36864
	ds_read_b128 v[214:217], v193 offset:37888
	ds_read_b128 v[218:221], v193 offset:38912
	ds_read_b128 v[242:245], v193 offset:39936
	global_load_lds_dwordx4 v[246:247], off
	v_lshl_add_u64 v[246:247], s[44:45], 0, v[158:159]
	s_mov_b32 m0, s34
	s_nop 0
	global_load_lds_dwordx4 v[246:247], off
	s_waitcnt vmcnt(8)
	s_waitcnt lgkmcnt(0)
	s_barrier
	s_setprio 1
	v_mfma_f32_16x16x32_bf16 v[150:153], v[66:69], v[174:177], v[150:153]
	v_mfma_f32_16x16x32_bf16 v[146:149], v[98:101], v[174:177], v[146:149]
	v_mfma_f32_16x16x32_bf16 v[126:129], v[66:69], v[182:185], v[126:129]
	v_mfma_f32_16x16x32_bf16 v[122:125], v[98:101], v[182:185], v[122:125]
	v_mfma_f32_16x16x32_bf16 v[110:113], v[66:69], v[210:213], v[110:113]
	v_mfma_f32_16x16x32_bf16 v[106:109], v[98:101], v[210:213], v[106:109]
	v_mfma_f32_16x16x32_bf16 v[86:89], v[66:69], v[218:221], v[86:89]
	v_mfma_f32_16x16x32_bf16 v[82:85], v[98:101], v[218:221], v[82:85]
	v_mfma_f32_16x16x32_bf16 v[150:153], v[70:73], v[178:181], v[150:153]
	v_mfma_f32_16x16x32_bf16 v[146:149], v[102:105], v[178:181], v[146:149]
	v_mfma_f32_16x16x32_bf16 v[126:129], v[70:73], v[186:189], v[126:129]
	v_mfma_f32_16x16x32_bf16 v[122:125], v[102:105], v[186:189], v[122:125]
	v_mfma_f32_16x16x32_bf16 v[110:113], v[70:73], v[214:217], v[110:113]
	v_mfma_f32_16x16x32_bf16 v[106:109], v[102:105], v[214:217], v[106:109]
	v_mfma_f32_16x16x32_bf16 v[86:89], v[70:73], v[242:245], v[86:89]
	v_mfma_f32_16x16x32_bf16 v[82:85], v[102:105], v[242:245], v[82:85]
	s_setprio 0
	s_setprio 1
	v_mfma_f32_16x16x32_bf16 v[134:137], v[138:141], v[174:177], v[134:137]
	v_mfma_f32_16x16x32_bf16 v[130:133], v[166:169], v[174:177], v[130:133]
	v_mfma_f32_16x16x32_bf16 v[118:121], v[138:141], v[182:185], v[118:121]
	v_mfma_f32_16x16x32_bf16 v[114:117], v[166:169], v[182:185], v[114:117]
	v_mfma_f32_16x16x32_bf16 v[94:97], v[138:141], v[210:213], v[94:97]
	v_mfma_f32_16x16x32_bf16 v[90:93], v[166:169], v[210:213], v[90:93]
	v_mfma_f32_16x16x32_bf16 v[78:81], v[138:141], v[218:221], v[78:81]
	v_mfma_f32_16x16x32_bf16 v[74:77], v[166:169], v[218:221], v[74:77]
	v_mfma_f32_16x16x32_bf16 v[134:137], v[142:145], v[178:181], v[134:137]
	v_mfma_f32_16x16x32_bf16 v[130:133], v[170:173], v[178:181], v[130:133]
	v_mfma_f32_16x16x32_bf16 v[118:121], v[142:145], v[186:189], v[118:121]
	v_mfma_f32_16x16x32_bf16 v[114:117], v[170:173], v[186:189], v[114:117]
	v_mfma_f32_16x16x32_bf16 v[94:97], v[142:145], v[214:217], v[94:97]
	v_mfma_f32_16x16x32_bf16 v[90:93], v[170:173], v[214:217], v[90:93]
	v_mfma_f32_16x16x32_bf16 v[78:81], v[142:145], v[242:245], v[78:81]
	v_mfma_f32_16x16x32_bf16 v[74:77], v[170:173], v[242:245], v[74:77]
	s_setprio 0
	s_barrier
; #define PG8_STAGE(bufoff, gbase, voff) do { _Pragma("unroll") for (int _i = 0; _i < 2; ++_i) \
;         __builtin_amdgcn_global_load_lds((const unsigned*)((const char*)(gbase) + (voff)[_i]), (PG8_LAS unsigned*)(lds + (bufoff) + ldsw + _i * 8192), 16, 0, 0); } while (0)
; #define PG8_LDA(dst, b, h) do { _Pragma("unroll") for (int m = 0; m < 4; ++m) _Pragma("unroll") for (int k = 0; k < 2; ++k) dst[m][k] = *(const PG8_LAS bf16x8*)(lds + PG8_SA(b, h) + aoff + m * 2048 + k * 1024); } while (0)
; #define PG8_MMA(ai, bj, At, Bt) do { __builtin_amdgcn_s_setprio(1); _Pragma("unroll") for (int m = 0; m < 4; ++m) _Pragma("unroll") for (int n = 0; n < 2; ++n) _Pragma("unroll") for (int k = 0; k < 2; ++k) \
;         acc[ai][bj][m][n] = __builtin_amdgcn_mfma_f32_16x16x32_bf16(Bt[n][k], At[m][k], acc[ai][bj][m][n], 0, 0, 0); __builtin_amdgcn_s_setprio(0); } while (0)
; #define PG8_WAIT_V(n) asm volatile("s_waitcnt vmcnt(" #n ")" ::: "memory")
; #define PG8_WAIT_L(n) asm volatile("s_waitcnt lgkmcnt(" #n ")" ::: "memory")
; #define PG8_BAR __builtin_amdgcn_s_barrier()
; #define PG8_SCHED __builtin_amdgcn_sched_barrier(0)
; template <class Epi, class Sched, bool ALIGN_EPI = false, bool SP2 = false>
; __device__ __forceinline__ void gemm_phase(PG8_LAS unsigned char* lds, const Gemm g, const Sched& S, const Epi& E) {
;     ...
;             PG8_LDA(At, 1, 1); PG8_STAGE(PG8_SB(1, 0), b3, voffB); PG8_STAGE(PG8_SB(1, 1), b3 + hstepB, voffB); PG8_STAGE(PG8_SA(1, 0), a3, voffA);
;             PG8_WAIT_V(8); PG8_WAIT_L(0); PG8_BAR; PG8_MMA(1, 0, At, B0); PG8_MMA(1, 1, At, B1); PG8_BAR; PG8_SCHED;
;     ...
;         }
;         if constexpr (ALIGN_EPI) { if (wr == 0) PG8_BAR; }
	s_add_i32 s41, s41, s94
	v_lshl_add_u64 v[194:195], v[194:195], 0, s[48:49]
	s_mov_b32 m0, s41
	ds_read_b128 v[174:177], v193 offset:49152
	ds_read_b128 v[178:181], v193 offset:50176
	ds_read_b128 v[182:185], v193 offset:51200
	ds_read_b128 v[186:189], v193 offset:52224
	ds_read_b128 v[210:213], v193 offset:53248
	ds_read_b128 v[214:217], v193 offset:54272
	ds_read_b128 v[218:221], v193 offset:55296
	ds_read_b128 v[242:245], v193 offset:56320
	global_load_lds_dwordx4 v[194:195], off
	s_add_i32 m0, s41, 0x2000
	s_add_u32 s8, s8, 0x40080
	v_lshl_add_u64 v[194:195], v[222:223], 0, s[48:49]
	s_addc_u32 s9, s9, 0
	s_add_i32 s41, s43, s94
	global_load_lds_dwordx4 v[194:195], off
	v_lshl_add_u64 v[194:195], s[8:9], 0, v[156:157]
	s_mov_b32 m0, s41
	s_nop 0
	global_load_lds_dwordx4 v[194:195], off
	v_lshl_add_u64 v[194:195], s[8:9], 0, v[160:161]
	s_add_i32 m0, s41, 0x2000
	s_nop 0
	global_load_lds_dwordx4 v[194:195], off
	v_lshl_add_u64 v[194:195], v[230:231], 0, s[48:49]
	s_mov_b32 m0, s93
	s_nop 0
	global_load_lds_dwordx4 v[194:195], off
	v_lshl_add_u64 v[194:195], v[232:233], 0, s[48:49]
	s_mov_b32 m0, s85
	s_nop 0
	global_load_lds_dwordx4 v[194:195], off
	s_waitcnt vmcnt(8)
	s_waitcnt lgkmcnt(0)
	s_barrier
	s_setprio 1
	v_mfma_f32_16x16x32_bf16 v[60:63], v[66:69], v[174:177], v[60:63]
	v_mfma_f32_16x16x32_bf16 v[56:59], v[98:101], v[174:177], v[56:59]
	v_mfma_f32_16x16x32_bf16 v[44:47], v[66:69], v[182:185], v[44:47]
	v_mfma_f32_16x16x32_bf16 v[40:43], v[98:101], v[182:185], v[40:43]
	v_mfma_f32_16x16x32_bf16 v[28:31], v[66:69], v[210:213], v[28:31]
	v_mfma_f32_16x16x32_bf16 v[24:27], v[98:101], v[210:213], v[24:27]
	v_mfma_f32_16x16x32_bf16 v[12:15], v[66:69], v[218:221], v[12:15]
	v_mfma_f32_16x16x32_bf16 v[8:11], v[98:101], v[218:221], v[8:11]
	v_mfma_f32_16x16x32_bf16 v[60:63], v[70:73], v[178:181], v[60:63]
	v_mfma_f32_16x16x32_bf16 v[56:59], v[102:105], v[178:181], v[56:59]
	v_mfma_f32_16x16x32_bf16 v[44:47], v[70:73], v[186:189], v[44:47]
	v_mfma_f32_16x16x32_bf16 v[40:43], v[102:105], v[186:189], v[40:43]
	v_mfma_f32_16x16x32_bf16 v[28:31], v[70:73], v[214:217], v[28:31]
	v_mfma_f32_16x16x32_bf16 v[24:27], v[102:105], v[214:217], v[24:27]
	v_mfma_f32_16x16x32_bf16 v[12:15], v[70:73], v[242:245], v[12:15]
	v_mfma_f32_16x16x32_bf16 v[8:11], v[102:105], v[242:245], v[8:11]
	s_setprio 0
	s_setprio 1
	v_mfma_f32_16x16x32_bf16 v[52:55], v[138:141], v[174:177], v[52:55]
	v_mfma_f32_16x16x32_bf16 v[48:51], v[166:169], v[174:177], v[48:51]
	v_mfma_f32_16x16x32_bf16 v[36:39], v[138:141], v[182:185], v[36:39]
	v_mfma_f32_16x16x32_bf16 v[32:35], v[166:169], v[182:185], v[32:35]
	v_mfma_f32_16x16x32_bf16 v[20:23], v[138:141], v[210:213], v[20:23]
	v_mfma_f32_16x16x32_bf16 v[16:19], v[166:169], v[210:213], v[16:19]
	v_mfma_f32_16x16x32_bf16 v[4:7], v[138:141], v[218:221], v[4:7]
	v_mfma_f32_16x16x32_bf16 v[0:3], v[166:169], v[218:221], v[0:3]
	v_mfma_f32_16x16x32_bf16 v[52:55], v[142:145], v[178:181], v[52:55]
	v_mfma_f32_16x16x32_bf16 v[48:51], v[170:173], v[178:181], v[48:51]
	v_mfma_f32_16x16x32_bf16 v[36:39], v[142:145], v[186:189], v[36:39]
	v_mfma_f32_16x16x32_bf16 v[32:35], v[170:173], v[186:189], v[32:35]
	v_mfma_f32_16x16x32_bf16 v[20:23], v[142:145], v[214:217], v[20:23]
	v_mfma_f32_16x16x32_bf16 v[16:19], v[170:173], v[214:217], v[16:19]
	v_mfma_f32_16x16x32_bf16 v[4:7], v[142:145], v[242:245], v[4:7]
	v_mfma_f32_16x16x32_bf16 v[0:3], v[170:173], v[242:245], v[0:3]
	s_setprio 0
	s_barrier
	s_add_i32 s31, s31, 2
	s_add_u32 s6, s6, 0x100
	s_addc_u32 s7, s7, 0
	s_add_u32 s24, s24, 0x100
	s_addc_u32 s25, s25, 0
	s_cmp_gt_u32 s31, 13
	s_cbranch_scc0 .LBB0_502
	s_and_b64 vcc, exec, s[20:21]
	s_cbranch_vccz .LBB0_505
	s_barrier

; #define PG8_STAGE(bufoff, gbase, voff) do { _Pragma("unroll") for (int _i = 0; _i < 2; ++_i) \
;         __builtin_amdgcn_global_load_lds((const unsigned*)((const char*)(gbase) + (voff)[_i]), (PG8_LAS unsigned*)(lds + (bufoff) + ldsw + _i * 8192), 16, 0, 0); } while (0)
; #define PG8_LDA(dst, b, h) do { _Pragma("unroll") for (int m = 0; m < 4; ++m) _Pragma("unroll") for (int k = 0; k < 2; ++k) dst[m][k] = *(const PG8_LAS bf16x8*)(lds + PG8_SA(b, h) + aoff + m * 2048 + k * 1024); } while (0)
; #define PG8_LDB(dst, b, h) do { _Pragma("unroll") for (int n = 0; n < 2; ++n) _Pragma("unroll") for (int k = 0; k < 2; ++k) dst[n][k] = *(const PG8_LAS bf16x8*)(lds + PG8_SB(b, h) + boff + n * 2048 + k * 1024); } while (0)
; #define PG8_MMA(ai, bj, At, Bt) do { __builtin_amdgcn_s_setprio(1); _Pragma("unroll") for (int m = 0; m < 4; ++m) _Pragma("unroll") for (int n = 0; n < 2; ++n) _Pragma("unroll") for (int k = 0; k < 2; ++k) \
;         acc[ai][bj][m][n] = __builtin_amdgcn_mfma_f32_16x16x32_bf16(Bt[n][k], At[m][k], acc[ai][bj][m][n], 0, 0, 0); __builtin_amdgcn_s_setprio(0); } while (0)
; #define PG8_WAIT_V(n) asm volatile("s_waitcnt vmcnt(" #n ")" ::: "memory")
; #define PG8_WAIT_L(n) asm volatile("s_waitcnt lgkmcnt(" #n ")" ::: "memory")
; #define PG8_BAR __builtin_amdgcn_s_barrier()
; #define PG8_SCHED __builtin_amdgcn_sched_barrier(0)
; template <class Epi, class Sched, bool ALIGN_EPI = false, bool SP2 = false>
; __device__ __forceinline__ void gemm_phase(PG8_LAS unsigned char* lds, const Gemm g, const Sched& S, const Epi& E) {
;     ...
;             const bool last = (t == nt - 2);
;             const char* a1 = cA + (size_t)(t + 1) * kstep;
;             const char* a2 = last ? nA : cA + (size_t)(t + 2) * kstep; const char* b2 = last ? nB : cB + (size_t)(t + 2) * kstep;
;             const char* a3 = a2 + kstep; const char* b3 = b2 + kstep;
;             if (last && has_next) S.a_ready(nxt);
;             if constexpr (SP2) {
;             PG8_LDB(B0, 0, 0); PG8_LDB(B1, 0, 1); PG8_SCHED; PG8_LDA(At, 0, 0); PG8_STAGE(PG8_SA(1, 1), a1 + hstepA, voffA);
;             PG8_WAIT_V(8); PG8_WAIT_L(0); PG8_BAR; PG8_MMA(0, 0, At, B0); PG8_MMA(0, 1, At, B1); PG8_BAR; PG8_SCHED;
;             PG8_LDA(At, 0, 1); PG8_STAGE(PG8_SB(0, 0), b2, voffB); PG8_STAGE(PG8_SB(0, 1), b2 + hstepB, voffB); PG8_STAGE(PG8_SA(0, 0), a2, voffA);
.LBB0_1029:
	s_add_u32 s16, s85, s2
	s_addc_u32 s17, s94, s3
	s_add_u32 s16, s16, 0x4600100
	s_addc_u32 s17, s17, 0
	s_add_u32 s22, s95, s2
	s_addc_u32 s41, s97, s3
	s_add_i32 s84, 0, 0x10000
	s_cmpk_eq_i32 s2, 0x700
	s_cselect_b32 s19, s11, s17
	s_cselect_b32 s18, s10, s16
	v_add_u32_e32 v119, s84, v117
	s_cselect_b32 s17, s1, s41
	s_cselect_b32 s16, s0, s22
	s_add_i32 s96, 0, 0x14000
	ds_read_b128 v[148:151], v119
	ds_read_b128 v[152:155], v119 offset:1024
	ds_read_b128 v[156:159], v119 offset:2048
	ds_read_b128 v[160:163], v119 offset:3072
	v_add_u32_e32 v119, s96, v117
	ds_read_b128 v[164:167], v119
	ds_read_b128 v[168:171], v119 offset:1024
	ds_read_b128 v[172:175], v119 offset:2048
	ds_read_b128 v[176:179], v119 offset:3072
	v_lshl_add_u64 v[120:121], v[104:105], 0, s[2:3]
	s_add_i32 m0, s31, 0xc000
	ds_read_b128 v[180:183], v118
	ds_read_b128 v[184:187], v118 offset:1024
	ds_read_b128 v[188:191], v118 offset:2048
	ds_read_b128 v[192:195], v118 offset:3072
	ds_read_b128 v[210:213], v118 offset:4096
	ds_read_b128 v[214:217], v118 offset:5120
	ds_read_b128 v[218:221], v118 offset:6144
	ds_read_b128 v[242:245], v118 offset:7168
	global_load_lds_dwordx4 v[120:121], off
	v_lshl_add_u64 v[120:121], v[114:115], 0, s[2:3]
	s_add_i32 m0, s31, 0xe000
	s_nop 0
	global_load_lds_dwordx4 v[120:121], off
	s_waitcnt vmcnt(8)
	s_waitcnt lgkmcnt(0)
	s_barrier
	s_setprio 1
	v_mfma_f32_16x16x32_bf16 v[142:145], v[148:151], v[180:183], v[142:145]
	v_mfma_f32_16x16x32_bf16 v[138:141], v[156:159], v[180:183], v[138:141]
	v_mfma_f32_16x16x32_bf16 v[126:129], v[148:151], v[188:191], v[126:129]
	v_mfma_f32_16x16x32_bf16 v[120:123], v[156:159], v[188:191], v[122:125]
	v_mfma_f32_16x16x32_bf16 v[94:97], v[148:151], v[210:213], v[94:97]
	v_mfma_f32_16x16x32_bf16 v[90:93], v[156:159], v[210:213], v[90:93]
	v_mfma_f32_16x16x32_bf16 v[78:81], v[148:151], v[218:221], v[78:81]
	v_mfma_f32_16x16x32_bf16 v[74:77], v[156:159], v[218:221], v[74:77]
	v_mfma_f32_16x16x32_bf16 v[142:145], v[152:155], v[184:187], v[142:145]
	v_mfma_f32_16x16x32_bf16 v[138:141], v[160:163], v[184:187], v[138:141]
	v_mfma_f32_16x16x32_bf16 v[126:129], v[152:155], v[192:195], v[126:129]
	v_mfma_f32_16x16x32_bf16 v[120:123], v[160:163], v[192:195], v[120:123]
	v_mfma_f32_16x16x32_bf16 v[94:97], v[152:155], v[214:217], v[94:97]
	v_mfma_f32_16x16x32_bf16 v[90:93], v[160:163], v[214:217], v[90:93]
	v_mfma_f32_16x16x32_bf16 v[78:81], v[152:155], v[242:245], v[78:81]
	v_mfma_f32_16x16x32_bf16 v[74:77], v[160:163], v[242:245], v[74:77]
	s_setprio 0
	s_setprio 1
	v_mfma_f32_16x16x32_bf16 v[134:137], v[164:167], v[180:183], v[134:137]
	v_mfma_f32_16x16x32_bf16 v[130:133], v[172:175], v[180:183], v[130:133]
	v_mfma_f32_16x16x32_bf16 v[110:113], v[164:167], v[188:191], v[110:113]
	v_mfma_f32_16x16x32_bf16 v[106:109], v[172:175], v[188:191], v[106:109]
	v_mfma_f32_16x16x32_bf16 v[86:89], v[164:167], v[210:213], v[86:89]
	v_mfma_f32_16x16x32_bf16 v[82:85], v[172:175], v[210:213], v[82:85]
	v_mfma_f32_16x16x32_bf16 v[70:73], v[164:167], v[218:221], v[70:73]
	v_mfma_f32_16x16x32_bf16 v[66:69], v[172:175], v[218:221], v[66:69]
	v_mfma_f32_16x16x32_bf16 v[134:137], v[168:171], v[184:187], v[134:137]
	v_mfma_f32_16x16x32_bf16 v[130:133], v[176:179], v[184:187], v[130:133]
	v_mfma_f32_16x16x32_bf16 v[110:113], v[168:171], v[192:195], v[110:113]
	v_mfma_f32_16x16x32_bf16 v[106:109], v[176:179], v[192:195], v[106:109]
	v_mfma_f32_16x16x32_bf16 v[86:89], v[168:171], v[214:217], v[86:89]
	v_mfma_f32_16x16x32_bf16 v[82:85], v[176:179], v[214:217], v[82:85]
	v_mfma_f32_16x16x32_bf16 v[70:73], v[168:171], v[242:245], v[70:73]
	v_mfma_f32_16x16x32_bf16 v[66:69], v[176:179], v[242:245], v[66:69]
	s_setprio 0
	s_barrier
	s_add_i32 s22, s84, s30
	v_lshl_add_u64 v[222:223], s[16:17], 0, v[64:65]
	s_mov_b32 m0, s22
	ds_read_b128 v[180:183], v118 offset:16384
	ds_read_b128 v[184:187], v118 offset:17408
	ds_read_b128 v[188:191], v118 offset:18432
	ds_read_b128 v[192:195], v118 offset:19456
	ds_read_b128 v[210:213], v118 offset:20480
	ds_read_b128 v[214:217], v118 offset:21504
	ds_read_b128 v[218:221], v118 offset:22528
	ds_read_b128 v[242:245], v118 offset:23552
	global_load_lds_dwordx4 v[222:223], off
	s_add_i32 m0, s22, 0x2000
	s_add_u32 s76, s16, 0x40000
	v_lshl_add_u64 v[230:231], s[16:17], 0, v[102:103]
	s_addc_u32 s77, s17, 0
	s_add_i32 s22, s96, s30
	global_load_lds_dwordx4 v[230:231], off
	v_lshl_add_u64 v[124:125], s[76:77], 0, v[64:65]
	s_mov_b32 m0, s22
	v_lshl_add_u64 v[232:233], s[18:19], 0, v[98:99]
	global_load_lds_dwordx4 v[124:125], off
	v_lshl_add_u64 v[124:125], s[76:77], 0, v[102:103]
	s_add_i32 m0, s22, 0x2000
	v_lshl_add_u64 v[246:247], s[18:19], 0, v[100:101]
	global_load_lds_dwordx4 v[124:125], off
	s_mov_b32 m0, s31
	s_nop 0
	global_load_lds_dwordx4 v[232:233], off
	s_mov_b32 m0, s24
	s_nop 0
	global_load_lds_dwordx4 v[246:247], off
	s_waitcnt vmcnt(8)
	s_waitcnt lgkmcnt(0)
	s_barrier
; #define PG8_STAGE(bufoff, gbase, voff) do { _Pragma("unroll") for (int _i = 0; _i < 2; ++_i) \
;         __builtin_amdgcn_global_load_lds((const unsigned*)((const char*)(gbase) + (voff)[_i]), (PG8_LAS unsigned*)(lds + (bufoff) + ldsw + _i * 8192), 16, 0, 0); } while (0)
; #define PG8_LDA(dst, b, h) do { _Pragma("unroll") for (int m = 0; m < 4; ++m) _Pragma("unroll") for (int k = 0; k < 2; ++k) dst[m][k] = *(const PG8_LAS bf16x8*)(lds + PG8_SA(b, h) + aoff + m * 2048 + k * 1024); } while (0)
; #define PG8_LDB(dst, b, h) do { _Pragma("unroll") for (int n = 0; n < 2; ++n) _Pragma("unroll") for (int k = 0; k < 2; ++k) dst[n][k] = *(const PG8_LAS bf16x8*)(lds + PG8_SB(b, h) + boff + n * 2048 + k * 1024); } while (0)
; #define PG8_MMA(ai, bj, At, Bt) do { __builtin_amdgcn_s_setprio(1); _Pragma("unroll") for (int m = 0; m < 4; ++m) _Pragma("unroll") for (int n = 0; n < 2; ++n) _Pragma("unroll") for (int k = 0; k < 2; ++k) \
;         acc[ai][bj][m][n] = __builtin_amdgcn_mfma_f32_16x16x32_bf16(Bt[n][k], At[m][k], acc[ai][bj][m][n], 0, 0, 0); __builtin_amdgcn_s_setprio(0); } while (0)
; #define PG8_WAIT_V(n) asm volatile("s_waitcnt vmcnt(" #n ")" ::: "memory")
; #define PG8_WAIT_L(n) asm volatile("s_waitcnt lgkmcnt(" #n ")" ::: "memory")
; #define PG8_BAR __builtin_amdgcn_s_barrier()
; #define PG8_SCHED __builtin_amdgcn_sched_barrier(0)
; template <class Epi, class Sched, bool ALIGN_EPI = false, bool SP2 = false>
; __device__ __forceinline__ void gemm_phase(PG8_LAS unsigned char* lds, const Gemm g, const Sched& S, const Epi& E) {
;     ...
;             PG8_WAIT_V(8); PG8_WAIT_L(0); PG8_BAR; PG8_MMA(1, 0, At, B0); PG8_MMA(1, 1, At, B1); PG8_BAR; PG8_SCHED;
;             PG8_LDB(B0, 1, 0); PG8_LDB(B1, 1, 1); PG8_SCHED; PG8_LDA(At, 1, 0); PG8_STAGE(PG8_SA(0, 1), a2 + hstepA, voffA);
;             PG8_WAIT_V(8); PG8_WAIT_L(0); PG8_BAR; PG8_MMA(0, 0, At, B0); PG8_MMA(0, 1, At, B1); PG8_BAR; PG8_SCHED;
	s_setprio 1
	v_mfma_f32_16x16x32_bf16 v[60:63], v[148:151], v[180:183], v[60:63]
	v_mfma_f32_16x16x32_bf16 v[56:59], v[156:159], v[180:183], v[56:59]
	v_mfma_f32_16x16x32_bf16 v[44:47], v[148:151], v[188:191], v[44:47]
	v_mfma_f32_16x16x32_bf16 v[40:43], v[156:159], v[188:191], v[40:43]
	v_mfma_f32_16x16x32_bf16 v[28:31], v[148:151], v[210:213], v[28:31]
	v_mfma_f32_16x16x32_bf16 v[24:27], v[156:159], v[210:213], v[24:27]
	v_mfma_f32_16x16x32_bf16 v[12:15], v[148:151], v[218:221], v[12:15]
	v_mfma_f32_16x16x32_bf16 v[8:11], v[156:159], v[218:221], v[8:11]
	v_mfma_f32_16x16x32_bf16 v[60:63], v[152:155], v[184:187], v[60:63]
	v_mfma_f32_16x16x32_bf16 v[56:59], v[160:163], v[184:187], v[56:59]
	v_mfma_f32_16x16x32_bf16 v[44:47], v[152:155], v[192:195], v[44:47]
	v_mfma_f32_16x16x32_bf16 v[40:43], v[160:163], v[192:195], v[40:43]
	v_mfma_f32_16x16x32_bf16 v[28:31], v[152:155], v[214:217], v[28:31]
	v_mfma_f32_16x16x32_bf16 v[24:27], v[160:163], v[214:217], v[24:27]
	v_mfma_f32_16x16x32_bf16 v[12:15], v[152:155], v[242:245], v[12:15]
	v_mfma_f32_16x16x32_bf16 v[8:11], v[160:163], v[242:245], v[8:11]
	s_setprio 0
	s_setprio 1
	v_mfma_f32_16x16x32_bf16 v[52:55], v[164:167], v[180:183], v[52:55]
	v_mfma_f32_16x16x32_bf16 v[48:51], v[172:175], v[180:183], v[48:51]
	v_mfma_f32_16x16x32_bf16 v[36:39], v[164:167], v[188:191], v[36:39]
	v_mfma_f32_16x16x32_bf16 v[32:35], v[172:175], v[188:191], v[32:35]
	v_mfma_f32_16x16x32_bf16 v[20:23], v[164:167], v[210:213], v[20:23]
	v_mfma_f32_16x16x32_bf16 v[16:19], v[172:175], v[210:213], v[16:19]
	v_mfma_f32_16x16x32_bf16 v[4:7], v[164:167], v[218:221], v[4:7]
	v_mfma_f32_16x16x32_bf16 v[0:3], v[172:175], v[218:221], v[0:3]
	v_mfma_f32_16x16x32_bf16 v[52:55], v[168:171], v[184:187], v[52:55]
	v_mfma_f32_16x16x32_bf16 v[48:51], v[176:179], v[184:187], v[48:51]
	v_mfma_f32_16x16x32_bf16 v[36:39], v[168:171], v[192:195], v[36:39]
	v_mfma_f32_16x16x32_bf16 v[32:35], v[176:179], v[192:195], v[32:35]
	v_mfma_f32_16x16x32_bf16 v[20:23], v[168:171], v[214:217], v[20:23]
	v_mfma_f32_16x16x32_bf16 v[16:19], v[176:179], v[214:217], v[16:19]
	v_mfma_f32_16x16x32_bf16 v[4:7], v[168:171], v[242:245], v[4:7]
	v_mfma_f32_16x16x32_bf16 v[0:3], v[176:179], v[242:245], v[0:3]
	s_setprio 0
	s_barrier
	s_add_i32 s43, 0, 0x18000
	v_add_u32_e32 v119, s43, v117
	s_add_i32 s22, 0, 0x1c000
	ds_read_b128 v[148:151], v119
	ds_read_b128 v[152:155], v119 offset:1024
	ds_read_b128 v[156:159], v119 offset:2048
	ds_read_b128 v[160:163], v119 offset:3072
	v_add_u32_e32 v119, s22, v117
	ds_read_b128 v[164:167], v119
	ds_read_b128 v[168:171], v119 offset:1024
	ds_read_b128 v[172:175], v119 offset:2048
	ds_read_b128 v[176:179], v119 offset:3072
	s_add_u32 s18, s18, 0x40000
	s_addc_u32 s19, s19, 0
	s_mov_b32 m0, s25
	v_lshl_add_u64 v[124:125], s[18:19], 0, v[98:99]
	ds_read_b128 v[180:183], v118 offset:32768
	ds_read_b128 v[184:187], v118 offset:33792
	ds_read_b128 v[188:191], v118 offset:34816
	ds_read_b128 v[192:195], v118 offset:35840
	ds_read_b128 v[210:213], v118 offset:36864
	ds_read_b128 v[214:217], v118 offset:37888
	ds_read_b128 v[218:221], v118 offset:38912
	ds_read_b128 v[242:245], v118 offset:39936
	global_load_lds_dwordx4 v[124:125], off
	v_lshl_add_u64 v[124:125], s[18:19], 0, v[100:101]
	s_mov_b32 m0, s34
	s_nop 0
	global_load_lds_dwordx4 v[124:125], off
	s_waitcnt vmcnt(8)
	s_waitcnt lgkmcnt(0)
	s_barrier
	s_setprio 1
	v_mfma_f32_16x16x32_bf16 v[142:145], v[148:151], v[180:183], v[142:145]
	v_mfma_f32_16x16x32_bf16 v[138:141], v[156:159], v[180:183], v[138:141]
	v_mfma_f32_16x16x32_bf16 v[124:127], v[148:151], v[188:191], v[126:129]
	v_mfma_f32_16x16x32_bf16 v[120:123], v[156:159], v[188:191], v[120:123]
	v_mfma_f32_16x16x32_bf16 v[94:97], v[148:151], v[210:213], v[94:97]
	v_mfma_f32_16x16x32_bf16 v[90:93], v[156:159], v[210:213], v[90:93]
	v_mfma_f32_16x16x32_bf16 v[78:81], v[148:151], v[218:221], v[78:81]
	v_mfma_f32_16x16x32_bf16 v[74:77], v[156:159], v[218:221], v[74:77]
	v_mfma_f32_16x16x32_bf16 v[142:145], v[152:155], v[184:187], v[142:145]
	v_mfma_f32_16x16x32_bf16 v[138:141], v[160:163], v[184:187], v[138:141]
	v_mfma_f32_16x16x32_bf16 v[126:129], v[152:155], v[192:195], v[124:127]
	v_mfma_f32_16x16x32_bf16 v[122:125], v[160:163], v[192:195], v[120:123]
	v_mfma_f32_16x16x32_bf16 v[94:97], v[152:155], v[214:217], v[94:97]
	v_mfma_f32_16x16x32_bf16 v[90:93], v[160:163], v[214:217], v[90:93]
	v_mfma_f32_16x16x32_bf16 v[78:81], v[152:155], v[242:245], v[78:81]
	v_mfma_f32_16x16x32_bf16 v[74:77], v[160:163], v[242:245], v[74:77]
	s_setprio 0
	s_setprio 1
	v_mfma_f32_16x16x32_bf16 v[134:137], v[164:167], v[180:183], v[134:137]
	v_mfma_f32_16x16x32_bf16 v[130:133], v[172:175], v[180:183], v[130:133]
	v_mfma_f32_16x16x32_bf16 v[110:113], v[164:167], v[188:191], v[110:113]
	v_mfma_f32_16x16x32_bf16 v[106:109], v[172:175], v[188:191], v[106:109]
	v_mfma_f32_16x16x32_bf16 v[86:89], v[164:167], v[210:213], v[86:89]
	v_mfma_f32_16x16x32_bf16 v[82:85], v[172:175], v[210:213], v[82:85]
	v_mfma_f32_16x16x32_bf16 v[70:73], v[164:167], v[218:221], v[70:73]
	v_mfma_f32_16x16x32_bf16 v[66:69], v[172:175], v[218:221], v[66:69]
	v_mfma_f32_16x16x32_bf16 v[134:137], v[168:171], v[184:187], v[134:137]
	v_mfma_f32_16x16x32_bf16 v[130:133], v[176:179], v[184:187], v[130:133]
	v_mfma_f32_16x16x32_bf16 v[110:113], v[168:171], v[192:195], v[110:113]
	v_mfma_f32_16x16x32_bf16 v[106:109], v[176:179], v[192:195], v[106:109]
	v_mfma_f32_16x16x32_bf16 v[86:89], v[168:171], v[214:217], v[86:89]
	v_mfma_f32_16x16x32_bf16 v[82:85], v[176:179], v[214:217], v[82:85]
	v_mfma_f32_16x16x32_bf16 v[70:73], v[168:171], v[242:245], v[70:73]
	v_mfma_f32_16x16x32_bf16 v[66:69], v[176:179], v[242:245], v[66:69]
	s_setprio 0
	s_barrier
; #define PG8_STAGE(bufoff, gbase, voff) do { _Pragma("unroll") for (int _i = 0; _i < 2; ++_i) \
;         __builtin_amdgcn_global_load_lds((const unsigned*)((const char*)(gbase) + (voff)[_i]), (PG8_LAS unsigned*)(lds + (bufoff) + ldsw + _i * 8192), 16, 0, 0); } while (0)
; #define PG8_LDA(dst, b, h) do { _Pragma("unroll") for (int m = 0; m < 4; ++m) _Pragma("unroll") for (int k = 0; k < 2; ++k) dst[m][k] = *(const PG8_LAS bf16x8*)(lds + PG8_SA(b, h) + aoff + m * 2048 + k * 1024); } while (0)
; #define PG8_MMA(ai, bj, At, Bt) do { __builtin_amdgcn_s_setprio(1); _Pragma("unroll") for (int m = 0; m < 4; ++m) _Pragma("unroll") for (int n = 0; n < 2; ++n) _Pragma("unroll") for (int k = 0; k < 2; ++k) \
;         acc[ai][bj][m][n] = __builtin_amdgcn_mfma_f32_16x16x32_bf16(Bt[n][k], At[m][k], acc[ai][bj][m][n], 0, 0, 0); __builtin_amdgcn_s_setprio(0); } while (0)
; #define PG8_WAIT_V(n) asm volatile("s_waitcnt vmcnt(" #n ")" ::: "memory")
; #define PG8_WAIT_L(n) asm volatile("s_waitcnt lgkmcnt(" #n ")" ::: "memory")
; #define PG8_BAR __builtin_amdgcn_s_barrier()
; #define PG8_SCHED __builtin_amdgcn_sched_barrier(0)
; template <class Epi, class Sched, bool ALIGN_EPI = false, bool SP2 = false>
; __device__ __forceinline__ void gemm_phase(PG8_LAS unsigned char* lds, const Gemm g, const Sched& S, const Epi& E) {
;     ...
;             PG8_LDA(At, 1, 1); PG8_STAGE(PG8_SB(1, 0), b3, voffB); PG8_STAGE(PG8_SB(1, 1), b3 + hstepB, voffB); PG8_STAGE(PG8_SA(1, 0), a3, voffA);
;             PG8_WAIT_V(8); PG8_WAIT_L(0); PG8_BAR; PG8_MMA(1, 0, At, B0); PG8_MMA(1, 1, At, B1); PG8_BAR; PG8_SCHED;
;     ...
;         }
;         if constexpr (ALIGN_EPI) { if (wr == 0) PG8_BAR; }
	s_add_i32 s18, s43, s30
	v_lshl_add_u64 v[120:121], v[222:223], 0, s[48:49]
	s_mov_b32 m0, s18
	ds_read_b128 v[180:183], v118 offset:49152
	ds_read_b128 v[184:187], v118 offset:50176
	ds_read_b128 v[188:191], v118 offset:51200
	ds_read_b128 v[192:195], v118 offset:52224
	ds_read_b128 v[210:213], v118 offset:53248
	ds_read_b128 v[214:217], v118 offset:54272
	ds_read_b128 v[218:221], v118 offset:55296
	ds_read_b128 v[242:245], v118 offset:56320
	global_load_lds_dwordx4 v[120:121], off
	s_add_i32 m0, s18, 0x2000
	s_add_u32 s16, s16, 0x40080
	v_lshl_add_u64 v[120:121], v[230:231], 0, s[48:49]
	s_addc_u32 s17, s17, 0
	s_add_i32 s18, s22, s30
	global_load_lds_dwordx4 v[120:121], off
	v_lshl_add_u64 v[120:121], s[16:17], 0, v[64:65]
	s_mov_b32 m0, s18
	s_nop 0
	global_load_lds_dwordx4 v[120:121], off
	v_lshl_add_u64 v[120:121], s[16:17], 0, v[102:103]
	s_add_i32 m0, s18, 0x2000
	s_nop 0
	global_load_lds_dwordx4 v[120:121], off
	v_lshl_add_u64 v[120:121], v[232:233], 0, s[48:49]
	s_mov_b32 m0, s61
	s_nop 0
	global_load_lds_dwordx4 v[120:121], off
	v_lshl_add_u64 v[120:121], v[246:247], 0, s[48:49]
	s_mov_b32 m0, vcc_lo
	s_nop 0
	global_load_lds_dwordx4 v[120:121], off
	s_waitcnt vmcnt(8)
	s_waitcnt lgkmcnt(0)
	s_barrier
	s_setprio 1
	v_mfma_f32_16x16x32_bf16 v[60:63], v[148:151], v[180:183], v[60:63]
	v_mfma_f32_16x16x32_bf16 v[56:59], v[156:159], v[180:183], v[56:59]
	v_mfma_f32_16x16x32_bf16 v[44:47], v[148:151], v[188:191], v[44:47]
	v_mfma_f32_16x16x32_bf16 v[40:43], v[156:159], v[188:191], v[40:43]
	v_mfma_f32_16x16x32_bf16 v[28:31], v[148:151], v[210:213], v[28:31]
	v_mfma_f32_16x16x32_bf16 v[24:27], v[156:159], v[210:213], v[24:27]
	v_mfma_f32_16x16x32_bf16 v[12:15], v[148:151], v[218:221], v[12:15]
	v_mfma_f32_16x16x32_bf16 v[8:11], v[156:159], v[218:221], v[8:11]
	v_mfma_f32_16x16x32_bf16 v[60:63], v[152:155], v[184:187], v[60:63]
	v_mfma_f32_16x16x32_bf16 v[56:59], v[160:163], v[184:187], v[56:59]
	v_mfma_f32_16x16x32_bf16 v[44:47], v[152:155], v[192:195], v[44:47]
	v_mfma_f32_16x16x32_bf16 v[40:43], v[160:163], v[192:195], v[40:43]
	v_mfma_f32_16x16x32_bf16 v[28:31], v[152:155], v[214:217], v[28:31]
	v_mfma_f32_16x16x32_bf16 v[24:27], v[160:163], v[214:217], v[24:27]
	v_mfma_f32_16x16x32_bf16 v[12:15], v[152:155], v[242:245], v[12:15]
	v_mfma_f32_16x16x32_bf16 v[8:11], v[160:163], v[242:245], v[8:11]
	s_setprio 0
	s_setprio 1
	v_mfma_f32_16x16x32_bf16 v[52:55], v[164:167], v[180:183], v[52:55]
	v_mfma_f32_16x16x32_bf16 v[48:51], v[172:175], v[180:183], v[48:51]
	v_mfma_f32_16x16x32_bf16 v[36:39], v[164:167], v[188:191], v[36:39]
	v_mfma_f32_16x16x32_bf16 v[32:35], v[172:175], v[188:191], v[32:35]
	v_mfma_f32_16x16x32_bf16 v[20:23], v[164:167], v[210:213], v[20:23]
	v_mfma_f32_16x16x32_bf16 v[16:19], v[172:175], v[210:213], v[16:19]
	v_mfma_f32_16x16x32_bf16 v[4:7], v[164:167], v[218:221], v[4:7]
	v_mfma_f32_16x16x32_bf16 v[0:3], v[172:175], v[218:221], v[0:3]
	v_mfma_f32_16x16x32_bf16 v[52:55], v[168:171], v[184:187], v[52:55]
	v_mfma_f32_16x16x32_bf16 v[48:51], v[176:179], v[184:187], v[48:51]
	v_mfma_f32_16x16x32_bf16 v[36:39], v[168:171], v[192:195], v[36:39]
	v_mfma_f32_16x16x32_bf16 v[32:35], v[176:179], v[192:195], v[32:35]
	v_mfma_f32_16x16x32_bf16 v[20:23], v[168:171], v[214:217], v[20:23]
	v_mfma_f32_16x16x32_bf16 v[16:19], v[176:179], v[214:217], v[16:19]
	v_mfma_f32_16x16x32_bf16 v[4:7], v[168:171], v[242:245], v[4:7]
	v_mfma_f32_16x16x32_bf16 v[0:3], v[176:179], v[242:245], v[0:3]
	s_setprio 0
	s_barrier
	s_add_i32 s62, s62, 2
	s_add_u32 s2, s2, 0x100
	s_addc_u32 s3, s3, 0
	s_cmp_gt_u32 s62, 13
	s_cbranch_scc0 .LBB0_1029
	s_cmpk_lt_u32 s23, 0x100
	s_cbranch_scc0 .LBB0_1032
	s_barrier

; #define PG8_STAGE(bufoff, gbase, voff) do { _Pragma("unroll") for (int _i = 0; _i < 2; ++_i) \
;         __builtin_amdgcn_global_load_lds((const unsigned*)((const char*)(gbase) + (voff)[_i]), (PG8_LAS unsigned*)(lds + (bufoff) + ldsw + _i * 8192), 16, 0, 0); } while (0)
; #define PG8_LDA(dst, b, h) do { _Pragma("unroll") for (int m = 0; m < 4; ++m) _Pragma("unroll") for (int k = 0; k < 2; ++k) dst[m][k] = *(const PG8_LAS bf16x8*)(lds + PG8_SA(b, h) + aoff + m * 2048 + k * 1024); } while (0)
; #define PG8_LDB(dst, b, h) do { _Pragma("unroll") for (int n = 0; n < 2; ++n) _Pragma("unroll") for (int k = 0; k < 2; ++k) dst[n][k] = *(const PG8_LAS bf16x8*)(lds + PG8_SB(b, h) + boff + n * 2048 + k * 1024); } while (0)
; #define PG8_MMA(ai, bj, At, Bt) do { __builtin_amdgcn_s_setprio(1); _Pragma("unroll") for (int m = 0; m < 4; ++m) _Pragma("unroll") for (int n = 0; n < 2; ++n) _Pragma("unroll") for (int k = 0; k < 2; ++k) \
;         acc[ai][bj][m][n] = __builtin_amdgcn_mfma_f32_16x16x32_bf16(Bt[n][k], At[m][k], acc[ai][bj][m][n], 0, 0, 0); __builtin_amdgcn_s_setprio(0); } while (0)
; #define PG8_WAIT_V(n) asm volatile("s_waitcnt vmcnt(" #n ")" ::: "memory")
; #define PG8_WAIT_L(n) asm volatile("s_waitcnt lgkmcnt(" #n ")" ::: "memory")
; #define PG8_BAR __builtin_amdgcn_s_barrier()
; #define PG8_SCHED __builtin_amdgcn_sched_barrier(0)
; template <class Epi, class Sched, bool ALIGN_EPI = false, bool SP2 = false>
; __device__ __forceinline__ void gemm_phase(PG8_LAS unsigned char* lds, const Gemm g, const Sched& S, const Epi& E) {
;     ...
;             const bool last = (t == nt - 2);
;             const char* a1 = cA + (size_t)(t + 1) * kstep;
;             const char* a2 = last ? nA : cA + (size_t)(t + 2) * kstep; const char* b2 = last ? nB : cB + (size_t)(t + 2) * kstep;
;             const char* a3 = a2 + kstep; const char* b3 = b2 + kstep;
;             if (last && has_next) S.a_ready(nxt);
;             if constexpr (SP2) {
;             PG8_LDB(B0, 0, 0); PG8_LDB(B1, 0, 1); PG8_SCHED; PG8_LDA(At, 0, 0); PG8_STAGE(PG8_SA(1, 1), a1 + hstepA, voffA);
;             PG8_WAIT_V(8); PG8_WAIT_L(0); PG8_BAR; PG8_MMA(0, 0, At, B0); PG8_MMA(0, 1, At, B1); PG8_BAR; PG8_SCHED;
;             PG8_LDA(At, 0, 1); PG8_STAGE(PG8_SB(0, 0), b2, voffB); PG8_STAGE(PG8_SB(0, 1), b2 + hstepB, voffB); PG8_STAGE(PG8_SA(0, 0), a2, voffA);
.LBB0_1035:
	s_add_i32 s41, s30, 2
	v_add_u32_e32 v156, s84, v142
	v_add_u32_e32 v172, s96, v142
	s_add_u32 s20, s18, 0x100
	ds_read_b128 v[144:147], v156
	ds_read_b128 v[148:151], v156 offset:1024
	ds_read_b128 v[152:155], v156 offset:2048
	ds_read_b128 v[156:159], v156 offset:3072
	ds_read_b128 v[160:163], v172
	ds_read_b128 v[164:167], v172 offset:1024
	ds_read_b128 v[168:171], v172 offset:2048
	ds_read_b128 v[172:175], v172 offset:3072
	s_addc_u32 s21, s19, 0
	s_cmp_lg_u32 s62, s30
	s_cselect_b32 s76, s20, 0
	s_cselect_b32 s77, s21, 0
	s_add_u32 s30, s16, s76
	s_addc_u32 s31, s17, s77
	s_add_u32 s76, s2, s76
	s_addc_u32 s77, s3, s77
	v_lshl_add_u64 v[222:223], v[136:137], 0, s[18:19]
	s_add_i32 m0, vcc_hi, 0xc000
	ds_read_b128 v[176:179], v143
	ds_read_b128 v[180:183], v143 offset:1024
	ds_read_b128 v[184:187], v143 offset:2048
	ds_read_b128 v[188:191], v143 offset:3072
	ds_read_b128 v[192:195], v143 offset:4096
	ds_read_b128 v[210:213], v143 offset:5120
	ds_read_b128 v[214:217], v143 offset:6144
	ds_read_b128 v[218:221], v143 offset:7168
	global_load_lds_dwordx4 v[222:223], off
	v_lshl_add_u64 v[222:223], v[138:139], 0, s[18:19]
	s_add_i32 m0, vcc_hi, 0xe000
	s_nop 0
	global_load_lds_dwordx4 v[222:223], off
	s_waitcnt vmcnt(8)
	s_waitcnt lgkmcnt(0)
	s_barrier
	s_setprio 1
	v_mfma_f32_16x16x32_bf16 v[128:131], v[144:147], v[176:179], v[128:131]
	v_mfma_f32_16x16x32_bf16 v[124:127], v[152:155], v[176:179], v[124:127]
	v_mfma_f32_16x16x32_bf16 v[116:119], v[144:147], v[184:187], v[116:119]
	v_mfma_f32_16x16x32_bf16 v[108:111], v[152:155], v[184:187], v[108:111]
	v_mfma_f32_16x16x32_bf16 v[100:103], v[144:147], v[192:195], v[100:103]
	v_mfma_f32_16x16x32_bf16 v[92:95], v[152:155], v[192:195], v[92:95]
	v_mfma_f32_16x16x32_bf16 v[84:87], v[144:147], v[214:217], v[84:87]
	v_mfma_f32_16x16x32_bf16 v[76:79], v[152:155], v[214:217], v[76:79]
	v_mfma_f32_16x16x32_bf16 v[128:131], v[148:151], v[180:183], v[128:131]
	v_mfma_f32_16x16x32_bf16 v[124:127], v[156:159], v[180:183], v[124:127]
	v_mfma_f32_16x16x32_bf16 v[116:119], v[148:151], v[188:191], v[116:119]
	v_mfma_f32_16x16x32_bf16 v[108:111], v[156:159], v[188:191], v[108:111]
	v_mfma_f32_16x16x32_bf16 v[100:103], v[148:151], v[210:213], v[100:103]
	v_mfma_f32_16x16x32_bf16 v[92:95], v[156:159], v[210:213], v[92:95]
	v_mfma_f32_16x16x32_bf16 v[84:87], v[148:151], v[218:221], v[84:87]
	v_mfma_f32_16x16x32_bf16 v[76:79], v[156:159], v[218:221], v[76:79]
	s_setprio 0
	s_setprio 1
	v_mfma_f32_16x16x32_bf16 v[120:123], v[160:163], v[176:179], v[120:123]
	v_mfma_f32_16x16x32_bf16 v[112:115], v[168:171], v[176:179], v[112:115]
	v_mfma_f32_16x16x32_bf16 v[104:107], v[160:163], v[184:187], v[104:107]
	v_mfma_f32_16x16x32_bf16 v[96:99], v[168:171], v[184:187], v[96:99]
	v_mfma_f32_16x16x32_bf16 v[88:91], v[160:163], v[192:195], v[88:91]
	v_mfma_f32_16x16x32_bf16 v[80:83], v[168:171], v[192:195], v[80:83]
	v_mfma_f32_16x16x32_bf16 v[72:75], v[160:163], v[214:217], v[72:75]
	v_mfma_f32_16x16x32_bf16 v[68:71], v[168:171], v[214:217], v[68:71]
	v_mfma_f32_16x16x32_bf16 v[120:123], v[164:167], v[180:183], v[120:123]
	v_mfma_f32_16x16x32_bf16 v[112:115], v[172:175], v[180:183], v[112:115]
	v_mfma_f32_16x16x32_bf16 v[104:107], v[164:167], v[188:191], v[104:107]
	v_mfma_f32_16x16x32_bf16 v[96:99], v[172:175], v[188:191], v[96:99]
	v_mfma_f32_16x16x32_bf16 v[88:91], v[164:167], v[210:213], v[88:91]
	v_mfma_f32_16x16x32_bf16 v[80:83], v[172:175], v[210:213], v[80:83]
	v_mfma_f32_16x16x32_bf16 v[72:75], v[164:167], v[218:221], v[72:75]
	v_mfma_f32_16x16x32_bf16 v[68:71], v[172:175], v[218:221], v[68:71]
	s_setprio 0
	s_barrier
	s_add_i32 s18, s84, vcc_lo
	v_lshl_add_u64 v[222:223], s[76:77], 0, v[64:65]
	s_mov_b32 m0, s18
	ds_read_b128 v[176:179], v143 offset:16384
	ds_read_b128 v[180:183], v143 offset:17408
	ds_read_b128 v[184:187], v143 offset:18432
	ds_read_b128 v[188:191], v143 offset:19456
	ds_read_b128 v[192:195], v143 offset:20480
	ds_read_b128 v[210:213], v143 offset:21504
	ds_read_b128 v[214:217], v143 offset:22528
	ds_read_b128 v[218:221], v143 offset:23552
	global_load_lds_dwordx4 v[222:223], off
	s_add_i32 m0, s18, 0x2000
	s_add_u32 s18, s76, s34
	v_lshl_add_u64 v[230:231], s[76:77], 0, v[134:135]
	s_addc_u32 s19, s77, 0
	s_add_i32 s76, s96, vcc_lo
	global_load_lds_dwordx4 v[230:231], off
	v_lshl_add_u64 v[232:233], s[18:19], 0, v[64:65]
	s_mov_b32 m0, s76
	v_lshl_add_u64 v[242:243], s[18:19], 0, v[134:135]
	global_load_lds_dwordx4 v[232:233], off
	s_add_i32 m0, s76, 0x2000
	v_lshl_add_u64 v[244:245], s[30:31], 0, v[66:67]
	global_load_lds_dwordx4 v[242:243], off
	s_mov_b32 m0, vcc_hi
	v_lshl_add_u64 v[246:247], s[30:31], 0, v[132:133]
	global_load_lds_dwordx4 v[244:245], off
	s_mov_b32 m0, s24
	s_nop 0
	global_load_lds_dwordx4 v[246:247], off
	s_waitcnt vmcnt(8)
	s_waitcnt lgkmcnt(0)
	s_barrier
; #define PG8_STAGE(bufoff, gbase, voff) do { _Pragma("unroll") for (int _i = 0; _i < 2; ++_i) \
;         __builtin_amdgcn_global_load_lds((const unsigned*)((const char*)(gbase) + (voff)[_i]), (PG8_LAS unsigned*)(lds + (bufoff) + ldsw + _i * 8192), 16, 0, 0); } while (0)
; #define PG8_LDA(dst, b, h) do { _Pragma("unroll") for (int m = 0; m < 4; ++m) _Pragma("unroll") for (int k = 0; k < 2; ++k) dst[m][k] = *(const PG8_LAS bf16x8*)(lds + PG8_SA(b, h) + aoff + m * 2048 + k * 1024); } while (0)
; #define PG8_LDB(dst, b, h) do { _Pragma("unroll") for (int n = 0; n < 2; ++n) _Pragma("unroll") for (int k = 0; k < 2; ++k) dst[n][k] = *(const PG8_LAS bf16x8*)(lds + PG8_SB(b, h) + boff + n * 2048 + k * 1024); } while (0)
; #define PG8_MMA(ai, bj, At, Bt) do { __builtin_amdgcn_s_setprio(1); _Pragma("unroll") for (int m = 0; m < 4; ++m) _Pragma("unroll") for (int n = 0; n < 2; ++n) _Pragma("unroll") for (int k = 0; k < 2; ++k) \
;         acc[ai][bj][m][n] = __builtin_amdgcn_mfma_f32_16x16x32_bf16(Bt[n][k], At[m][k], acc[ai][bj][m][n], 0, 0, 0); __builtin_amdgcn_s_setprio(0); } while (0)
; #define PG8_WAIT_V(n) asm volatile("s_waitcnt vmcnt(" #n ")" ::: "memory")
; #define PG8_WAIT_L(n) asm volatile("s_waitcnt lgkmcnt(" #n ")" ::: "memory")
; #define PG8_BAR __builtin_amdgcn_s_barrier()
; #define PG8_SCHED __builtin_amdgcn_sched_barrier(0)
; template <class Epi, class Sched, bool ALIGN_EPI = false, bool SP2 = false>
; __device__ __forceinline__ void gemm_phase(PG8_LAS unsigned char* lds, const Gemm g, const Sched& S, const Epi& E) {
;     ...
;             PG8_WAIT_V(8); PG8_WAIT_L(0); PG8_BAR; PG8_MMA(1, 0, At, B0); PG8_MMA(1, 1, At, B1); PG8_BAR; PG8_SCHED;
;             PG8_LDB(B0, 1, 0); PG8_LDB(B1, 1, 1); PG8_SCHED; PG8_LDA(At, 1, 0); PG8_STAGE(PG8_SA(0, 1), a2 + hstepA, voffA);
;             PG8_WAIT_V(8); PG8_WAIT_L(0); PG8_BAR; PG8_MMA(0, 0, At, B0); PG8_MMA(0, 1, At, B1); PG8_BAR; PG8_SCHED;
	s_setprio 1
	v_mfma_f32_16x16x32_bf16 v[60:63], v[144:147], v[176:179], v[60:63]
	v_mfma_f32_16x16x32_bf16 v[56:59], v[152:155], v[176:179], v[56:59]
	v_mfma_f32_16x16x32_bf16 v[48:51], v[144:147], v[184:187], v[48:51]
	v_mfma_f32_16x16x32_bf16 v[40:43], v[152:155], v[184:187], v[40:43]
	v_mfma_f32_16x16x32_bf16 v[32:35], v[144:147], v[192:195], v[32:35]
	v_mfma_f32_16x16x32_bf16 v[24:27], v[152:155], v[192:195], v[24:27]
	v_mfma_f32_16x16x32_bf16 v[16:19], v[144:147], v[214:217], v[16:19]
	v_mfma_f32_16x16x32_bf16 v[8:11], v[152:155], v[214:217], v[8:11]
	v_mfma_f32_16x16x32_bf16 v[60:63], v[148:151], v[180:183], v[60:63]
	v_mfma_f32_16x16x32_bf16 v[56:59], v[156:159], v[180:183], v[56:59]
	v_mfma_f32_16x16x32_bf16 v[48:51], v[148:151], v[188:191], v[48:51]
	v_mfma_f32_16x16x32_bf16 v[40:43], v[156:159], v[188:191], v[40:43]
	v_mfma_f32_16x16x32_bf16 v[32:35], v[148:151], v[210:213], v[32:35]
	v_mfma_f32_16x16x32_bf16 v[24:27], v[156:159], v[210:213], v[24:27]
	v_mfma_f32_16x16x32_bf16 v[16:19], v[148:151], v[218:221], v[16:19]
	v_mfma_f32_16x16x32_bf16 v[8:11], v[156:159], v[218:221], v[8:11]
	s_setprio 0
	s_setprio 1
	v_mfma_f32_16x16x32_bf16 v[52:55], v[160:163], v[176:179], v[52:55]
	v_mfma_f32_16x16x32_bf16 v[44:47], v[168:171], v[176:179], v[44:47]
	v_mfma_f32_16x16x32_bf16 v[36:39], v[160:163], v[184:187], v[36:39]
	v_mfma_f32_16x16x32_bf16 v[28:31], v[168:171], v[184:187], v[28:31]
	v_mfma_f32_16x16x32_bf16 v[20:23], v[160:163], v[192:195], v[20:23]
	v_mfma_f32_16x16x32_bf16 v[12:15], v[168:171], v[192:195], v[12:15]
	v_mfma_f32_16x16x32_bf16 v[4:7], v[160:163], v[214:217], v[4:7]
	v_mfma_f32_16x16x32_bf16 v[0:3], v[168:171], v[214:217], v[0:3]
	v_mfma_f32_16x16x32_bf16 v[52:55], v[164:167], v[180:183], v[52:55]
	v_mfma_f32_16x16x32_bf16 v[44:47], v[172:175], v[180:183], v[44:47]
	v_mfma_f32_16x16x32_bf16 v[36:39], v[164:167], v[188:191], v[36:39]
	v_mfma_f32_16x16x32_bf16 v[28:31], v[172:175], v[188:191], v[28:31]
	v_mfma_f32_16x16x32_bf16 v[20:23], v[164:167], v[210:213], v[20:23]
	v_mfma_f32_16x16x32_bf16 v[12:15], v[172:175], v[210:213], v[12:15]
	v_mfma_f32_16x16x32_bf16 v[4:7], v[164:167], v[218:221], v[4:7]
	v_mfma_f32_16x16x32_bf16 v[0:3], v[172:175], v[218:221], v[0:3]
	s_setprio 0
	s_barrier
	v_add_u32_e32 v156, s43, v142
	v_add_u32_e32 v172, s22, v142
	ds_read_b128 v[144:147], v156
	ds_read_b128 v[148:151], v156 offset:1024
	ds_read_b128 v[152:155], v156 offset:2048
	ds_read_b128 v[156:159], v156 offset:3072
	ds_read_b128 v[160:163], v172
	ds_read_b128 v[164:167], v172 offset:1024
	ds_read_b128 v[168:171], v172 offset:2048
	ds_read_b128 v[172:175], v172 offset:3072
	s_add_u32 s18, s30, s34
	s_addc_u32 s19, s31, 0
	s_mov_b32 m0, s25
	v_lshl_add_u64 v[248:249], s[18:19], 0, v[66:67]
	ds_read_b128 v[176:179], v143 offset:32768
	ds_read_b128 v[180:183], v143 offset:33792
	ds_read_b128 v[184:187], v143 offset:34816
	ds_read_b128 v[188:191], v143 offset:35840
	ds_read_b128 v[192:195], v143 offset:36864
	ds_read_b128 v[210:213], v143 offset:37888
	ds_read_b128 v[214:217], v143 offset:38912
	ds_read_b128 v[218:221], v143 offset:39936
	global_load_lds_dwordx4 v[248:249], off
	v_lshl_add_u64 v[248:249], s[18:19], 0, v[132:133]
	s_mov_b32 m0, s60
	s_nop 0
	global_load_lds_dwordx4 v[248:249], off
	s_waitcnt vmcnt(8)
	s_waitcnt lgkmcnt(0)
	s_barrier
	s_setprio 1
	v_mfma_f32_16x16x32_bf16 v[128:131], v[144:147], v[176:179], v[128:131]
	v_mfma_f32_16x16x32_bf16 v[124:127], v[152:155], v[176:179], v[124:127]
	v_mfma_f32_16x16x32_bf16 v[116:119], v[144:147], v[184:187], v[116:119]
	v_mfma_f32_16x16x32_bf16 v[108:111], v[152:155], v[184:187], v[108:111]
	v_mfma_f32_16x16x32_bf16 v[100:103], v[144:147], v[192:195], v[100:103]
	v_mfma_f32_16x16x32_bf16 v[92:95], v[152:155], v[192:195], v[92:95]
	v_mfma_f32_16x16x32_bf16 v[84:87], v[144:147], v[214:217], v[84:87]
	v_mfma_f32_16x16x32_bf16 v[76:79], v[152:155], v[214:217], v[76:79]
	v_mfma_f32_16x16x32_bf16 v[128:131], v[148:151], v[180:183], v[128:131]
	v_mfma_f32_16x16x32_bf16 v[124:127], v[156:159], v[180:183], v[124:127]
	v_mfma_f32_16x16x32_bf16 v[116:119], v[148:151], v[188:191], v[116:119]
	v_mfma_f32_16x16x32_bf16 v[108:111], v[156:159], v[188:191], v[108:111]
	v_mfma_f32_16x16x32_bf16 v[100:103], v[148:151], v[210:213], v[100:103]
	v_mfma_f32_16x16x32_bf16 v[92:95], v[156:159], v[210:213], v[92:95]
	v_mfma_f32_16x16x32_bf16 v[84:87], v[148:151], v[218:221], v[84:87]
	v_mfma_f32_16x16x32_bf16 v[76:79], v[156:159], v[218:221], v[76:79]
	s_setprio 0
	s_setprio 1
	v_mfma_f32_16x16x32_bf16 v[120:123], v[160:163], v[176:179], v[120:123]
	v_mfma_f32_16x16x32_bf16 v[112:115], v[168:171], v[176:179], v[112:115]
	v_mfma_f32_16x16x32_bf16 v[104:107], v[160:163], v[184:187], v[104:107]
	v_mfma_f32_16x16x32_bf16 v[96:99], v[168:171], v[184:187], v[96:99]
	v_mfma_f32_16x16x32_bf16 v[88:91], v[160:163], v[192:195], v[88:91]
	v_mfma_f32_16x16x32_bf16 v[80:83], v[168:171], v[192:195], v[80:83]
	v_mfma_f32_16x16x32_bf16 v[72:75], v[160:163], v[214:217], v[72:75]
	v_mfma_f32_16x16x32_bf16 v[68:71], v[168:171], v[214:217], v[68:71]
	v_mfma_f32_16x16x32_bf16 v[120:123], v[164:167], v[180:183], v[120:123]
	v_mfma_f32_16x16x32_bf16 v[112:115], v[172:175], v[180:183], v[112:115]
	v_mfma_f32_16x16x32_bf16 v[104:107], v[164:167], v[188:191], v[104:107]
	v_mfma_f32_16x16x32_bf16 v[96:99], v[172:175], v[188:191], v[96:99]
	v_mfma_f32_16x16x32_bf16 v[88:91], v[164:167], v[210:213], v[88:91]
	v_mfma_f32_16x16x32_bf16 v[80:83], v[172:175], v[210:213], v[80:83]
	v_mfma_f32_16x16x32_bf16 v[72:75], v[164:167], v[218:221], v[72:75]
	v_mfma_f32_16x16x32_bf16 v[68:71], v[172:175], v[218:221], v[68:71]
	s_setprio 0
	s_barrier
; #define PG8_STAGE(bufoff, gbase, voff) do { _Pragma("unroll") for (int _i = 0; _i < 2; ++_i) \
;         __builtin_amdgcn_global_load_lds((const unsigned*)((const char*)(gbase) + (voff)[_i]), (PG8_LAS unsigned*)(lds + (bufoff) + ldsw + _i * 8192), 16, 0, 0); } while (0)
; #define PG8_LDA(dst, b, h) do { _Pragma("unroll") for (int m = 0; m < 4; ++m) _Pragma("unroll") for (int k = 0; k < 2; ++k) dst[m][k] = *(const PG8_LAS bf16x8*)(lds + PG8_SA(b, h) + aoff + m * 2048 + k * 1024); } while (0)
; #define PG8_MMA(ai, bj, At, Bt) do { __builtin_amdgcn_s_setprio(1); _Pragma("unroll") for (int m = 0; m < 4; ++m) _Pragma("unroll") for (int n = 0; n < 2; ++n) _Pragma("unroll") for (int k = 0; k < 2; ++k) \
;         acc[ai][bj][m][n] = __builtin_amdgcn_mfma_f32_16x16x32_bf16(Bt[n][k], At[m][k], acc[ai][bj][m][n], 0, 0, 0); __builtin_amdgcn_s_setprio(0); } while (0)
; #define PG8_WAIT_V(n) asm volatile("s_waitcnt vmcnt(" #n ")" ::: "memory")
; #define PG8_WAIT_L(n) asm volatile("s_waitcnt lgkmcnt(" #n ")" ::: "memory")
; #define PG8_BAR __builtin_amdgcn_s_barrier()
; #define PG8_SCHED __builtin_amdgcn_sched_barrier(0)
; template <class Epi, class Sched, bool ALIGN_EPI = false, bool SP2 = false>
; __device__ __forceinline__ void gemm_phase(PG8_LAS unsigned char* lds, const Gemm g, const Sched& S, const Epi& E) {
;     ...
;             PG8_LDA(At, 1, 1); PG8_STAGE(PG8_SB(1, 0), b3, voffB); PG8_STAGE(PG8_SB(1, 1), b3 + hstepB, voffB); PG8_STAGE(PG8_SA(1, 0), a3, voffA);
;             PG8_WAIT_V(8); PG8_WAIT_L(0); PG8_BAR; PG8_MMA(1, 0, At, B0); PG8_MMA(1, 1, At, B1); PG8_BAR; PG8_SCHED;
;     ...
;         }
;         if constexpr (ALIGN_EPI) { if (wr == 0) PG8_BAR; }
	s_add_i32 s18, s43, vcc_lo
	v_lshl_add_u64 v[222:223], v[222:223], 0, s[48:49]
	s_mov_b32 m0, s18
	ds_read_b128 v[176:179], v143 offset:49152
	ds_read_b128 v[180:183], v143 offset:50176
	ds_read_b128 v[184:187], v143 offset:51200
	ds_read_b128 v[188:191], v143 offset:52224
	ds_read_b128 v[192:195], v143 offset:53248
	ds_read_b128 v[210:213], v143 offset:54272
	ds_read_b128 v[214:217], v143 offset:55296
	ds_read_b128 v[218:221], v143 offset:56320
	global_load_lds_dwordx4 v[222:223], off
	v_lshl_add_u64 v[222:223], v[230:231], 0, s[48:49]
	s_add_i32 m0, s18, 0x2000
	s_add_i32 s18, s22, vcc_lo
	global_load_lds_dwordx4 v[222:223], off
	v_lshl_add_u64 v[222:223], v[232:233], 0, s[48:49]
	s_mov_b32 m0, s18
	s_nop 0
	global_load_lds_dwordx4 v[222:223], off
	v_lshl_add_u64 v[222:223], v[242:243], 0, s[48:49]
	s_add_i32 m0, s18, 0x2000
	s_nop 0
	global_load_lds_dwordx4 v[222:223], off
	v_lshl_add_u64 v[222:223], v[244:245], 0, s[48:49]
	s_mov_b32 m0, s63
	s_nop 0
	global_load_lds_dwordx4 v[222:223], off
	v_lshl_add_u64 v[222:223], v[246:247], 0, s[48:49]
	s_mov_b32 m0, s65
	s_nop 0
	global_load_lds_dwordx4 v[222:223], off
	s_waitcnt vmcnt(8)
	s_waitcnt lgkmcnt(0)
	s_barrier
	s_setprio 1
	v_mfma_f32_16x16x32_bf16 v[60:63], v[144:147], v[176:179], v[60:63]
	v_mfma_f32_16x16x32_bf16 v[56:59], v[152:155], v[176:179], v[56:59]
	v_mfma_f32_16x16x32_bf16 v[48:51], v[144:147], v[184:187], v[48:51]
	v_mfma_f32_16x16x32_bf16 v[40:43], v[152:155], v[184:187], v[40:43]
	v_mfma_f32_16x16x32_bf16 v[32:35], v[144:147], v[192:195], v[32:35]
	v_mfma_f32_16x16x32_bf16 v[24:27], v[152:155], v[192:195], v[24:27]
	v_mfma_f32_16x16x32_bf16 v[16:19], v[144:147], v[214:217], v[16:19]
	v_mfma_f32_16x16x32_bf16 v[8:11], v[152:155], v[214:217], v[8:11]
	v_mfma_f32_16x16x32_bf16 v[60:63], v[148:151], v[180:183], v[60:63]
	v_mfma_f32_16x16x32_bf16 v[56:59], v[156:159], v[180:183], v[56:59]
	v_mfma_f32_16x16x32_bf16 v[48:51], v[148:151], v[188:191], v[48:51]
	v_mfma_f32_16x16x32_bf16 v[40:43], v[156:159], v[188:191], v[40:43]
	v_mfma_f32_16x16x32_bf16 v[32:35], v[148:151], v[210:213], v[32:35]
	v_mfma_f32_16x16x32_bf16 v[24:27], v[156:159], v[210:213], v[24:27]
	v_mfma_f32_16x16x32_bf16 v[16:19], v[148:151], v[218:221], v[16:19]
	v_mfma_f32_16x16x32_bf16 v[8:11], v[156:159], v[218:221], v[8:11]
	s_setprio 0
	s_setprio 1
	v_mfma_f32_16x16x32_bf16 v[52:55], v[160:163], v[176:179], v[52:55]
	v_mfma_f32_16x16x32_bf16 v[44:47], v[168:171], v[176:179], v[44:47]
	v_mfma_f32_16x16x32_bf16 v[36:39], v[160:163], v[184:187], v[36:39]
	v_mfma_f32_16x16x32_bf16 v[28:31], v[168:171], v[184:187], v[28:31]
	v_mfma_f32_16x16x32_bf16 v[20:23], v[160:163], v[192:195], v[20:23]
	v_mfma_f32_16x16x32_bf16 v[12:15], v[168:171], v[192:195], v[12:15]
	v_mfma_f32_16x16x32_bf16 v[4:7], v[160:163], v[214:217], v[4:7]
	v_mfma_f32_16x16x32_bf16 v[0:3], v[168:171], v[214:217], v[0:3]
	v_mfma_f32_16x16x32_bf16 v[52:55], v[164:167], v[180:183], v[52:55]
	v_mfma_f32_16x16x32_bf16 v[44:47], v[172:175], v[180:183], v[44:47]
	v_mfma_f32_16x16x32_bf16 v[36:39], v[164:167], v[188:191], v[36:39]
	v_mfma_f32_16x16x32_bf16 v[28:31], v[172:175], v[188:191], v[28:31]
	v_mfma_f32_16x16x32_bf16 v[20:23], v[164:167], v[210:213], v[20:23]
	v_mfma_f32_16x16x32_bf16 v[12:15], v[172:175], v[210:213], v[12:15]
	v_mfma_f32_16x16x32_bf16 v[4:7], v[164:167], v[218:221], v[4:7]
	v_mfma_f32_16x16x32_bf16 v[0:3], v[172:175], v[218:221], v[0:3]
	s_setprio 0
	s_barrier
	s_cmp_ge_u32 s41, s68
	s_mov_b64 s[18:19], s[20:21]
	s_mov_b32 s30, s41
	s_cbranch_scc0 .LBB0_1035
	s_cmpk_lt_u32 s23, 0x100
	s_cbranch_scc0 .LBB0_1038
	s_barrier

; #define PG8_STAGE(bufoff, gbase, voff) do { _Pragma("unroll") for (int _i = 0; _i < 2; ++_i) \
;         __builtin_amdgcn_global_load_lds((const unsigned*)((const char*)(gbase) + (voff)[_i]), (PG8_LAS unsigned*)(lds + (bufoff) + ldsw + _i * 8192), 16, 0, 0); } while (0)
; #define PG8_LDA(dst, b, h) do { _Pragma("unroll") for (int m = 0; m < 4; ++m) _Pragma("unroll") for (int k = 0; k < 2; ++k) dst[m][k] = *(const PG8_LAS bf16x8*)(lds + PG8_SA(b, h) + aoff + m * 2048 + k * 1024); } while (0)
; #define PG8_LDB(dst, b, h) do { _Pragma("unroll") for (int n = 0; n < 2; ++n) _Pragma("unroll") for (int k = 0; k < 2; ++k) dst[n][k] = *(const PG8_LAS bf16x8*)(lds + PG8_SB(b, h) + boff + n * 2048 + k * 1024); } while (0)
; #define PG8_MMA(ai, bj, At, Bt) do { __builtin_amdgcn_s_setprio(1); _Pragma("unroll") for (int m = 0; m < 4; ++m) _Pragma("unroll") for (int n = 0; n < 2; ++n) _Pragma("unroll") for (int k = 0; k < 2; ++k) \
;         acc[ai][bj][m][n] = __builtin_amdgcn_mfma_f32_16x16x32_bf16(Bt[n][k], At[m][k], acc[ai][bj][m][n], 0, 0, 0); __builtin_amdgcn_s_setprio(0); } while (0)
; #define PG8_WAIT_V(n) asm volatile("s_waitcnt vmcnt(" #n ")" ::: "memory")
; #define PG8_WAIT_L(n) asm volatile("s_waitcnt lgkmcnt(" #n ")" ::: "memory")
; #define PG8_BAR __builtin_amdgcn_s_barrier()
; #define PG8_SCHED __builtin_amdgcn_sched_barrier(0)
; template <class Epi, class Sched, bool ALIGN_EPI = false, bool SP2 = false>
; __device__ __forceinline__ void gemm_phase(PG8_LAS unsigned char* lds, const Gemm g, const Sched& S, const Epi& E) {
;     ...
;             const bool last = (t == nt - 2);
;             const char* a1 = cA + (size_t)(t + 1) * kstep;
;             const char* a2 = last ? nA : cA + (size_t)(t + 2) * kstep; const char* b2 = last ? nB : cB + (size_t)(t + 2) * kstep;
;             const char* a3 = a2 + kstep; const char* b3 = b2 + kstep;
;             if (last && has_next) S.a_ready(nxt);
;             if constexpr (SP2) {
;             PG8_LDB(B0, 0, 0); PG8_LDB(B1, 0, 1); PG8_SCHED; PG8_LDA(At, 0, 0); PG8_STAGE(PG8_SA(1, 1), a1 + hstepA, voffA);
;             PG8_WAIT_V(8); PG8_WAIT_L(0); PG8_BAR; PG8_MMA(0, 0, At, B0); PG8_MMA(0, 1, At, B1); PG8_BAR; PG8_SCHED;
;             PG8_LDA(At, 0, 1); PG8_STAGE(PG8_SB(0, 0), b2, voffB); PG8_STAGE(PG8_SB(0, 1), b2 + hstepB, voffB); PG8_STAGE(PG8_SA(0, 0), a2, voffA);
.LBB0_1183:
	s_add_u32 s8, s6, 0xf39c0080
	s_addc_u32 s9, s7, -1
	s_cmp_lg_u32 s43, 12
	s_cselect_b32 s8, s8, 0
	s_cselect_b32 s9, s9, 0
	s_add_u32 s10, s4, s8
	s_addc_u32 s11, s5, s9
	s_add_i32 s41, 0, 0x10000
	s_add_u32 s8, s0, s8
	v_add_u32_e32 v141, s41, v139
	s_addc_u32 s9, s1, s9
	s_add_i32 s60, 0, 0x14000
	ds_read_b128 v[142:145], v141
	ds_read_b128 v[146:149], v141 offset:1024
	ds_read_b128 v[150:153], v141 offset:2048
	ds_read_b128 v[154:157], v141 offset:3072
	v_add_u32_e32 v141, s60, v139
	ds_read_b128 v[158:161], v141
	ds_read_b128 v[162:165], v141 offset:1024
	ds_read_b128 v[166:169], v141 offset:2048
	ds_read_b128 v[170:173], v141 offset:3072
	v_lshl_add_u64 v[222:223], v[132:133], 0, s[6:7]
	s_add_i32 m0, s23, 0xc000
	ds_read_b128 v[174:177], v140
	ds_read_b128 v[180:183], v140 offset:1024
	ds_read_b128 v[184:187], v140 offset:2048
	ds_read_b128 v[188:191], v140 offset:3072
	ds_read_b128 v[192:195], v140 offset:4096
	ds_read_b128 v[210:213], v140 offset:5120
	ds_read_b128 v[214:217], v140 offset:6144
	ds_read_b128 v[218:221], v140 offset:7168
	global_load_lds_dwordx4 v[222:223], off
	v_lshl_add_u64 v[222:223], v[134:135], 0, s[6:7]
	s_add_i32 m0, s23, 0xe000
	s_nop 0
	global_load_lds_dwordx4 v[222:223], off
	s_waitcnt vmcnt(8)
	s_waitcnt lgkmcnt(0)
	s_barrier
	s_setprio 1
	v_mfma_f32_16x16x32_bf16 v[126:129], v[142:145], v[174:177], v[126:129]
	v_mfma_f32_16x16x32_bf16 v[122:125], v[150:153], v[174:177], v[122:125]
	v_mfma_f32_16x16x32_bf16 v[110:113], v[142:145], v[184:187], v[110:113]
	v_mfma_f32_16x16x32_bf16 v[106:109], v[150:153], v[184:187], v[106:109]
	v_mfma_f32_16x16x32_bf16 v[94:97], v[142:145], v[192:195], v[94:97]
	v_mfma_f32_16x16x32_bf16 v[90:93], v[150:153], v[192:195], v[90:93]
	v_mfma_f32_16x16x32_bf16 v[78:81], v[142:145], v[214:217], v[78:81]
	v_mfma_f32_16x16x32_bf16 v[74:77], v[150:153], v[214:217], v[74:77]
	v_mfma_f32_16x16x32_bf16 v[126:129], v[146:149], v[180:183], v[126:129]
	v_mfma_f32_16x16x32_bf16 v[122:125], v[154:157], v[180:183], v[122:125]
	v_mfma_f32_16x16x32_bf16 v[110:113], v[146:149], v[188:191], v[110:113]
	v_mfma_f32_16x16x32_bf16 v[106:109], v[154:157], v[188:191], v[106:109]
	v_mfma_f32_16x16x32_bf16 v[94:97], v[146:149], v[210:213], v[94:97]
	v_mfma_f32_16x16x32_bf16 v[90:93], v[154:157], v[210:213], v[90:93]
	v_mfma_f32_16x16x32_bf16 v[78:81], v[146:149], v[218:221], v[78:81]
	v_mfma_f32_16x16x32_bf16 v[74:77], v[154:157], v[218:221], v[74:77]
	s_setprio 0
	s_setprio 1
	v_mfma_f32_16x16x32_bf16 v[118:121], v[158:161], v[174:177], v[118:121]
	v_mfma_f32_16x16x32_bf16 v[114:117], v[166:169], v[174:177], v[114:117]
	v_mfma_f32_16x16x32_bf16 v[102:105], v[158:161], v[184:187], v[102:105]
	v_mfma_f32_16x16x32_bf16 v[98:101], v[166:169], v[184:187], v[98:101]
	v_mfma_f32_16x16x32_bf16 v[86:89], v[158:161], v[192:195], v[86:89]
	v_mfma_f32_16x16x32_bf16 v[82:85], v[166:169], v[192:195], v[82:85]
	v_mfma_f32_16x16x32_bf16 v[70:73], v[158:161], v[214:217], v[70:73]
	v_mfma_f32_16x16x32_bf16 v[66:69], v[166:169], v[214:217], v[66:69]
	v_mfma_f32_16x16x32_bf16 v[118:121], v[162:165], v[180:183], v[118:121]
	v_mfma_f32_16x16x32_bf16 v[114:117], v[170:173], v[180:183], v[114:117]
	v_mfma_f32_16x16x32_bf16 v[102:105], v[162:165], v[188:191], v[102:105]
	v_mfma_f32_16x16x32_bf16 v[98:101], v[170:173], v[188:191], v[98:101]
	v_mfma_f32_16x16x32_bf16 v[86:89], v[162:165], v[210:213], v[86:89]
	v_mfma_f32_16x16x32_bf16 v[82:85], v[170:173], v[210:213], v[82:85]
	v_mfma_f32_16x16x32_bf16 v[70:73], v[162:165], v[218:221], v[70:73]
	v_mfma_f32_16x16x32_bf16 v[66:69], v[170:173], v[218:221], v[66:69]
	s_setprio 0
	s_barrier
	s_add_i32 s41, s41, s22
	v_lshl_add_u64 v[222:223], s[8:9], 0, v[64:65]
	s_mov_b32 m0, s41
	ds_read_b128 v[174:177], v140 offset:16384
	ds_read_b128 v[180:183], v140 offset:17408
	ds_read_b128 v[184:187], v140 offset:18432
	ds_read_b128 v[188:191], v140 offset:19456
	ds_read_b128 v[192:195], v140 offset:20480
	ds_read_b128 v[210:213], v140 offset:21504
	ds_read_b128 v[214:217], v140 offset:22528
	ds_read_b128 v[218:221], v140 offset:23552
	global_load_lds_dwordx4 v[222:223], off
	s_add_i32 m0, s41, 0x2000
	s_add_u32 s44, s8, 0x40000
	v_lshl_add_u64 v[230:231], s[8:9], 0, v[130:131]
	s_addc_u32 s45, s9, 0
	s_add_i32 s41, s60, s22
	global_load_lds_dwordx4 v[230:231], off
	v_lshl_add_u64 v[232:233], s[44:45], 0, v[64:65]
	s_mov_b32 m0, s41
	v_lshl_add_u64 v[242:243], s[10:11], 0, v[130:131]
	global_load_lds_dwordx4 v[232:233], off
	v_lshl_add_u64 v[232:233], s[44:45], 0, v[130:131]
	s_add_i32 m0, s41, 0x2000
	s_nop 0
	global_load_lds_dwordx4 v[232:233], off
	v_lshl_add_u64 v[232:233], s[10:11], 0, v[64:65]
	s_mov_b32 m0, s23
	s_nop 0
	global_load_lds_dwordx4 v[232:233], off
	s_mov_b32 m0, s25
	s_nop 0
	global_load_lds_dwordx4 v[242:243], off
	s_waitcnt vmcnt(8)
	s_waitcnt lgkmcnt(0)
	s_barrier
; #define PG8_STAGE(bufoff, gbase, voff) do { _Pragma("unroll") for (int _i = 0; _i < 2; ++_i) \
;         __builtin_amdgcn_global_load_lds((const unsigned*)((const char*)(gbase) + (voff)[_i]), (PG8_LAS unsigned*)(lds + (bufoff) + ldsw + _i * 8192), 16, 0, 0); } while (0)
; #define PG8_LDA(dst, b, h) do { _Pragma("unroll") for (int m = 0; m < 4; ++m) _Pragma("unroll") for (int k = 0; k < 2; ++k) dst[m][k] = *(const PG8_LAS bf16x8*)(lds + PG8_SA(b, h) + aoff + m * 2048 + k * 1024); } while (0)
; #define PG8_LDB(dst, b, h) do { _Pragma("unroll") for (int n = 0; n < 2; ++n) _Pragma("unroll") for (int k = 0; k < 2; ++k) dst[n][k] = *(const PG8_LAS bf16x8*)(lds + PG8_SB(b, h) + boff + n * 2048 + k * 1024); } while (0)
; #define PG8_MMA(ai, bj, At, Bt) do { __builtin_amdgcn_s_setprio(1); _Pragma("unroll") for (int m = 0; m < 4; ++m) _Pragma("unroll") for (int n = 0; n < 2; ++n) _Pragma("unroll") for (int k = 0; k < 2; ++k) \
;         acc[ai][bj][m][n] = __builtin_amdgcn_mfma_f32_16x16x32_bf16(Bt[n][k], At[m][k], acc[ai][bj][m][n], 0, 0, 0); __builtin_amdgcn_s_setprio(0); } while (0)
; #define PG8_WAIT_V(n) asm volatile("s_waitcnt vmcnt(" #n ")" ::: "memory")
; #define PG8_WAIT_L(n) asm volatile("s_waitcnt lgkmcnt(" #n ")" ::: "memory")
; #define PG8_BAR __builtin_amdgcn_s_barrier()
; #define PG8_SCHED __builtin_amdgcn_sched_barrier(0)
; template <class Epi, class Sched, bool ALIGN_EPI = false, bool SP2 = false>
; __device__ __forceinline__ void gemm_phase(PG8_LAS unsigned char* lds, const Gemm g, const Sched& S, const Epi& E) {
;     ...
;             PG8_WAIT_V(8); PG8_WAIT_L(0); PG8_BAR; PG8_MMA(1, 0, At, B0); PG8_MMA(1, 1, At, B1); PG8_BAR; PG8_SCHED;
;             PG8_LDB(B0, 1, 0); PG8_LDB(B1, 1, 1); PG8_SCHED; PG8_LDA(At, 1, 0); PG8_STAGE(PG8_SA(0, 1), a2 + hstepA, voffA);
;             PG8_WAIT_V(8); PG8_WAIT_L(0); PG8_BAR; PG8_MMA(0, 0, At, B0); PG8_MMA(0, 1, At, B1); PG8_BAR; PG8_SCHED;
	s_setprio 1
	v_mfma_f32_16x16x32_bf16 v[60:63], v[142:145], v[174:177], v[60:63]
	v_mfma_f32_16x16x32_bf16 v[56:59], v[150:153], v[174:177], v[56:59]
	v_mfma_f32_16x16x32_bf16 v[44:47], v[142:145], v[184:187], v[44:47]
	v_mfma_f32_16x16x32_bf16 v[40:43], v[150:153], v[184:187], v[40:43]
	v_mfma_f32_16x16x32_bf16 v[28:31], v[142:145], v[192:195], v[28:31]
	v_mfma_f32_16x16x32_bf16 v[24:27], v[150:153], v[192:195], v[24:27]
	v_mfma_f32_16x16x32_bf16 v[12:15], v[142:145], v[214:217], v[12:15]
	v_mfma_f32_16x16x32_bf16 v[8:11], v[150:153], v[214:217], v[8:11]
	v_mfma_f32_16x16x32_bf16 v[60:63], v[146:149], v[180:183], v[60:63]
	v_mfma_f32_16x16x32_bf16 v[56:59], v[154:157], v[180:183], v[56:59]
	v_mfma_f32_16x16x32_bf16 v[44:47], v[146:149], v[188:191], v[44:47]
	v_mfma_f32_16x16x32_bf16 v[40:43], v[154:157], v[188:191], v[40:43]
	v_mfma_f32_16x16x32_bf16 v[28:31], v[146:149], v[210:213], v[28:31]
	v_mfma_f32_16x16x32_bf16 v[24:27], v[154:157], v[210:213], v[24:27]
	v_mfma_f32_16x16x32_bf16 v[12:15], v[146:149], v[218:221], v[12:15]
	v_mfma_f32_16x16x32_bf16 v[8:11], v[154:157], v[218:221], v[8:11]
	s_setprio 0
	s_setprio 1
	v_mfma_f32_16x16x32_bf16 v[52:55], v[158:161], v[174:177], v[52:55]
	v_mfma_f32_16x16x32_bf16 v[48:51], v[166:169], v[174:177], v[48:51]
	v_mfma_f32_16x16x32_bf16 v[36:39], v[158:161], v[184:187], v[36:39]
	v_mfma_f32_16x16x32_bf16 v[32:35], v[166:169], v[184:187], v[32:35]
	v_mfma_f32_16x16x32_bf16 v[20:23], v[158:161], v[192:195], v[20:23]
	v_mfma_f32_16x16x32_bf16 v[16:19], v[166:169], v[192:195], v[16:19]
	v_mfma_f32_16x16x32_bf16 v[4:7], v[158:161], v[214:217], v[4:7]
	v_mfma_f32_16x16x32_bf16 v[0:3], v[166:169], v[214:217], v[0:3]
	v_mfma_f32_16x16x32_bf16 v[52:55], v[162:165], v[180:183], v[52:55]
	v_mfma_f32_16x16x32_bf16 v[48:51], v[170:173], v[180:183], v[48:51]
	v_mfma_f32_16x16x32_bf16 v[36:39], v[162:165], v[188:191], v[36:39]
	v_mfma_f32_16x16x32_bf16 v[32:35], v[170:173], v[188:191], v[32:35]
	v_mfma_f32_16x16x32_bf16 v[20:23], v[162:165], v[210:213], v[20:23]
	v_mfma_f32_16x16x32_bf16 v[16:19], v[170:173], v[210:213], v[16:19]
	v_mfma_f32_16x16x32_bf16 v[4:7], v[162:165], v[218:221], v[4:7]
	v_mfma_f32_16x16x32_bf16 v[0:3], v[170:173], v[218:221], v[0:3]
	s_setprio 0
	s_barrier
	s_add_i32 s41, 0, 0x18000
	v_add_u32_e32 v141, s41, v139
	s_add_i32 s44, 0, 0x1c000
	ds_read_b128 v[142:145], v141
	ds_read_b128 v[146:149], v141 offset:1024
	ds_read_b128 v[150:153], v141 offset:2048
	ds_read_b128 v[154:157], v141 offset:3072
	v_add_u32_e32 v141, s44, v139
	ds_read_b128 v[158:161], v141
	ds_read_b128 v[162:165], v141 offset:1024
	ds_read_b128 v[166:169], v141 offset:2048
	ds_read_b128 v[170:173], v141 offset:3072
	s_add_u32 s10, s10, 0x40000
	s_addc_u32 s11, s11, 0
	s_mov_b32 m0, s31
	v_lshl_add_u64 v[244:245], s[10:11], 0, v[64:65]
	ds_read_b128 v[174:177], v140 offset:32768
	ds_read_b128 v[180:183], v140 offset:33792
	ds_read_b128 v[184:187], v140 offset:34816
	ds_read_b128 v[188:191], v140 offset:35840
	ds_read_b128 v[192:195], v140 offset:36864
	ds_read_b128 v[210:213], v140 offset:37888
	ds_read_b128 v[214:217], v140 offset:38912
	ds_read_b128 v[218:221], v140 offset:39936
	global_load_lds_dwordx4 v[244:245], off
	v_lshl_add_u64 v[244:245], s[10:11], 0, v[130:131]
	s_mov_b32 m0, s34
	s_nop 0
	global_load_lds_dwordx4 v[244:245], off
	s_waitcnt vmcnt(8)
	s_waitcnt lgkmcnt(0)
	s_barrier
	s_setprio 1
	v_mfma_f32_16x16x32_bf16 v[126:129], v[142:145], v[174:177], v[126:129]
	v_mfma_f32_16x16x32_bf16 v[122:125], v[150:153], v[174:177], v[122:125]
	v_mfma_f32_16x16x32_bf16 v[110:113], v[142:145], v[184:187], v[110:113]
	v_mfma_f32_16x16x32_bf16 v[106:109], v[150:153], v[184:187], v[106:109]
	v_mfma_f32_16x16x32_bf16 v[94:97], v[142:145], v[192:195], v[94:97]
	v_mfma_f32_16x16x32_bf16 v[90:93], v[150:153], v[192:195], v[90:93]
	v_mfma_f32_16x16x32_bf16 v[78:81], v[142:145], v[214:217], v[78:81]
	v_mfma_f32_16x16x32_bf16 v[74:77], v[150:153], v[214:217], v[74:77]
	v_mfma_f32_16x16x32_bf16 v[126:129], v[146:149], v[180:183], v[126:129]
	v_mfma_f32_16x16x32_bf16 v[122:125], v[154:157], v[180:183], v[122:125]
	v_mfma_f32_16x16x32_bf16 v[110:113], v[146:149], v[188:191], v[110:113]
	v_mfma_f32_16x16x32_bf16 v[106:109], v[154:157], v[188:191], v[106:109]
	v_mfma_f32_16x16x32_bf16 v[94:97], v[146:149], v[210:213], v[94:97]
	v_mfma_f32_16x16x32_bf16 v[90:93], v[154:157], v[210:213], v[90:93]
	v_mfma_f32_16x16x32_bf16 v[78:81], v[146:149], v[218:221], v[78:81]
	v_mfma_f32_16x16x32_bf16 v[74:77], v[154:157], v[218:221], v[74:77]
	s_setprio 0
	s_setprio 1
	v_mfma_f32_16x16x32_bf16 v[118:121], v[158:161], v[174:177], v[118:121]
	v_mfma_f32_16x16x32_bf16 v[114:117], v[166:169], v[174:177], v[114:117]
	v_mfma_f32_16x16x32_bf16 v[102:105], v[158:161], v[184:187], v[102:105]
	v_mfma_f32_16x16x32_bf16 v[98:101], v[166:169], v[184:187], v[98:101]
	v_mfma_f32_16x16x32_bf16 v[86:89], v[158:161], v[192:195], v[86:89]
	v_mfma_f32_16x16x32_bf16 v[82:85], v[166:169], v[192:195], v[82:85]
	v_mfma_f32_16x16x32_bf16 v[70:73], v[158:161], v[214:217], v[70:73]
	v_mfma_f32_16x16x32_bf16 v[66:69], v[166:169], v[214:217], v[66:69]
	v_mfma_f32_16x16x32_bf16 v[118:121], v[162:165], v[180:183], v[118:121]
	v_mfma_f32_16x16x32_bf16 v[114:117], v[170:173], v[180:183], v[114:117]
	v_mfma_f32_16x16x32_bf16 v[102:105], v[162:165], v[188:191], v[102:105]
	v_mfma_f32_16x16x32_bf16 v[98:101], v[170:173], v[188:191], v[98:101]
	v_mfma_f32_16x16x32_bf16 v[86:89], v[162:165], v[210:213], v[86:89]
	v_mfma_f32_16x16x32_bf16 v[82:85], v[170:173], v[210:213], v[82:85]
	v_mfma_f32_16x16x32_bf16 v[70:73], v[162:165], v[218:221], v[70:73]
	v_mfma_f32_16x16x32_bf16 v[66:69], v[170:173], v[218:221], v[66:69]
	s_setprio 0
	s_barrier
; #define PG8_STAGE(bufoff, gbase, voff) do { _Pragma("unroll") for (int _i = 0; _i < 2; ++_i) \
;         __builtin_amdgcn_global_load_lds((const unsigned*)((const char*)(gbase) + (voff)[_i]), (PG8_LAS unsigned*)(lds + (bufoff) + ldsw + _i * 8192), 16, 0, 0); } while (0)
; #define PG8_LDA(dst, b, h) do { _Pragma("unroll") for (int m = 0; m < 4; ++m) _Pragma("unroll") for (int k = 0; k < 2; ++k) dst[m][k] = *(const PG8_LAS bf16x8*)(lds + PG8_SA(b, h) + aoff + m * 2048 + k * 1024); } while (0)
; #define PG8_MMA(ai, bj, At, Bt) do { __builtin_amdgcn_s_setprio(1); _Pragma("unroll") for (int m = 0; m < 4; ++m) _Pragma("unroll") for (int n = 0; n < 2; ++n) _Pragma("unroll") for (int k = 0; k < 2; ++k) \
;         acc[ai][bj][m][n] = __builtin_amdgcn_mfma_f32_16x16x32_bf16(Bt[n][k], At[m][k], acc[ai][bj][m][n], 0, 0, 0); __builtin_amdgcn_s_setprio(0); } while (0)
; #define PG8_WAIT_V(n) asm volatile("s_waitcnt vmcnt(" #n ")" ::: "memory")
; #define PG8_WAIT_L(n) asm volatile("s_waitcnt lgkmcnt(" #n ")" ::: "memory")
; #define PG8_BAR __builtin_amdgcn_s_barrier()
; #define PG8_SCHED __builtin_amdgcn_sched_barrier(0)
; template <class Epi, class Sched, bool ALIGN_EPI = false, bool SP2 = false>
; __device__ __forceinline__ void gemm_phase(PG8_LAS unsigned char* lds, const Gemm g, const Sched& S, const Epi& E) {
;     ...
;             PG8_LDA(At, 1, 1); PG8_STAGE(PG8_SB(1, 0), b3, voffB); PG8_STAGE(PG8_SB(1, 1), b3 + hstepB, voffB); PG8_STAGE(PG8_SA(1, 0), a3, voffA);
;             PG8_WAIT_V(8); PG8_WAIT_L(0); PG8_BAR; PG8_MMA(1, 0, At, B0); PG8_MMA(1, 1, At, B1); PG8_BAR; PG8_SCHED;
;     ...
;     PG8_WAIT_V(0);
;     if constexpr (!ALIGN_EPI) { if (wr == 0) PG8_BAR; }
	s_add_i32 s10, s41, s22
	v_lshl_add_u64 v[222:223], v[222:223], 0, s[48:49]
	s_mov_b32 m0, s10
	ds_read_b128 v[174:177], v140 offset:49152
	ds_read_b128 v[180:183], v140 offset:50176
	ds_read_b128 v[184:187], v140 offset:51200
	ds_read_b128 v[188:191], v140 offset:52224
	ds_read_b128 v[192:195], v140 offset:53248
	ds_read_b128 v[210:213], v140 offset:54272
	ds_read_b128 v[214:217], v140 offset:55296
	ds_read_b128 v[218:221], v140 offset:56320
	global_load_lds_dwordx4 v[222:223], off
	s_add_i32 m0, s10, 0x2000
	s_add_u32 s8, s8, 0x40080
	v_lshl_add_u64 v[222:223], v[230:231], 0, s[48:49]
	s_addc_u32 s9, s9, 0
	s_add_i32 s10, s44, s22
	global_load_lds_dwordx4 v[222:223], off
	v_lshl_add_u64 v[222:223], s[8:9], 0, v[64:65]
	s_mov_b32 m0, s10
	s_nop 0
	global_load_lds_dwordx4 v[222:223], off
	v_lshl_add_u64 v[222:223], s[8:9], 0, v[130:131]
	s_add_i32 m0, s10, 0x2000
	s_nop 0
	global_load_lds_dwordx4 v[222:223], off
	v_lshl_add_u64 v[222:223], v[232:233], 0, s[48:49]
	s_mov_b32 m0, s38
	s_nop 0
	global_load_lds_dwordx4 v[222:223], off
	v_lshl_add_u64 v[222:223], v[242:243], 0, s[48:49]
	s_mov_b32 m0, s39
	s_nop 0
	global_load_lds_dwordx4 v[222:223], off
	s_waitcnt vmcnt(8)
	s_waitcnt lgkmcnt(0)
	s_barrier
	s_setprio 1
	v_mfma_f32_16x16x32_bf16 v[60:63], v[142:145], v[174:177], v[60:63]
	v_mfma_f32_16x16x32_bf16 v[56:59], v[150:153], v[174:177], v[56:59]
	v_mfma_f32_16x16x32_bf16 v[44:47], v[142:145], v[184:187], v[44:47]
	v_mfma_f32_16x16x32_bf16 v[40:43], v[150:153], v[184:187], v[40:43]
	v_mfma_f32_16x16x32_bf16 v[28:31], v[142:145], v[192:195], v[28:31]
	v_mfma_f32_16x16x32_bf16 v[24:27], v[150:153], v[192:195], v[24:27]
	v_mfma_f32_16x16x32_bf16 v[12:15], v[142:145], v[214:217], v[12:15]
	v_mfma_f32_16x16x32_bf16 v[8:11], v[150:153], v[214:217], v[8:11]
	v_mfma_f32_16x16x32_bf16 v[60:63], v[146:149], v[180:183], v[60:63]
	v_mfma_f32_16x16x32_bf16 v[56:59], v[154:157], v[180:183], v[56:59]
	v_mfma_f32_16x16x32_bf16 v[44:47], v[146:149], v[188:191], v[44:47]
	v_mfma_f32_16x16x32_bf16 v[40:43], v[154:157], v[188:191], v[40:43]
	v_mfma_f32_16x16x32_bf16 v[28:31], v[146:149], v[210:213], v[28:31]
	v_mfma_f32_16x16x32_bf16 v[24:27], v[154:157], v[210:213], v[24:27]
	v_mfma_f32_16x16x32_bf16 v[12:15], v[146:149], v[218:221], v[12:15]
	v_mfma_f32_16x16x32_bf16 v[8:11], v[154:157], v[218:221], v[8:11]
	s_setprio 0
	s_setprio 1
	v_mfma_f32_16x16x32_bf16 v[52:55], v[158:161], v[174:177], v[52:55]
	v_mfma_f32_16x16x32_bf16 v[48:51], v[166:169], v[174:177], v[48:51]
	v_mfma_f32_16x16x32_bf16 v[36:39], v[158:161], v[184:187], v[36:39]
	v_mfma_f32_16x16x32_bf16 v[32:35], v[166:169], v[184:187], v[32:35]
	v_mfma_f32_16x16x32_bf16 v[20:23], v[158:161], v[192:195], v[20:23]
	v_mfma_f32_16x16x32_bf16 v[16:19], v[166:169], v[192:195], v[16:19]
	v_mfma_f32_16x16x32_bf16 v[4:7], v[158:161], v[214:217], v[4:7]
	v_mfma_f32_16x16x32_bf16 v[0:3], v[166:169], v[214:217], v[0:3]
	v_mfma_f32_16x16x32_bf16 v[52:55], v[162:165], v[180:183], v[52:55]
	v_mfma_f32_16x16x32_bf16 v[48:51], v[170:173], v[180:183], v[48:51]
	v_mfma_f32_16x16x32_bf16 v[36:39], v[162:165], v[188:191], v[36:39]
	v_mfma_f32_16x16x32_bf16 v[32:35], v[170:173], v[188:191], v[32:35]
	v_mfma_f32_16x16x32_bf16 v[20:23], v[162:165], v[210:213], v[20:23]
	v_mfma_f32_16x16x32_bf16 v[16:19], v[170:173], v[210:213], v[16:19]
	v_mfma_f32_16x16x32_bf16 v[4:7], v[162:165], v[218:221], v[4:7]
	v_mfma_f32_16x16x32_bf16 v[0:3], v[170:173], v[218:221], v[0:3]
	s_setprio 0
	s_barrier
	s_add_i32 s43, s43, 2
	s_add_u32 s6, s6, 0x100
	s_addc_u32 s7, s7, 0
	s_cmp_lt_u32 s43, 14
	s_cbranch_scc1 .LBB0_1183
	s_waitcnt vmcnt(0)
	s_cmpk_gt_u32 s21, 0xff
	s_cbranch_scc1 .LBB0_1186
	s_barrier

; #define PG8_STAGE(bufoff, gbase, voff) do { _Pragma("unroll") for (int _i = 0; _i < 2; ++_i) \
;         __builtin_amdgcn_global_load_lds((const unsigned*)((const char*)(gbase) + (voff)[_i]), (PG8_LAS unsigned*)(lds + (bufoff) + ldsw + _i * 8192), 16, 0, 0); } while (0)
; #define PG8_LDA(dst, b, h) do { _Pragma("unroll") for (int m = 0; m < 4; ++m) _Pragma("unroll") for (int k = 0; k < 2; ++k) dst[m][k] = *(const PG8_LAS bf16x8*)(lds + PG8_SA(b, h) + aoff + m * 2048 + k * 1024); } while (0)
; #define PG8_LDB(dst, b, h) do { _Pragma("unroll") for (int n = 0; n < 2; ++n) _Pragma("unroll") for (int k = 0; k < 2; ++k) dst[n][k] = *(const PG8_LAS bf16x8*)(lds + PG8_SB(b, h) + boff + n * 2048 + k * 1024); } while (0)
; #define PG8_MMA(ai, bj, At, Bt) do { __builtin_amdgcn_s_setprio(1); _Pragma("unroll") for (int m = 0; m < 4; ++m) _Pragma("unroll") for (int n = 0; n < 2; ++n) _Pragma("unroll") for (int k = 0; k < 2; ++k) \
;         acc[ai][bj][m][n] = __builtin_amdgcn_mfma_f32_16x16x32_bf16(Bt[n][k], At[m][k], acc[ai][bj][m][n], 0, 0, 0); __builtin_amdgcn_s_setprio(0); } while (0)
; #define PG8_WAIT_V(n) asm volatile("s_waitcnt vmcnt(" #n ")" ::: "memory")
; #define PG8_WAIT_L(n) asm volatile("s_waitcnt lgkmcnt(" #n ")" ::: "memory")
; #define PG8_BAR __builtin_amdgcn_s_barrier()
; #define PG8_SCHED __builtin_amdgcn_sched_barrier(0)
; template <class Epi, class Sched, bool ALIGN_EPI = false, bool SP2 = false>
; __device__ __forceinline__ void gemm_phase(PG8_LAS unsigned char* lds, const Gemm g, const Sched& S, const Epi& E) {
;     ...
;             const bool last = (t == nt - 2);
;             const char* a1 = cA + (size_t)(t + 1) * kstep;
;             const char* a2 = last ? nA : cA + (size_t)(t + 2) * kstep; const char* b2 = last ? nB : cB + (size_t)(t + 2) * kstep;
;             const char* a3 = a2 + kstep; const char* b3 = b2 + kstep;
;             if (last && has_next) S.a_ready(nxt);
;             if constexpr (SP2) {
;             PG8_LDB(B0, 0, 0); PG8_LDB(B1, 0, 1); PG8_SCHED; PG8_LDA(At, 0, 0); PG8_STAGE(PG8_SA(1, 1), a1 + hstepA, voffA);
;             PG8_WAIT_V(8); PG8_WAIT_L(0); PG8_BAR; PG8_MMA(0, 0, At, B0); PG8_MMA(0, 1, At, B1); PG8_BAR; PG8_SCHED;
;             PG8_LDA(At, 0, 1); PG8_STAGE(PG8_SB(0, 0), b2, voffB); PG8_STAGE(PG8_SB(0, 1), b2 + hstepB, voffB); PG8_STAGE(PG8_SA(0, 0), a2, voffA);
.LBB0_1264:
	s_add_u32 s30, s20, 0xfb9c0080
	s_addc_u32 s31, s21, -1
	s_cmp_lg_u32 s91, 12
	s_cselect_b32 s30, s30, 0
	s_cselect_b32 s31, s31, 0
	s_add_u32 s38, s16, s30
	s_addc_u32 s39, s17, s31
	s_add_i32 s72, 0, 0x10000
	s_add_u32 s30, s18, s30
	v_add_u32_e32 v147, s72, v140
	s_addc_u32 s31, s19, s31
	s_add_i32 s73, 0, 0x14000
	ds_read_b128 v[142:145], v147
	ds_read_b128 v[148:151], v147 offset:1024
	ds_read_b128 v[152:155], v147 offset:2048
	ds_read_b128 v[156:159], v147 offset:3072
	v_add_u32_e32 v147, s73, v140
	ds_read_b128 v[160:163], v147
	ds_read_b128 v[166:169], v147 offset:1024
	ds_read_b128 v[170:173], v147 offset:2048
	ds_read_b128 v[174:177], v147 offset:3072
	v_lshl_add_u64 v[194:195], v[136:137], 0, s[20:21]
	s_add_i32 m0, s84, 0xc000
	ds_read_b128 v[178:181], v141
	ds_read_b128 v[182:185], v141 offset:1024
	ds_read_b128 v[186:189], v141 offset:2048
	ds_read_b128 v[190:193], v141 offset:3072
	ds_read_b128 v[210:213], v141 offset:4096
	ds_read_b128 v[214:217], v141 offset:5120
	ds_read_b128 v[218:221], v141 offset:6144
	ds_read_b128 v[242:245], v141 offset:7168
	global_load_lds_dwordx4 v[194:195], off
	v_lshl_add_u64 v[194:195], v[138:139], 0, s[20:21]
	s_add_i32 m0, s84, 0xe000
	s_nop 0
	global_load_lds_dwordx4 v[194:195], off
	s_waitcnt vmcnt(8)
	s_waitcnt lgkmcnt(0)
	s_barrier
	s_setprio 1
	v_mfma_f32_16x16x32_bf16 v[126:129], v[142:145], v[178:181], v[126:129]
	v_mfma_f32_16x16x32_bf16 v[122:125], v[152:155], v[178:181], v[122:125]
	v_mfma_f32_16x16x32_bf16 v[114:117], v[142:145], v[186:189], v[114:117]
	v_mfma_f32_16x16x32_bf16 v[106:109], v[152:155], v[186:189], v[106:109]
	v_mfma_f32_16x16x32_bf16 v[98:101], v[142:145], v[210:213], v[98:101]
	v_mfma_f32_16x16x32_bf16 v[90:93], v[152:155], v[210:213], v[90:93]
	v_mfma_f32_16x16x32_bf16 v[82:85], v[142:145], v[218:221], v[82:85]
	v_mfma_f32_16x16x32_bf16 v[74:77], v[152:155], v[218:221], v[74:77]
	v_mfma_f32_16x16x32_bf16 v[126:129], v[148:151], v[182:185], v[126:129]
	v_mfma_f32_16x16x32_bf16 v[122:125], v[156:159], v[182:185], v[122:125]
	v_mfma_f32_16x16x32_bf16 v[114:117], v[148:151], v[190:193], v[114:117]
	v_mfma_f32_16x16x32_bf16 v[106:109], v[156:159], v[190:193], v[106:109]
	v_mfma_f32_16x16x32_bf16 v[98:101], v[148:151], v[214:217], v[98:101]
	v_mfma_f32_16x16x32_bf16 v[90:93], v[156:159], v[214:217], v[90:93]
	v_mfma_f32_16x16x32_bf16 v[82:85], v[148:151], v[242:245], v[82:85]
	v_mfma_f32_16x16x32_bf16 v[74:77], v[156:159], v[242:245], v[74:77]
	s_setprio 0
	s_setprio 1
	v_mfma_f32_16x16x32_bf16 v[118:121], v[160:163], v[178:181], v[118:121]
	v_mfma_f32_16x16x32_bf16 v[110:113], v[170:173], v[178:181], v[110:113]
	v_mfma_f32_16x16x32_bf16 v[102:105], v[160:163], v[186:189], v[102:105]
	v_mfma_f32_16x16x32_bf16 v[94:97], v[170:173], v[186:189], v[94:97]
	v_mfma_f32_16x16x32_bf16 v[86:89], v[160:163], v[210:213], v[86:89]
	v_mfma_f32_16x16x32_bf16 v[78:81], v[170:173], v[210:213], v[78:81]
	v_mfma_f32_16x16x32_bf16 v[70:73], v[160:163], v[218:221], v[70:73]
	v_mfma_f32_16x16x32_bf16 v[66:69], v[170:173], v[218:221], v[66:69]
	v_mfma_f32_16x16x32_bf16 v[118:121], v[166:169], v[182:185], v[118:121]
	v_mfma_f32_16x16x32_bf16 v[110:113], v[174:177], v[182:185], v[110:113]
	v_mfma_f32_16x16x32_bf16 v[102:105], v[166:169], v[190:193], v[102:105]
	v_mfma_f32_16x16x32_bf16 v[94:97], v[174:177], v[190:193], v[94:97]
	v_mfma_f32_16x16x32_bf16 v[86:89], v[166:169], v[214:217], v[86:89]
	v_mfma_f32_16x16x32_bf16 v[78:81], v[174:177], v[214:217], v[78:81]
	v_mfma_f32_16x16x32_bf16 v[70:73], v[166:169], v[242:245], v[70:73]
	v_mfma_f32_16x16x32_bf16 v[66:69], v[174:177], v[242:245], v[66:69]
	s_setprio 0
	s_barrier
	s_add_i32 s41, s72, s43
	v_lshl_add_u64 v[194:195], s[30:31], 0, v[64:65]
	s_mov_b32 m0, s41
	ds_read_b128 v[178:181], v141 offset:16384
	ds_read_b128 v[182:185], v141 offset:17408
	ds_read_b128 v[186:189], v141 offset:18432
	ds_read_b128 v[190:193], v141 offset:19456
	ds_read_b128 v[210:213], v141 offset:20480
	ds_read_b128 v[214:217], v141 offset:21504
	ds_read_b128 v[218:221], v141 offset:22528
	ds_read_b128 v[242:245], v141 offset:23552
	global_load_lds_dwordx4 v[194:195], off
	s_add_i32 m0, s41, 0x2000
	s_add_u32 s76, s30, 0x40000
	v_lshl_add_u64 v[222:223], s[30:31], 0, v[134:135]
	s_addc_u32 s77, s31, 0
	s_add_i32 s41, s73, s43
	global_load_lds_dwordx4 v[222:223], off
	v_lshl_add_u64 v[230:231], s[76:77], 0, v[64:65]
	s_mov_b32 m0, s41
	v_lshl_add_u64 v[232:233], s[38:39], 0, v[132:133]
	global_load_lds_dwordx4 v[230:231], off
	v_lshl_add_u64 v[230:231], s[76:77], 0, v[134:135]
	s_add_i32 m0, s41, 0x2000
	s_nop 0
	global_load_lds_dwordx4 v[230:231], off
	v_lshl_add_u64 v[230:231], s[38:39], 0, v[130:131]
	s_mov_b32 m0, s84
	s_nop 0
	global_load_lds_dwordx4 v[230:231], off
	s_mov_b32 m0, s24
	s_nop 0
	global_load_lds_dwordx4 v[232:233], off
	s_waitcnt vmcnt(8)
	s_waitcnt lgkmcnt(0)
	s_barrier
; #define PG8_STAGE(bufoff, gbase, voff) do { _Pragma("unroll") for (int _i = 0; _i < 2; ++_i) \
;         __builtin_amdgcn_global_load_lds((const unsigned*)((const char*)(gbase) + (voff)[_i]), (PG8_LAS unsigned*)(lds + (bufoff) + ldsw + _i * 8192), 16, 0, 0); } while (0)
; #define PG8_LDA(dst, b, h) do { _Pragma("unroll") for (int m = 0; m < 4; ++m) _Pragma("unroll") for (int k = 0; k < 2; ++k) dst[m][k] = *(const PG8_LAS bf16x8*)(lds + PG8_SA(b, h) + aoff + m * 2048 + k * 1024); } while (0)
; #define PG8_LDB(dst, b, h) do { _Pragma("unroll") for (int n = 0; n < 2; ++n) _Pragma("unroll") for (int k = 0; k < 2; ++k) dst[n][k] = *(const PG8_LAS bf16x8*)(lds + PG8_SB(b, h) + boff + n * 2048 + k * 1024); } while (0)
; #define PG8_MMA(ai, bj, At, Bt) do { __builtin_amdgcn_s_setprio(1); _Pragma("unroll") for (int m = 0; m < 4; ++m) _Pragma("unroll") for (int n = 0; n < 2; ++n) _Pragma("unroll") for (int k = 0; k < 2; ++k) \
;         acc[ai][bj][m][n] = __builtin_amdgcn_mfma_f32_16x16x32_bf16(Bt[n][k], At[m][k], acc[ai][bj][m][n], 0, 0, 0); __builtin_amdgcn_s_setprio(0); } while (0)
; #define PG8_WAIT_V(n) asm volatile("s_waitcnt vmcnt(" #n ")" ::: "memory")
; #define PG8_WAIT_L(n) asm volatile("s_waitcnt lgkmcnt(" #n ")" ::: "memory")
; #define PG8_BAR __builtin_amdgcn_s_barrier()
; #define PG8_SCHED __builtin_amdgcn_sched_barrier(0)
; template <class Epi, class Sched, bool ALIGN_EPI = false, bool SP2 = false>
; __device__ __forceinline__ void gemm_phase(PG8_LAS unsigned char* lds, const Gemm g, const Sched& S, const Epi& E) {
;     ...
;             PG8_WAIT_V(8); PG8_WAIT_L(0); PG8_BAR; PG8_MMA(1, 0, At, B0); PG8_MMA(1, 1, At, B1); PG8_BAR; PG8_SCHED;
;             PG8_LDB(B0, 1, 0); PG8_LDB(B1, 1, 1); PG8_SCHED; PG8_LDA(At, 1, 0); PG8_STAGE(PG8_SA(0, 1), a2 + hstepA, voffA);
;             PG8_WAIT_V(8); PG8_WAIT_L(0); PG8_BAR; PG8_MMA(0, 0, At, B0); PG8_MMA(0, 1, At, B1); PG8_BAR; PG8_SCHED;
	s_setprio 1
	v_mfma_f32_16x16x32_bf16 v[60:63], v[142:145], v[178:181], v[60:63]
	v_mfma_f32_16x16x32_bf16 v[56:59], v[152:155], v[178:181], v[56:59]
	v_mfma_f32_16x16x32_bf16 v[48:51], v[142:145], v[186:189], v[48:51]
	v_mfma_f32_16x16x32_bf16 v[40:43], v[152:155], v[186:189], v[40:43]
	v_mfma_f32_16x16x32_bf16 v[32:35], v[142:145], v[210:213], v[32:35]
	v_mfma_f32_16x16x32_bf16 v[24:27], v[152:155], v[210:213], v[24:27]
	v_mfma_f32_16x16x32_bf16 v[16:19], v[142:145], v[218:221], v[16:19]
	v_mfma_f32_16x16x32_bf16 v[8:11], v[152:155], v[218:221], v[8:11]
	v_mfma_f32_16x16x32_bf16 v[60:63], v[148:151], v[182:185], v[60:63]
	v_mfma_f32_16x16x32_bf16 v[56:59], v[156:159], v[182:185], v[56:59]
	v_mfma_f32_16x16x32_bf16 v[48:51], v[148:151], v[190:193], v[48:51]
	v_mfma_f32_16x16x32_bf16 v[40:43], v[156:159], v[190:193], v[40:43]
	v_mfma_f32_16x16x32_bf16 v[32:35], v[148:151], v[214:217], v[32:35]
	v_mfma_f32_16x16x32_bf16 v[24:27], v[156:159], v[214:217], v[24:27]
	v_mfma_f32_16x16x32_bf16 v[16:19], v[148:151], v[242:245], v[16:19]
	v_mfma_f32_16x16x32_bf16 v[8:11], v[156:159], v[242:245], v[8:11]
	s_setprio 0
	s_setprio 1
	v_mfma_f32_16x16x32_bf16 v[52:55], v[160:163], v[178:181], v[52:55]
	v_mfma_f32_16x16x32_bf16 v[44:47], v[170:173], v[178:181], v[44:47]
	v_mfma_f32_16x16x32_bf16 v[36:39], v[160:163], v[186:189], v[36:39]
	v_mfma_f32_16x16x32_bf16 v[28:31], v[170:173], v[186:189], v[28:31]
	v_mfma_f32_16x16x32_bf16 v[20:23], v[160:163], v[210:213], v[20:23]
	v_mfma_f32_16x16x32_bf16 v[12:15], v[170:173], v[210:213], v[12:15]
	v_mfma_f32_16x16x32_bf16 v[4:7], v[160:163], v[218:221], v[4:7]
	v_mfma_f32_16x16x32_bf16 v[0:3], v[170:173], v[218:221], v[0:3]
	v_mfma_f32_16x16x32_bf16 v[52:55], v[166:169], v[182:185], v[52:55]
	v_mfma_f32_16x16x32_bf16 v[44:47], v[174:177], v[182:185], v[44:47]
	v_mfma_f32_16x16x32_bf16 v[36:39], v[166:169], v[190:193], v[36:39]
	v_mfma_f32_16x16x32_bf16 v[28:31], v[174:177], v[190:193], v[28:31]
	v_mfma_f32_16x16x32_bf16 v[20:23], v[166:169], v[214:217], v[20:23]
	v_mfma_f32_16x16x32_bf16 v[12:15], v[174:177], v[214:217], v[12:15]
	v_mfma_f32_16x16x32_bf16 v[4:7], v[166:169], v[242:245], v[4:7]
	v_mfma_f32_16x16x32_bf16 v[0:3], v[174:177], v[242:245], v[0:3]
	s_setprio 0
	s_barrier
	s_add_i32 s80, 0, 0x18000
	v_add_u32_e32 v147, s80, v140
	s_add_i32 s81, 0, 0x1c000
	ds_read_b128 v[142:145], v147
	ds_read_b128 v[148:151], v147 offset:1024
	ds_read_b128 v[152:155], v147 offset:2048
	ds_read_b128 v[156:159], v147 offset:3072
	v_add_u32_e32 v147, s81, v140
	ds_read_b128 v[160:163], v147
	ds_read_b128 v[166:169], v147 offset:1024
	ds_read_b128 v[170:173], v147 offset:2048
	ds_read_b128 v[174:177], v147 offset:3072
	s_add_u32 s38, s38, 0x40000
	s_addc_u32 s39, s39, 0
	s_mov_b32 m0, s25
	v_lshl_add_u64 v[246:247], s[38:39], 0, v[130:131]
	ds_read_b128 v[178:181], v141 offset:32768
	ds_read_b128 v[182:185], v141 offset:33792
	ds_read_b128 v[186:189], v141 offset:34816
	ds_read_b128 v[190:193], v141 offset:35840
	ds_read_b128 v[210:213], v141 offset:36864
	ds_read_b128 v[214:217], v141 offset:37888
	ds_read_b128 v[218:221], v141 offset:38912
	ds_read_b128 v[242:245], v141 offset:39936
	global_load_lds_dwordx4 v[246:247], off
	v_lshl_add_u64 v[246:247], s[38:39], 0, v[132:133]
	s_mov_b32 m0, s60
	s_nop 0
	global_load_lds_dwordx4 v[246:247], off
	s_waitcnt vmcnt(8)
	s_waitcnt lgkmcnt(0)
	s_barrier
	s_setprio 1
	v_mfma_f32_16x16x32_bf16 v[126:129], v[142:145], v[178:181], v[126:129]
	v_mfma_f32_16x16x32_bf16 v[122:125], v[152:155], v[178:181], v[122:125]
	v_mfma_f32_16x16x32_bf16 v[114:117], v[142:145], v[186:189], v[114:117]
	v_mfma_f32_16x16x32_bf16 v[106:109], v[152:155], v[186:189], v[106:109]
	v_mfma_f32_16x16x32_bf16 v[98:101], v[142:145], v[210:213], v[98:101]
	v_mfma_f32_16x16x32_bf16 v[90:93], v[152:155], v[210:213], v[90:93]
	v_mfma_f32_16x16x32_bf16 v[82:85], v[142:145], v[218:221], v[82:85]
	v_mfma_f32_16x16x32_bf16 v[74:77], v[152:155], v[218:221], v[74:77]
	v_mfma_f32_16x16x32_bf16 v[126:129], v[148:151], v[182:185], v[126:129]
	v_mfma_f32_16x16x32_bf16 v[122:125], v[156:159], v[182:185], v[122:125]
	v_mfma_f32_16x16x32_bf16 v[114:117], v[148:151], v[190:193], v[114:117]
	v_mfma_f32_16x16x32_bf16 v[106:109], v[156:159], v[190:193], v[106:109]
	v_mfma_f32_16x16x32_bf16 v[98:101], v[148:151], v[214:217], v[98:101]
	v_mfma_f32_16x16x32_bf16 v[90:93], v[156:159], v[214:217], v[90:93]
	v_mfma_f32_16x16x32_bf16 v[82:85], v[148:151], v[242:245], v[82:85]
	v_mfma_f32_16x16x32_bf16 v[74:77], v[156:159], v[242:245], v[74:77]
	s_setprio 0
	s_setprio 1
	v_mfma_f32_16x16x32_bf16 v[118:121], v[160:163], v[178:181], v[118:121]
	v_mfma_f32_16x16x32_bf16 v[110:113], v[170:173], v[178:181], v[110:113]
	v_mfma_f32_16x16x32_bf16 v[102:105], v[160:163], v[186:189], v[102:105]
	v_mfma_f32_16x16x32_bf16 v[94:97], v[170:173], v[186:189], v[94:97]
	v_mfma_f32_16x16x32_bf16 v[86:89], v[160:163], v[210:213], v[86:89]
	v_mfma_f32_16x16x32_bf16 v[78:81], v[170:173], v[210:213], v[78:81]
	v_mfma_f32_16x16x32_bf16 v[70:73], v[160:163], v[218:221], v[70:73]
	v_mfma_f32_16x16x32_bf16 v[66:69], v[170:173], v[218:221], v[66:69]
	v_mfma_f32_16x16x32_bf16 v[118:121], v[166:169], v[182:185], v[118:121]
	v_mfma_f32_16x16x32_bf16 v[110:113], v[174:177], v[182:185], v[110:113]
	v_mfma_f32_16x16x32_bf16 v[102:105], v[166:169], v[190:193], v[102:105]
	v_mfma_f32_16x16x32_bf16 v[94:97], v[174:177], v[190:193], v[94:97]
	v_mfma_f32_16x16x32_bf16 v[86:89], v[166:169], v[214:217], v[86:89]
	v_mfma_f32_16x16x32_bf16 v[78:81], v[174:177], v[214:217], v[78:81]
	v_mfma_f32_16x16x32_bf16 v[70:73], v[166:169], v[242:245], v[70:73]
	v_mfma_f32_16x16x32_bf16 v[66:69], v[174:177], v[242:245], v[66:69]
	s_setprio 0
	s_barrier
; #define PG8_STAGE(bufoff, gbase, voff) do { _Pragma("unroll") for (int _i = 0; _i < 2; ++_i) \
;         __builtin_amdgcn_global_load_lds((const unsigned*)((const char*)(gbase) + (voff)[_i]), (PG8_LAS unsigned*)(lds + (bufoff) + ldsw + _i * 8192), 16, 0, 0); } while (0)
; #define PG8_LDA(dst, b, h) do { _Pragma("unroll") for (int m = 0; m < 4; ++m) _Pragma("unroll") for (int k = 0; k < 2; ++k) dst[m][k] = *(const PG8_LAS bf16x8*)(lds + PG8_SA(b, h) + aoff + m * 2048 + k * 1024); } while (0)
; #define PG8_MMA(ai, bj, At, Bt) do { __builtin_amdgcn_s_setprio(1); _Pragma("unroll") for (int m = 0; m < 4; ++m) _Pragma("unroll") for (int n = 0; n < 2; ++n) _Pragma("unroll") for (int k = 0; k < 2; ++k) \
;         acc[ai][bj][m][n] = __builtin_amdgcn_mfma_f32_16x16x32_bf16(Bt[n][k], At[m][k], acc[ai][bj][m][n], 0, 0, 0); __builtin_amdgcn_s_setprio(0); } while (0)
; #define PG8_WAIT_V(n) asm volatile("s_waitcnt vmcnt(" #n ")" ::: "memory")
; #define PG8_WAIT_L(n) asm volatile("s_waitcnt lgkmcnt(" #n ")" ::: "memory")
; #define PG8_BAR __builtin_amdgcn_s_barrier()
; #define PG8_SCHED __builtin_amdgcn_sched_barrier(0)
; template <class Epi, class Sched, bool ALIGN_EPI = false, bool SP2 = false>
; __device__ __forceinline__ void gemm_phase(PG8_LAS unsigned char* lds, const Gemm g, const Sched& S, const Epi& E) {
;     ...
;             PG8_LDA(At, 1, 1); PG8_STAGE(PG8_SB(1, 0), b3, voffB); PG8_STAGE(PG8_SB(1, 1), b3 + hstepB, voffB); PG8_STAGE(PG8_SA(1, 0), a3, voffA);
;             PG8_WAIT_V(8); PG8_WAIT_L(0); PG8_BAR; PG8_MMA(1, 0, At, B0); PG8_MMA(1, 1, At, B1); PG8_BAR; PG8_SCHED;
;     ...
;         }
;         if constexpr (ALIGN_EPI) { if (wr == 0) PG8_BAR; }
	s_add_i32 s38, s80, s43
	v_lshl_add_u64 v[194:195], v[194:195], 0, s[48:49]
	s_mov_b32 m0, s38
	ds_read_b128 v[178:181], v141 offset:49152
	ds_read_b128 v[182:185], v141 offset:50176
	ds_read_b128 v[186:189], v141 offset:51200
	ds_read_b128 v[190:193], v141 offset:52224
	ds_read_b128 v[210:213], v141 offset:53248
	ds_read_b128 v[214:217], v141 offset:54272
	ds_read_b128 v[218:221], v141 offset:55296
	ds_read_b128 v[242:245], v141 offset:56320
	global_load_lds_dwordx4 v[194:195], off
	s_add_i32 m0, s38, 0x2000
	s_add_u32 s30, s30, 0x40080
	v_lshl_add_u64 v[194:195], v[222:223], 0, s[48:49]
	s_addc_u32 s31, s31, 0
	s_add_i32 s38, s81, s43
	global_load_lds_dwordx4 v[194:195], off
	v_lshl_add_u64 v[194:195], s[30:31], 0, v[64:65]
	s_mov_b32 m0, s38
	s_nop 0
	global_load_lds_dwordx4 v[194:195], off
	v_lshl_add_u64 v[194:195], s[30:31], 0, v[134:135]
	s_add_i32 m0, s38, 0x2000
	s_nop 0
	global_load_lds_dwordx4 v[194:195], off
	v_lshl_add_u64 v[194:195], v[230:231], 0, s[48:49]
	s_mov_b32 m0, s61
	s_nop 0
	global_load_lds_dwordx4 v[194:195], off
	v_lshl_add_u64 v[194:195], v[232:233], 0, s[48:49]
	s_mov_b32 m0, s87
	s_nop 0
	global_load_lds_dwordx4 v[194:195], off
	s_waitcnt vmcnt(8)
	s_waitcnt lgkmcnt(0)
	s_barrier
	s_setprio 1
	v_mfma_f32_16x16x32_bf16 v[60:63], v[142:145], v[178:181], v[60:63]
	v_mfma_f32_16x16x32_bf16 v[56:59], v[152:155], v[178:181], v[56:59]
	v_mfma_f32_16x16x32_bf16 v[48:51], v[142:145], v[186:189], v[48:51]
	v_mfma_f32_16x16x32_bf16 v[40:43], v[152:155], v[186:189], v[40:43]
	v_mfma_f32_16x16x32_bf16 v[32:35], v[142:145], v[210:213], v[32:35]
	v_mfma_f32_16x16x32_bf16 v[24:27], v[152:155], v[210:213], v[24:27]
	v_mfma_f32_16x16x32_bf16 v[16:19], v[142:145], v[218:221], v[16:19]
	v_mfma_f32_16x16x32_bf16 v[8:11], v[152:155], v[218:221], v[8:11]
	v_mfma_f32_16x16x32_bf16 v[60:63], v[148:151], v[182:185], v[60:63]
	v_mfma_f32_16x16x32_bf16 v[56:59], v[156:159], v[182:185], v[56:59]
	v_mfma_f32_16x16x32_bf16 v[48:51], v[148:151], v[190:193], v[48:51]
	v_mfma_f32_16x16x32_bf16 v[40:43], v[156:159], v[190:193], v[40:43]
	v_mfma_f32_16x16x32_bf16 v[32:35], v[148:151], v[214:217], v[32:35]
	v_mfma_f32_16x16x32_bf16 v[24:27], v[156:159], v[214:217], v[24:27]
	v_mfma_f32_16x16x32_bf16 v[16:19], v[148:151], v[242:245], v[16:19]
	v_mfma_f32_16x16x32_bf16 v[8:11], v[156:159], v[242:245], v[8:11]
	s_setprio 0
	s_setprio 1
	v_mfma_f32_16x16x32_bf16 v[52:55], v[160:163], v[178:181], v[52:55]
	v_mfma_f32_16x16x32_bf16 v[44:47], v[170:173], v[178:181], v[44:47]
	v_mfma_f32_16x16x32_bf16 v[36:39], v[160:163], v[186:189], v[36:39]
	v_mfma_f32_16x16x32_bf16 v[28:31], v[170:173], v[186:189], v[28:31]
	v_mfma_f32_16x16x32_bf16 v[20:23], v[160:163], v[210:213], v[20:23]
	v_mfma_f32_16x16x32_bf16 v[12:15], v[170:173], v[210:213], v[12:15]
	v_mfma_f32_16x16x32_bf16 v[4:7], v[160:163], v[218:221], v[4:7]
	v_mfma_f32_16x16x32_bf16 v[0:3], v[170:173], v[218:221], v[0:3]
	v_mfma_f32_16x16x32_bf16 v[52:55], v[166:169], v[182:185], v[52:55]
	v_mfma_f32_16x16x32_bf16 v[44:47], v[174:177], v[182:185], v[44:47]
	v_mfma_f32_16x16x32_bf16 v[36:39], v[166:169], v[190:193], v[36:39]
	v_mfma_f32_16x16x32_bf16 v[28:31], v[174:177], v[190:193], v[28:31]
	v_mfma_f32_16x16x32_bf16 v[20:23], v[166:169], v[214:217], v[20:23]
	v_mfma_f32_16x16x32_bf16 v[12:15], v[174:177], v[214:217], v[12:15]
	v_mfma_f32_16x16x32_bf16 v[4:7], v[166:169], v[242:245], v[4:7]
	v_mfma_f32_16x16x32_bf16 v[0:3], v[174:177], v[242:245], v[0:3]
	s_setprio 0
	s_barrier
	s_add_i32 s91, s91, 2
	s_add_u32 s20, s20, 0x100
	s_addc_u32 s21, s21, 0
	s_cmp_gt_u32 s91, 13
	s_cbranch_scc0 .LBB0_1264
	s_cmpk_lt_u32 s34, 0x100
	s_cbranch_scc0 .LBB0_1267
	s_barrier

; #define PG8_STAGE(bufoff, gbase, voff) do { _Pragma("unroll") for (int _i = 0; _i < 2; ++_i) \
;         __builtin_amdgcn_global_load_lds((const unsigned*)((const char*)(gbase) + (voff)[_i]), (PG8_LAS unsigned*)(lds + (bufoff) + ldsw + _i * 8192), 16, 0, 0); } while (0)
; #define PG8_LDA(dst, b, h) do { _Pragma("unroll") for (int m = 0; m < 4; ++m) _Pragma("unroll") for (int k = 0; k < 2; ++k) dst[m][k] = *(const PG8_LAS bf16x8*)(lds + PG8_SA(b, h) + aoff + m * 2048 + k * 1024); } while (0)
; #define PG8_LDB(dst, b, h) do { _Pragma("unroll") for (int n = 0; n < 2; ++n) _Pragma("unroll") for (int k = 0; k < 2; ++k) dst[n][k] = *(const PG8_LAS bf16x8*)(lds + PG8_SB(b, h) + boff + n * 2048 + k * 1024); } while (0)
; #define PG8_MMA(ai, bj, At, Bt) do { __builtin_amdgcn_s_setprio(1); _Pragma("unroll") for (int m = 0; m < 4; ++m) _Pragma("unroll") for (int n = 0; n < 2; ++n) _Pragma("unroll") for (int k = 0; k < 2; ++k) \
;         acc[ai][bj][m][n] = __builtin_amdgcn_mfma_f32_16x16x32_bf16(Bt[n][k], At[m][k], acc[ai][bj][m][n], 0, 0, 0); __builtin_amdgcn_s_setprio(0); } while (0)
; #define PG8_WAIT_V(n) asm volatile("s_waitcnt vmcnt(" #n ")" ::: "memory")
; #define PG8_WAIT_L(n) asm volatile("s_waitcnt lgkmcnt(" #n ")" ::: "memory")
; #define PG8_BAR __builtin_amdgcn_s_barrier()
; #define PG8_SCHED __builtin_amdgcn_sched_barrier(0)
; template <class Epi, class Sched, bool ALIGN_EPI = false, bool SP2 = false>
; __device__ __forceinline__ void gemm_phase(PG8_LAS unsigned char* lds, const Gemm g, const Sched& S, const Epi& E) {
;     ...
;             const bool last = (t == nt - 2);
;             const char* a1 = cA + (size_t)(t + 1) * kstep;
;             const char* a2 = last ? nA : cA + (size_t)(t + 2) * kstep; const char* b2 = last ? nB : cB + (size_t)(t + 2) * kstep;
;             const char* a3 = a2 + kstep; const char* b3 = b2 + kstep;
;             if (last && has_next) S.a_ready(nxt);
;             if constexpr (SP2) {
;             PG8_LDB(B0, 0, 0); PG8_LDB(B1, 0, 1); PG8_SCHED; PG8_LDA(At, 0, 0); PG8_STAGE(PG8_SA(1, 1), a1 + hstepA, voffA);
;             PG8_WAIT_V(8); PG8_WAIT_L(0); PG8_BAR; PG8_MMA(0, 0, At, B0); PG8_MMA(0, 1, At, B1); PG8_BAR; PG8_SCHED;
;             PG8_LDA(At, 0, 1); PG8_STAGE(PG8_SB(0, 0), b2, voffB); PG8_STAGE(PG8_SB(0, 1), b2 + hstepB, voffB); PG8_STAGE(PG8_SA(0, 0), a2, voffA);
.LBB0_1274:
	v_add_u32_e32 v147, s72, v145
	s_add_i32 s24, s22, 2
	ds_read_b128 v[148:151], v147
	ds_read_b128 v[152:155], v147 offset:1024
	ds_read_b128 v[156:159], v147 offset:2048
	ds_read_b128 v[160:163], v147 offset:3072
	v_add_u32_e32 v147, s73, v145
	s_add_u32 s25, s20, 0xf99f0080
	ds_read_b128 v[164:167], v147
	ds_read_b128 v[168:171], v147 offset:1024
	ds_read_b128 v[172:175], v147 offset:2048
	ds_read_b128 v[176:179], v147 offset:3072
	s_addc_u32 s30, s21, -1
	s_cmp_lg_u32 s91, s22
	s_cselect_b32 s25, s25, 0
	s_cselect_b32 s22, s30, 0
	s_add_u32 s38, s8, s25
	s_addc_u32 s39, s9, s22
	s_add_u32 s30, s18, s25
	s_addc_u32 s31, s19, s22
	v_lshl_add_u64 v[222:223], v[140:141], 0, s[20:21]
	s_add_i32 m0, s84, 0xc000
	ds_read_b128 v[180:183], v146
	ds_read_b128 v[184:187], v146 offset:1024
	ds_read_b128 v[188:191], v146 offset:2048
	ds_read_b128 v[192:195], v146 offset:3072
	ds_read_b128 v[210:213], v146 offset:4096
	ds_read_b128 v[214:217], v146 offset:5120
	ds_read_b128 v[218:221], v146 offset:6144
	ds_read_b128 v[242:245], v146 offset:7168
	global_load_lds_dwordx4 v[222:223], off
	v_lshl_add_u64 v[222:223], v[142:143], 0, s[20:21]
	s_add_i32 m0, s84, 0xe000
	s_nop 0
	global_load_lds_dwordx4 v[222:223], off
	s_waitcnt vmcnt(8)
	s_waitcnt lgkmcnt(0)
	s_barrier
	s_setprio 1
	v_mfma_f32_16x16x32_bf16 v[126:129], v[148:151], v[180:183], v[126:129]
	v_mfma_f32_16x16x32_bf16 v[122:125], v[156:159], v[180:183], v[122:125]
	v_mfma_f32_16x16x32_bf16 v[110:113], v[148:151], v[188:191], v[110:113]
	v_mfma_f32_16x16x32_bf16 v[106:109], v[156:159], v[188:191], v[106:109]
	v_mfma_f32_16x16x32_bf16 v[94:97], v[148:151], v[210:213], v[94:97]
	v_mfma_f32_16x16x32_bf16 v[90:93], v[156:159], v[210:213], v[90:93]
	v_mfma_f32_16x16x32_bf16 v[78:81], v[148:151], v[218:221], v[78:81]
	v_mfma_f32_16x16x32_bf16 v[74:77], v[156:159], v[218:221], v[74:77]
	v_mfma_f32_16x16x32_bf16 v[126:129], v[152:155], v[184:187], v[126:129]
	v_mfma_f32_16x16x32_bf16 v[122:125], v[160:163], v[184:187], v[122:125]
	v_mfma_f32_16x16x32_bf16 v[110:113], v[152:155], v[192:195], v[110:113]
	v_mfma_f32_16x16x32_bf16 v[106:109], v[160:163], v[192:195], v[106:109]
	v_mfma_f32_16x16x32_bf16 v[94:97], v[152:155], v[214:217], v[94:97]
	v_mfma_f32_16x16x32_bf16 v[90:93], v[160:163], v[214:217], v[90:93]
	v_mfma_f32_16x16x32_bf16 v[78:81], v[152:155], v[242:245], v[78:81]
	v_mfma_f32_16x16x32_bf16 v[74:77], v[160:163], v[242:245], v[74:77]
	s_setprio 0
	s_setprio 1
	v_mfma_f32_16x16x32_bf16 v[118:121], v[164:167], v[180:183], v[118:121]
	v_mfma_f32_16x16x32_bf16 v[114:117], v[172:175], v[180:183], v[114:117]
	v_mfma_f32_16x16x32_bf16 v[102:105], v[164:167], v[188:191], v[102:105]
	v_mfma_f32_16x16x32_bf16 v[98:101], v[172:175], v[188:191], v[98:101]
	v_mfma_f32_16x16x32_bf16 v[86:89], v[164:167], v[210:213], v[86:89]
	v_mfma_f32_16x16x32_bf16 v[82:85], v[172:175], v[210:213], v[82:85]
	v_mfma_f32_16x16x32_bf16 v[70:73], v[164:167], v[218:221], v[70:73]
	v_mfma_f32_16x16x32_bf16 v[66:69], v[172:175], v[218:221], v[66:69]
	v_mfma_f32_16x16x32_bf16 v[118:121], v[168:171], v[184:187], v[118:121]
	v_mfma_f32_16x16x32_bf16 v[114:117], v[176:179], v[184:187], v[114:117]
	v_mfma_f32_16x16x32_bf16 v[102:105], v[168:171], v[192:195], v[102:105]
	v_mfma_f32_16x16x32_bf16 v[98:101], v[176:179], v[192:195], v[98:101]
	v_mfma_f32_16x16x32_bf16 v[86:89], v[168:171], v[214:217], v[86:89]
	v_mfma_f32_16x16x32_bf16 v[82:85], v[176:179], v[214:217], v[82:85]
	v_mfma_f32_16x16x32_bf16 v[70:73], v[168:171], v[242:245], v[70:73]
	v_mfma_f32_16x16x32_bf16 v[66:69], v[176:179], v[242:245], v[66:69]
	s_setprio 0
	s_barrier
	s_add_i32 s22, s72, s43
	v_lshl_add_u64 v[222:223], s[30:31], 0, v[64:65]
	s_mov_b32 m0, s22
	ds_read_b128 v[180:183], v146 offset:16384
	ds_read_b128 v[184:187], v146 offset:17408
	ds_read_b128 v[188:191], v146 offset:18432
	ds_read_b128 v[192:195], v146 offset:19456
	ds_read_b128 v[210:213], v146 offset:20480
	ds_read_b128 v[214:217], v146 offset:21504
	ds_read_b128 v[218:221], v146 offset:22528
	ds_read_b128 v[242:245], v146 offset:23552
	global_load_lds_dwordx4 v[222:223], off
	s_add_i32 m0, s22, 0x2000
	s_add_u32 s60, s30, 0x40000
	v_lshl_add_u64 v[230:231], s[30:31], 0, v[138:139]
	s_addc_u32 s61, s31, 0
	s_add_i32 s22, s73, s43
	global_load_lds_dwordx4 v[230:231], off
	v_lshl_add_u64 v[232:233], s[60:61], 0, v[64:65]
	s_mov_b32 m0, s22
	v_lshl_add_u64 v[246:247], s[38:39], 0, v[136:137]
	global_load_lds_dwordx4 v[232:233], off
	v_lshl_add_u64 v[232:233], s[60:61], 0, v[138:139]
	s_add_i32 m0, s22, 0x2000
	s_nop 0
	global_load_lds_dwordx4 v[232:233], off
	v_lshl_add_u64 v[232:233], s[38:39], 0, v[134:135]
	s_mov_b32 m0, s84
	s_nop 0
	global_load_lds_dwordx4 v[232:233], off
	s_mov_b32 m0, s93
	s_nop 0
	global_load_lds_dwordx4 v[246:247], off
	s_waitcnt vmcnt(8)
	s_waitcnt lgkmcnt(0)
	s_barrier
; #define PG8_STAGE(bufoff, gbase, voff) do { _Pragma("unroll") for (int _i = 0; _i < 2; ++_i) \
;         __builtin_amdgcn_global_load_lds((const unsigned*)((const char*)(gbase) + (voff)[_i]), (PG8_LAS unsigned*)(lds + (bufoff) + ldsw + _i * 8192), 16, 0, 0); } while (0)
; #define PG8_LDA(dst, b, h) do { _Pragma("unroll") for (int m = 0; m < 4; ++m) _Pragma("unroll") for (int k = 0; k < 2; ++k) dst[m][k] = *(const PG8_LAS bf16x8*)(lds + PG8_SA(b, h) + aoff + m * 2048 + k * 1024); } while (0)
; #define PG8_LDB(dst, b, h) do { _Pragma("unroll") for (int n = 0; n < 2; ++n) _Pragma("unroll") for (int k = 0; k < 2; ++k) dst[n][k] = *(const PG8_LAS bf16x8*)(lds + PG8_SB(b, h) + boff + n * 2048 + k * 1024); } while (0)
; #define PG8_MMA(ai, bj, At, Bt) do { __builtin_amdgcn_s_setprio(1); _Pragma("unroll") for (int m = 0; m < 4; ++m) _Pragma("unroll") for (int n = 0; n < 2; ++n) _Pragma("unroll") for (int k = 0; k < 2; ++k) \
;         acc[ai][bj][m][n] = __builtin_amdgcn_mfma_f32_16x16x32_bf16(Bt[n][k], At[m][k], acc[ai][bj][m][n], 0, 0, 0); __builtin_amdgcn_s_setprio(0); } while (0)
; #define PG8_WAIT_V(n) asm volatile("s_waitcnt vmcnt(" #n ")" ::: "memory")
; #define PG8_WAIT_L(n) asm volatile("s_waitcnt lgkmcnt(" #n ")" ::: "memory")
; #define PG8_BAR __builtin_amdgcn_s_barrier()
; #define PG8_SCHED __builtin_amdgcn_sched_barrier(0)
; template <class Epi, class Sched, bool ALIGN_EPI = false, bool SP2 = false>
; __device__ __forceinline__ void gemm_phase(PG8_LAS unsigned char* lds, const Gemm g, const Sched& S, const Epi& E) {
;     ...
;             PG8_WAIT_V(8); PG8_WAIT_L(0); PG8_BAR; PG8_MMA(1, 0, At, B0); PG8_MMA(1, 1, At, B1); PG8_BAR; PG8_SCHED;
;             PG8_LDB(B0, 1, 0); PG8_LDB(B1, 1, 1); PG8_SCHED; PG8_LDA(At, 1, 0); PG8_STAGE(PG8_SA(0, 1), a2 + hstepA, voffA);
;             PG8_WAIT_V(8); PG8_WAIT_L(0); PG8_BAR; PG8_MMA(0, 0, At, B0); PG8_MMA(0, 1, At, B1); PG8_BAR; PG8_SCHED;
	s_setprio 1
	v_mfma_f32_16x16x32_bf16 v[60:63], v[148:151], v[180:183], v[60:63]
	v_mfma_f32_16x16x32_bf16 v[56:59], v[156:159], v[180:183], v[56:59]
	v_mfma_f32_16x16x32_bf16 v[44:47], v[148:151], v[188:191], v[44:47]
	v_mfma_f32_16x16x32_bf16 v[40:43], v[156:159], v[188:191], v[40:43]
	v_mfma_f32_16x16x32_bf16 v[28:31], v[148:151], v[210:213], v[28:31]
	v_mfma_f32_16x16x32_bf16 v[24:27], v[156:159], v[210:213], v[24:27]
	v_mfma_f32_16x16x32_bf16 v[12:15], v[148:151], v[218:221], v[12:15]
	v_mfma_f32_16x16x32_bf16 v[8:11], v[156:159], v[218:221], v[8:11]
	v_mfma_f32_16x16x32_bf16 v[60:63], v[152:155], v[184:187], v[60:63]
	v_mfma_f32_16x16x32_bf16 v[56:59], v[160:163], v[184:187], v[56:59]
	v_mfma_f32_16x16x32_bf16 v[44:47], v[152:155], v[192:195], v[44:47]
	v_mfma_f32_16x16x32_bf16 v[40:43], v[160:163], v[192:195], v[40:43]
	v_mfma_f32_16x16x32_bf16 v[28:31], v[152:155], v[214:217], v[28:31]
	v_mfma_f32_16x16x32_bf16 v[24:27], v[160:163], v[214:217], v[24:27]
	v_mfma_f32_16x16x32_bf16 v[12:15], v[152:155], v[242:245], v[12:15]
	v_mfma_f32_16x16x32_bf16 v[8:11], v[160:163], v[242:245], v[8:11]
	s_setprio 0
	s_setprio 1
	v_mfma_f32_16x16x32_bf16 v[52:55], v[164:167], v[180:183], v[52:55]
	v_mfma_f32_16x16x32_bf16 v[48:51], v[172:175], v[180:183], v[48:51]
	v_mfma_f32_16x16x32_bf16 v[36:39], v[164:167], v[188:191], v[36:39]
	v_mfma_f32_16x16x32_bf16 v[32:35], v[172:175], v[188:191], v[32:35]
	v_mfma_f32_16x16x32_bf16 v[20:23], v[164:167], v[210:213], v[20:23]
	v_mfma_f32_16x16x32_bf16 v[16:19], v[172:175], v[210:213], v[16:19]
	v_mfma_f32_16x16x32_bf16 v[4:7], v[164:167], v[218:221], v[4:7]
	v_mfma_f32_16x16x32_bf16 v[0:3], v[172:175], v[218:221], v[0:3]
	v_mfma_f32_16x16x32_bf16 v[52:55], v[168:171], v[184:187], v[52:55]
	v_mfma_f32_16x16x32_bf16 v[48:51], v[176:179], v[184:187], v[48:51]
	v_mfma_f32_16x16x32_bf16 v[36:39], v[168:171], v[192:195], v[36:39]
	v_mfma_f32_16x16x32_bf16 v[32:35], v[176:179], v[192:195], v[32:35]
	v_mfma_f32_16x16x32_bf16 v[20:23], v[168:171], v[214:217], v[20:23]
	v_mfma_f32_16x16x32_bf16 v[16:19], v[176:179], v[214:217], v[16:19]
	v_mfma_f32_16x16x32_bf16 v[4:7], v[168:171], v[242:245], v[4:7]
	v_mfma_f32_16x16x32_bf16 v[0:3], v[176:179], v[242:245], v[0:3]
	s_setprio 0
	s_barrier
	v_add_u32_e32 v147, s80, v145
	ds_read_b128 v[148:151], v147
	ds_read_b128 v[152:155], v147 offset:1024
	ds_read_b128 v[156:159], v147 offset:2048
	ds_read_b128 v[160:163], v147 offset:3072
	v_add_u32_e32 v147, s81, v145
	ds_read_b128 v[164:167], v147
	ds_read_b128 v[168:171], v147 offset:1024
	ds_read_b128 v[172:175], v147 offset:2048
	ds_read_b128 v[176:179], v147 offset:3072
	s_add_u32 s38, s38, 0x10000
	s_addc_u32 s39, s39, 0
	s_mov_b32 m0, s94
	v_lshl_add_u64 v[248:249], s[38:39], 0, v[134:135]
	ds_read_b128 v[180:183], v146 offset:32768
	ds_read_b128 v[184:187], v146 offset:33792
	ds_read_b128 v[188:191], v146 offset:34816
	ds_read_b128 v[192:195], v146 offset:35840
	ds_read_b128 v[210:213], v146 offset:36864
	ds_read_b128 v[214:217], v146 offset:37888
	ds_read_b128 v[218:221], v146 offset:38912
	ds_read_b128 v[242:245], v146 offset:39936
	global_load_lds_dwordx4 v[248:249], off
	v_lshl_add_u64 v[248:249], s[38:39], 0, v[136:137]
	s_mov_b32 m0, s95
	s_nop 0
	global_load_lds_dwordx4 v[248:249], off
	s_waitcnt vmcnt(8)
	s_waitcnt lgkmcnt(0)
	s_barrier
	s_setprio 1
	v_mfma_f32_16x16x32_bf16 v[126:129], v[148:151], v[180:183], v[126:129]
	v_mfma_f32_16x16x32_bf16 v[122:125], v[156:159], v[180:183], v[122:125]
	v_mfma_f32_16x16x32_bf16 v[110:113], v[148:151], v[188:191], v[110:113]
	v_mfma_f32_16x16x32_bf16 v[106:109], v[156:159], v[188:191], v[106:109]
	v_mfma_f32_16x16x32_bf16 v[94:97], v[148:151], v[210:213], v[94:97]
	v_mfma_f32_16x16x32_bf16 v[90:93], v[156:159], v[210:213], v[90:93]
	v_mfma_f32_16x16x32_bf16 v[78:81], v[148:151], v[218:221], v[78:81]
	v_mfma_f32_16x16x32_bf16 v[74:77], v[156:159], v[218:221], v[74:77]
	v_mfma_f32_16x16x32_bf16 v[126:129], v[152:155], v[184:187], v[126:129]
	v_mfma_f32_16x16x32_bf16 v[122:125], v[160:163], v[184:187], v[122:125]
	v_mfma_f32_16x16x32_bf16 v[110:113], v[152:155], v[192:195], v[110:113]
	v_mfma_f32_16x16x32_bf16 v[106:109], v[160:163], v[192:195], v[106:109]
	v_mfma_f32_16x16x32_bf16 v[94:97], v[152:155], v[214:217], v[94:97]
	v_mfma_f32_16x16x32_bf16 v[90:93], v[160:163], v[214:217], v[90:93]
	v_mfma_f32_16x16x32_bf16 v[78:81], v[152:155], v[242:245], v[78:81]
	v_mfma_f32_16x16x32_bf16 v[74:77], v[160:163], v[242:245], v[74:77]
	s_setprio 0
	s_setprio 1
	v_mfma_f32_16x16x32_bf16 v[118:121], v[164:167], v[180:183], v[118:121]
	v_mfma_f32_16x16x32_bf16 v[114:117], v[172:175], v[180:183], v[114:117]
	v_mfma_f32_16x16x32_bf16 v[102:105], v[164:167], v[188:191], v[102:105]
	v_mfma_f32_16x16x32_bf16 v[98:101], v[172:175], v[188:191], v[98:101]
	v_mfma_f32_16x16x32_bf16 v[86:89], v[164:167], v[210:213], v[86:89]
	v_mfma_f32_16x16x32_bf16 v[82:85], v[172:175], v[210:213], v[82:85]
	v_mfma_f32_16x16x32_bf16 v[70:73], v[164:167], v[218:221], v[70:73]
	v_mfma_f32_16x16x32_bf16 v[66:69], v[172:175], v[218:221], v[66:69]
	v_mfma_f32_16x16x32_bf16 v[118:121], v[168:171], v[184:187], v[118:121]
	v_mfma_f32_16x16x32_bf16 v[114:117], v[176:179], v[184:187], v[114:117]
	v_mfma_f32_16x16x32_bf16 v[102:105], v[168:171], v[192:195], v[102:105]
	v_mfma_f32_16x16x32_bf16 v[98:101], v[176:179], v[192:195], v[98:101]
	v_mfma_f32_16x16x32_bf16 v[86:89], v[168:171], v[214:217], v[86:89]
	v_mfma_f32_16x16x32_bf16 v[82:85], v[176:179], v[214:217], v[82:85]
	v_mfma_f32_16x16x32_bf16 v[70:73], v[168:171], v[242:245], v[70:73]
	v_mfma_f32_16x16x32_bf16 v[66:69], v[176:179], v[242:245], v[66:69]
	s_setprio 0
	s_barrier
; #define PG8_STAGE(bufoff, gbase, voff) do { _Pragma("unroll") for (int _i = 0; _i < 2; ++_i) \
;         __builtin_amdgcn_global_load_lds((const unsigned*)((const char*)(gbase) + (voff)[_i]), (PG8_LAS unsigned*)(lds + (bufoff) + ldsw + _i * 8192), 16, 0, 0); } while (0)
; #define PG8_LDA(dst, b, h) do { _Pragma("unroll") for (int m = 0; m < 4; ++m) _Pragma("unroll") for (int k = 0; k < 2; ++k) dst[m][k] = *(const PG8_LAS bf16x8*)(lds + PG8_SA(b, h) + aoff + m * 2048 + k * 1024); } while (0)
; #define PG8_MMA(ai, bj, At, Bt) do { __builtin_amdgcn_s_setprio(1); _Pragma("unroll") for (int m = 0; m < 4; ++m) _Pragma("unroll") for (int n = 0; n < 2; ++n) _Pragma("unroll") for (int k = 0; k < 2; ++k) \
;         acc[ai][bj][m][n] = __builtin_amdgcn_mfma_f32_16x16x32_bf16(Bt[n][k], At[m][k], acc[ai][bj][m][n], 0, 0, 0); __builtin_amdgcn_s_setprio(0); } while (0)
; #define PG8_WAIT_V(n) asm volatile("s_waitcnt vmcnt(" #n ")" ::: "memory")
; #define PG8_WAIT_L(n) asm volatile("s_waitcnt lgkmcnt(" #n ")" ::: "memory")
; #define PG8_BAR __builtin_amdgcn_s_barrier()
; #define PG8_SCHED __builtin_amdgcn_sched_barrier(0)
; template <class Epi, class Sched, bool ALIGN_EPI = false, bool SP2 = false>
; __device__ __forceinline__ void gemm_phase(PG8_LAS unsigned char* lds, const Gemm g, const Sched& S, const Epi& E) {
;     ...
;             PG8_LDA(At, 1, 1); PG8_STAGE(PG8_SB(1, 0), b3, voffB); PG8_STAGE(PG8_SB(1, 1), b3 + hstepB, voffB); PG8_STAGE(PG8_SA(1, 0), a3, voffA);
;             PG8_WAIT_V(8); PG8_WAIT_L(0); PG8_BAR; PG8_MMA(1, 0, At, B0); PG8_MMA(1, 1, At, B1); PG8_BAR; PG8_SCHED;
	s_add_i32 s22, s80, s43
	v_lshl_add_u64 v[222:223], v[222:223], 0, s[48:49]
	s_mov_b32 m0, s22
	ds_read_b128 v[180:183], v146 offset:49152
	ds_read_b128 v[184:187], v146 offset:50176
	ds_read_b128 v[188:191], v146 offset:51200
	ds_read_b128 v[192:195], v146 offset:52224
	ds_read_b128 v[210:213], v146 offset:53248
	ds_read_b128 v[214:217], v146 offset:54272
	ds_read_b128 v[218:221], v146 offset:55296
	ds_read_b128 v[242:245], v146 offset:56320
	global_load_lds_dwordx4 v[222:223], off
	s_add_i32 m0, s22, 0x2000
	s_add_u32 s30, s30, 0x40080
	v_lshl_add_u64 v[222:223], v[230:231], 0, s[48:49]
	s_addc_u32 s31, s31, 0
	s_add_i32 s22, s81, s43
	global_load_lds_dwordx4 v[222:223], off
	v_lshl_add_u64 v[222:223], s[30:31], 0, v[64:65]
	s_mov_b32 m0, s22
	s_nop 0
	global_load_lds_dwordx4 v[222:223], off
	v_lshl_add_u64 v[222:223], s[30:31], 0, v[138:139]
	s_add_i32 m0, s22, 0x2000
	s_nop 0
	global_load_lds_dwordx4 v[222:223], off
	v_lshl_add_u64 v[222:223], v[232:233], 0, s[48:49]
	s_mov_b32 m0, s96
	s_nop 0
	global_load_lds_dwordx4 v[222:223], off
	v_lshl_add_u64 v[222:223], v[246:247], 0, s[48:49]
	s_mov_b32 m0, s97
	s_nop 0
	global_load_lds_dwordx4 v[222:223], off
	s_waitcnt vmcnt(8)
	s_waitcnt lgkmcnt(0)
	s_barrier
	s_setprio 1
	v_mfma_f32_16x16x32_bf16 v[60:63], v[148:151], v[180:183], v[60:63]
	v_mfma_f32_16x16x32_bf16 v[56:59], v[156:159], v[180:183], v[56:59]
	v_mfma_f32_16x16x32_bf16 v[44:47], v[148:151], v[188:191], v[44:47]
	v_mfma_f32_16x16x32_bf16 v[40:43], v[156:159], v[188:191], v[40:43]
	v_mfma_f32_16x16x32_bf16 v[28:31], v[148:151], v[210:213], v[28:31]
	v_mfma_f32_16x16x32_bf16 v[24:27], v[156:159], v[210:213], v[24:27]
	v_mfma_f32_16x16x32_bf16 v[12:15], v[148:151], v[218:221], v[12:15]
	v_mfma_f32_16x16x32_bf16 v[8:11], v[156:159], v[218:221], v[8:11]
	v_mfma_f32_16x16x32_bf16 v[60:63], v[152:155], v[184:187], v[60:63]
	v_mfma_f32_16x16x32_bf16 v[56:59], v[160:163], v[184:187], v[56:59]
	v_mfma_f32_16x16x32_bf16 v[44:47], v[152:155], v[192:195], v[44:47]
	v_mfma_f32_16x16x32_bf16 v[40:43], v[160:163], v[192:195], v[40:43]
	v_mfma_f32_16x16x32_bf16 v[28:31], v[152:155], v[214:217], v[28:31]
	v_mfma_f32_16x16x32_bf16 v[24:27], v[160:163], v[214:217], v[24:27]
	v_mfma_f32_16x16x32_bf16 v[12:15], v[152:155], v[242:245], v[12:15]
	v_mfma_f32_16x16x32_bf16 v[8:11], v[160:163], v[242:245], v[8:11]
	s_setprio 0
	s_setprio 1
	v_mfma_f32_16x16x32_bf16 v[52:55], v[164:167], v[180:183], v[52:55]
	v_mfma_f32_16x16x32_bf16 v[48:51], v[172:175], v[180:183], v[48:51]
	v_mfma_f32_16x16x32_bf16 v[36:39], v[164:167], v[188:191], v[36:39]
	v_mfma_f32_16x16x32_bf16 v[32:35], v[172:175], v[188:191], v[32:35]
	v_mfma_f32_16x16x32_bf16 v[20:23], v[164:167], v[210:213], v[20:23]
	v_mfma_f32_16x16x32_bf16 v[16:19], v[172:175], v[210:213], v[16:19]
	v_mfma_f32_16x16x32_bf16 v[4:7], v[164:167], v[218:221], v[4:7]
	v_mfma_f32_16x16x32_bf16 v[0:3], v[172:175], v[218:221], v[0:3]
	v_mfma_f32_16x16x32_bf16 v[52:55], v[168:171], v[184:187], v[52:55]
	v_mfma_f32_16x16x32_bf16 v[48:51], v[176:179], v[184:187], v[48:51]
	v_mfma_f32_16x16x32_bf16 v[36:39], v[168:171], v[192:195], v[36:39]
	v_mfma_f32_16x16x32_bf16 v[32:35], v[176:179], v[192:195], v[32:35]
	v_mfma_f32_16x16x32_bf16 v[20:23], v[168:171], v[214:217], v[20:23]
	v_mfma_f32_16x16x32_bf16 v[16:19], v[176:179], v[214:217], v[16:19]
	v_mfma_f32_16x16x32_bf16 v[4:7], v[168:171], v[242:245], v[4:7]
	v_mfma_f32_16x16x32_bf16 v[0:3], v[176:179], v[242:245], v[0:3]
	s_setprio 0
	s_barrier
	s_add_u32 s20, s20, 0x100
	s_addc_u32 s21, s21, 0
	s_cmp_lt_i32 s24, s87
	s_mov_b32 s22, s24
	s_cbranch_scc1 .LBB0_1274

; #define PG8_STAGE(bufoff, gbase, voff) do { _Pragma("unroll") for (int _i = 0; _i < 2; ++_i) \
;         __builtin_amdgcn_global_load_lds((const unsigned*)((const char*)(gbase) + (voff)[_i]), (PG8_LAS unsigned*)(lds + (bufoff) + ldsw + _i * 8192), 16, 0, 0); } while (0)
; #define PG8_LDA(dst, b, h) do { _Pragma("unroll") for (int m = 0; m < 4; ++m) _Pragma("unroll") for (int k = 0; k < 2; ++k) dst[m][k] = *(const PG8_LAS bf16x8*)(lds + PG8_SA(b, h) + aoff + m * 2048 + k * 1024); } while (0)
; #define PG8_LDB(dst, b, h) do { _Pragma("unroll") for (int n = 0; n < 2; ++n) _Pragma("unroll") for (int k = 0; k < 2; ++k) dst[n][k] = *(const PG8_LAS bf16x8*)(lds + PG8_SB(b, h) + boff + n * 2048 + k * 1024); } while (0)
; #define PG8_MMA(ai, bj, At, Bt) do { __builtin_amdgcn_s_setprio(1); _Pragma("unroll") for (int m = 0; m < 4; ++m) _Pragma("unroll") for (int n = 0; n < 2; ++n) _Pragma("unroll") for (int k = 0; k < 2; ++k) \
;         acc[ai][bj][m][n] = __builtin_amdgcn_mfma_f32_16x16x32_bf16(Bt[n][k], At[m][k], acc[ai][bj][m][n], 0, 0, 0); __builtin_amdgcn_s_setprio(0); } while (0)
; #define PG8_WAIT_V(n) asm volatile("s_waitcnt vmcnt(" #n ")" ::: "memory")
; #define PG8_WAIT_L(n) asm volatile("s_waitcnt lgkmcnt(" #n ")" ::: "memory")
; #define PG8_BAR __builtin_amdgcn_s_barrier()
; #define PG8_SCHED __builtin_amdgcn_sched_barrier(0)
; template <class Epi, class Sched, bool ALIGN_EPI = false, bool SP2 = false>
; __device__ __forceinline__ void gemm_phase(PG8_LAS unsigned char* lds, const Gemm g, const Sched& S, const Epi& E) {
;     ...
;         for (int t = 0; t < nt; t += 2) {
;             const bool last = (t == nt - 2);
;             const char* a1 = cA + (size_t)(t + 1) * kstep;
;             const char* a2 = last ? nA : cA + (size_t)(t + 2) * kstep; const char* b2 = last ? nB : cB + (size_t)(t + 2) * kstep;
;             const char* a3 = a2 + kstep; const char* b3 = b2 + kstep;
;             if (last && has_next) S.a_ready(nxt);
;             if constexpr (SP2) {
;             PG8_LDB(B0, 0, 0); PG8_LDB(B1, 0, 1); PG8_SCHED; PG8_LDA(At, 0, 0); PG8_STAGE(PG8_SA(1, 1), a1 + hstepA, voffA);
;             PG8_WAIT_V(8); PG8_WAIT_L(0); PG8_BAR; PG8_MMA(0, 0, At, B0); PG8_MMA(0, 1, At, B1); PG8_BAR; PG8_SCHED;
;             PG8_LDA(At, 0, 1); PG8_STAGE(PG8_SB(0, 0), b2, voffB); PG8_STAGE(PG8_SB(0, 1), b2 + hstepB, voffB); PG8_STAGE(PG8_SA(0, 0), a2, voffA);
.LBB0_1297:
	s_add_i32 s24, s18, 2
	v_add_u32_e32 v156, s72, v131
	v_add_u32_e32 v172, s73, v131
	s_add_u32 s19, s16, 0xf39f0080
	ds_read_b128 v[144:147], v156
	ds_read_b128 v[148:151], v156 offset:1024
	ds_read_b128 v[152:155], v156 offset:2048
	ds_read_b128 v[156:159], v156 offset:3072
	ds_read_b128 v[160:163], v172
	ds_read_b128 v[164:167], v172 offset:1024
	ds_read_b128 v[168:171], v172 offset:2048
	ds_read_b128 v[172:175], v172 offset:3072
	s_addc_u32 s20, s17, -1
	s_cmp_lg_u32 s91, s18
	s_cselect_b32 s18, s19, 0
	s_cselect_b32 s25, s20, 0
	s_add_u32 s20, s6, s18
	s_addc_u32 s21, s7, s25
	s_add_u32 s18, s0, s18
	s_addc_u32 s19, s1, s25
	v_lshl_add_u64 v[222:223], v[138:139], 0, s[16:17]
	s_add_i32 m0, s34, 0xc000
	ds_read_b128 v[176:179], v143
	ds_read_b128 v[180:183], v143 offset:1024
	ds_read_b128 v[184:187], v143 offset:2048
	ds_read_b128 v[188:191], v143 offset:3072
	ds_read_b128 v[192:195], v143 offset:4096
	ds_read_b128 v[210:213], v143 offset:5120
	ds_read_b128 v[214:217], v143 offset:6144
	ds_read_b128 v[218:221], v143 offset:7168
	global_load_lds_dwordx4 v[222:223], off
	v_lshl_add_u64 v[222:223], v[140:141], 0, s[16:17]
	s_add_i32 m0, s34, 0xe000
	s_nop 0
	global_load_lds_dwordx4 v[222:223], off
	s_waitcnt vmcnt(8)
	s_waitcnt lgkmcnt(0)
	s_barrier
	s_setprio 1
	v_mfma_f32_16x16x32_bf16 v[122:125], v[144:147], v[176:179], v[122:125]
	v_mfma_f32_16x16x32_bf16 v[126:129], v[152:155], v[176:179], v[126:129]
	v_mfma_f32_16x16x32_bf16 v[110:113], v[144:147], v[184:187], v[110:113]
	v_mfma_f32_16x16x32_bf16 v[106:109], v[152:155], v[184:187], v[106:109]
	v_mfma_f32_16x16x32_bf16 v[94:97], v[144:147], v[192:195], v[94:97]
	v_mfma_f32_16x16x32_bf16 v[90:93], v[152:155], v[192:195], v[90:93]
	v_mfma_f32_16x16x32_bf16 v[78:81], v[144:147], v[214:217], v[78:81]
	v_mfma_f32_16x16x32_bf16 v[74:77], v[152:155], v[214:217], v[74:77]
	v_mfma_f32_16x16x32_bf16 v[122:125], v[148:151], v[180:183], v[122:125]
	v_mfma_f32_16x16x32_bf16 v[126:129], v[156:159], v[180:183], v[126:129]
	v_mfma_f32_16x16x32_bf16 v[110:113], v[148:151], v[188:191], v[110:113]
	v_mfma_f32_16x16x32_bf16 v[106:109], v[156:159], v[188:191], v[106:109]
	v_mfma_f32_16x16x32_bf16 v[94:97], v[148:151], v[210:213], v[94:97]
	v_mfma_f32_16x16x32_bf16 v[90:93], v[156:159], v[210:213], v[90:93]
	v_mfma_f32_16x16x32_bf16 v[78:81], v[148:151], v[218:221], v[78:81]
	v_mfma_f32_16x16x32_bf16 v[74:77], v[156:159], v[218:221], v[74:77]
	s_setprio 0
	s_setprio 1
	v_mfma_f32_16x16x32_bf16 v[118:121], v[160:163], v[176:179], v[118:121]
	v_mfma_f32_16x16x32_bf16 v[114:117], v[168:171], v[176:179], v[114:117]
	v_mfma_f32_16x16x32_bf16 v[102:105], v[160:163], v[184:187], v[102:105]
	v_mfma_f32_16x16x32_bf16 v[98:101], v[168:171], v[184:187], v[98:101]
	v_mfma_f32_16x16x32_bf16 v[86:89], v[160:163], v[192:195], v[86:89]
	v_mfma_f32_16x16x32_bf16 v[82:85], v[168:171], v[192:195], v[82:85]
	v_mfma_f32_16x16x32_bf16 v[70:73], v[160:163], v[214:217], v[70:73]
	v_mfma_f32_16x16x32_bf16 v[66:69], v[168:171], v[214:217], v[66:69]
	v_mfma_f32_16x16x32_bf16 v[118:121], v[164:167], v[180:183], v[118:121]
	v_mfma_f32_16x16x32_bf16 v[114:117], v[172:175], v[180:183], v[114:117]
	v_mfma_f32_16x16x32_bf16 v[102:105], v[164:167], v[188:191], v[102:105]
	v_mfma_f32_16x16x32_bf16 v[98:101], v[172:175], v[188:191], v[98:101]
	v_mfma_f32_16x16x32_bf16 v[86:89], v[164:167], v[210:213], v[86:89]
	v_mfma_f32_16x16x32_bf16 v[82:85], v[172:175], v[210:213], v[82:85]
	v_mfma_f32_16x16x32_bf16 v[70:73], v[164:167], v[218:221], v[70:73]
	v_mfma_f32_16x16x32_bf16 v[66:69], v[172:175], v[218:221], v[66:69]
	s_setprio 0
	s_barrier
	s_add_i32 s25, s72, s31
	v_lshl_add_u64 v[222:223], s[18:19], 0, v[64:65]
	s_mov_b32 m0, s25
	ds_read_b128 v[176:179], v143 offset:16384
	ds_read_b128 v[180:183], v143 offset:17408
	ds_read_b128 v[184:187], v143 offset:18432
	ds_read_b128 v[188:191], v143 offset:19456
	ds_read_b128 v[192:195], v143 offset:20480
	ds_read_b128 v[210:213], v143 offset:21504
	ds_read_b128 v[214:217], v143 offset:22528
	ds_read_b128 v[218:221], v143 offset:23552
	global_load_lds_dwordx4 v[222:223], off
	s_add_i32 m0, s25, 0x2000
	s_add_u32 s60, s18, 0x10000
	v_lshl_add_u64 v[230:231], s[18:19], 0, v[136:137]
	s_addc_u32 s61, s19, 0
	s_add_i32 s25, s73, s31
	global_load_lds_dwordx4 v[230:231], off
	v_lshl_add_u64 v[232:233], s[60:61], 0, v[64:65]
	s_mov_b32 m0, s25
	v_lshl_add_u64 v[242:243], s[20:21], 0, v[134:135]
	global_load_lds_dwordx4 v[232:233], off
	v_lshl_add_u64 v[232:233], s[60:61], 0, v[136:137]
	s_add_i32 m0, s25, 0x2000
	s_nop 0
	global_load_lds_dwordx4 v[232:233], off
	v_lshl_add_u64 v[232:233], s[20:21], 0, v[132:133]
	s_mov_b32 m0, s34
	s_nop 0
	global_load_lds_dwordx4 v[232:233], off
	s_mov_b32 m0, s38
	s_nop 0
	global_load_lds_dwordx4 v[242:243], off
	s_waitcnt vmcnt(8)
	s_waitcnt lgkmcnt(0)
	s_barrier
; #define PG8_STAGE(bufoff, gbase, voff) do { _Pragma("unroll") for (int _i = 0; _i < 2; ++_i) \
;         __builtin_amdgcn_global_load_lds((const unsigned*)((const char*)(gbase) + (voff)[_i]), (PG8_LAS unsigned*)(lds + (bufoff) + ldsw + _i * 8192), 16, 0, 0); } while (0)
; #define PG8_LDA(dst, b, h) do { _Pragma("unroll") for (int m = 0; m < 4; ++m) _Pragma("unroll") for (int k = 0; k < 2; ++k) dst[m][k] = *(const PG8_LAS bf16x8*)(lds + PG8_SA(b, h) + aoff + m * 2048 + k * 1024); } while (0)
; #define PG8_LDB(dst, b, h) do { _Pragma("unroll") for (int n = 0; n < 2; ++n) _Pragma("unroll") for (int k = 0; k < 2; ++k) dst[n][k] = *(const PG8_LAS bf16x8*)(lds + PG8_SB(b, h) + boff + n * 2048 + k * 1024); } while (0)
; #define PG8_MMA(ai, bj, At, Bt) do { __builtin_amdgcn_s_setprio(1); _Pragma("unroll") for (int m = 0; m < 4; ++m) _Pragma("unroll") for (int n = 0; n < 2; ++n) _Pragma("unroll") for (int k = 0; k < 2; ++k) \
;         acc[ai][bj][m][n] = __builtin_amdgcn_mfma_f32_16x16x32_bf16(Bt[n][k], At[m][k], acc[ai][bj][m][n], 0, 0, 0); __builtin_amdgcn_s_setprio(0); } while (0)
; #define PG8_WAIT_V(n) asm volatile("s_waitcnt vmcnt(" #n ")" ::: "memory")
; #define PG8_WAIT_L(n) asm volatile("s_waitcnt lgkmcnt(" #n ")" ::: "memory")
; #define PG8_BAR __builtin_amdgcn_s_barrier()
; #define PG8_SCHED __builtin_amdgcn_sched_barrier(0)
; template <class Epi, class Sched, bool ALIGN_EPI = false, bool SP2 = false>
; __device__ __forceinline__ void gemm_phase(PG8_LAS unsigned char* lds, const Gemm g, const Sched& S, const Epi& E) {
;     ...
;             PG8_WAIT_V(8); PG8_WAIT_L(0); PG8_BAR; PG8_MMA(1, 0, At, B0); PG8_MMA(1, 1, At, B1); PG8_BAR; PG8_SCHED;
;             PG8_LDB(B0, 1, 0); PG8_LDB(B1, 1, 1); PG8_SCHED; PG8_LDA(At, 1, 0); PG8_STAGE(PG8_SA(0, 1), a2 + hstepA, voffA);
;             PG8_WAIT_V(8); PG8_WAIT_L(0); PG8_BAR; PG8_MMA(0, 0, At, B0); PG8_MMA(0, 1, At, B1); PG8_BAR; PG8_SCHED;
	s_setprio 1
	v_mfma_f32_16x16x32_bf16 v[60:63], v[144:147], v[176:179], v[60:63]
	v_mfma_f32_16x16x32_bf16 v[56:59], v[152:155], v[176:179], v[56:59]
	v_mfma_f32_16x16x32_bf16 v[44:47], v[144:147], v[184:187], v[44:47]
	v_mfma_f32_16x16x32_bf16 v[40:43], v[152:155], v[184:187], v[40:43]
	v_mfma_f32_16x16x32_bf16 v[28:31], v[144:147], v[192:195], v[28:31]
	v_mfma_f32_16x16x32_bf16 v[24:27], v[152:155], v[192:195], v[24:27]
	v_mfma_f32_16x16x32_bf16 v[12:15], v[144:147], v[214:217], v[12:15]
	v_mfma_f32_16x16x32_bf16 v[8:11], v[152:155], v[214:217], v[8:11]
	v_mfma_f32_16x16x32_bf16 v[60:63], v[148:151], v[180:183], v[60:63]
	v_mfma_f32_16x16x32_bf16 v[56:59], v[156:159], v[180:183], v[56:59]
	v_mfma_f32_16x16x32_bf16 v[44:47], v[148:151], v[188:191], v[44:47]
	v_mfma_f32_16x16x32_bf16 v[40:43], v[156:159], v[188:191], v[40:43]
	v_mfma_f32_16x16x32_bf16 v[28:31], v[148:151], v[210:213], v[28:31]
	v_mfma_f32_16x16x32_bf16 v[24:27], v[156:159], v[210:213], v[24:27]
	v_mfma_f32_16x16x32_bf16 v[12:15], v[148:151], v[218:221], v[12:15]
	v_mfma_f32_16x16x32_bf16 v[8:11], v[156:159], v[218:221], v[8:11]
	s_setprio 0
	s_setprio 1
	v_mfma_f32_16x16x32_bf16 v[52:55], v[160:163], v[176:179], v[52:55]
	v_mfma_f32_16x16x32_bf16 v[48:51], v[168:171], v[176:179], v[48:51]
	v_mfma_f32_16x16x32_bf16 v[36:39], v[160:163], v[184:187], v[36:39]
	v_mfma_f32_16x16x32_bf16 v[32:35], v[168:171], v[184:187], v[32:35]
	v_mfma_f32_16x16x32_bf16 v[20:23], v[160:163], v[192:195], v[20:23]
	v_mfma_f32_16x16x32_bf16 v[16:19], v[168:171], v[192:195], v[16:19]
	v_mfma_f32_16x16x32_bf16 v[4:7], v[160:163], v[214:217], v[4:7]
	v_mfma_f32_16x16x32_bf16 v[0:3], v[168:171], v[214:217], v[0:3]
	v_mfma_f32_16x16x32_bf16 v[52:55], v[164:167], v[180:183], v[52:55]
	v_mfma_f32_16x16x32_bf16 v[48:51], v[172:175], v[180:183], v[48:51]
	v_mfma_f32_16x16x32_bf16 v[36:39], v[164:167], v[188:191], v[36:39]
	v_mfma_f32_16x16x32_bf16 v[32:35], v[172:175], v[188:191], v[32:35]
	v_mfma_f32_16x16x32_bf16 v[20:23], v[164:167], v[210:213], v[20:23]
	v_mfma_f32_16x16x32_bf16 v[16:19], v[172:175], v[210:213], v[16:19]
	v_mfma_f32_16x16x32_bf16 v[4:7], v[164:167], v[218:221], v[4:7]
	v_mfma_f32_16x16x32_bf16 v[0:3], v[172:175], v[218:221], v[0:3]
	s_setprio 0
	s_barrier
	v_add_u32_e32 v156, s80, v131
	v_add_u32_e32 v172, s81, v131
	ds_read_b128 v[144:147], v156
	ds_read_b128 v[148:151], v156 offset:1024
	ds_read_b128 v[152:155], v156 offset:2048
	ds_read_b128 v[156:159], v156 offset:3072
	ds_read_b128 v[160:163], v172
	ds_read_b128 v[164:167], v172 offset:1024
	ds_read_b128 v[168:171], v172 offset:2048
	ds_read_b128 v[172:175], v172 offset:3072
	s_add_u32 s20, s20, 0x10000
	s_addc_u32 s21, s21, 0
	s_mov_b32 m0, s39
	v_lshl_add_u64 v[244:245], s[20:21], 0, v[132:133]
	ds_read_b128 v[176:179], v143 offset:32768
	ds_read_b128 v[180:183], v143 offset:33792
	ds_read_b128 v[184:187], v143 offset:34816
	ds_read_b128 v[188:191], v143 offset:35840
	ds_read_b128 v[192:195], v143 offset:36864
	ds_read_b128 v[210:213], v143 offset:37888
	ds_read_b128 v[214:217], v143 offset:38912
	ds_read_b128 v[218:221], v143 offset:39936
	global_load_lds_dwordx4 v[244:245], off
	v_lshl_add_u64 v[244:245], s[20:21], 0, v[134:135]
	s_mov_b32 m0, s43
	s_nop 0
	global_load_lds_dwordx4 v[244:245], off
	s_waitcnt vmcnt(8)
	s_waitcnt lgkmcnt(0)
	s_barrier
	s_setprio 1
	v_mfma_f32_16x16x32_bf16 v[122:125], v[144:147], v[176:179], v[122:125]
	v_mfma_f32_16x16x32_bf16 v[126:129], v[152:155], v[176:179], v[126:129]
	v_mfma_f32_16x16x32_bf16 v[110:113], v[144:147], v[184:187], v[110:113]
	v_mfma_f32_16x16x32_bf16 v[106:109], v[152:155], v[184:187], v[106:109]
	v_mfma_f32_16x16x32_bf16 v[94:97], v[144:147], v[192:195], v[94:97]
	v_mfma_f32_16x16x32_bf16 v[90:93], v[152:155], v[192:195], v[90:93]
	v_mfma_f32_16x16x32_bf16 v[78:81], v[144:147], v[214:217], v[78:81]
	v_mfma_f32_16x16x32_bf16 v[74:77], v[152:155], v[214:217], v[74:77]
	v_mfma_f32_16x16x32_bf16 v[122:125], v[148:151], v[180:183], v[122:125]
	v_mfma_f32_16x16x32_bf16 v[126:129], v[156:159], v[180:183], v[126:129]
	v_mfma_f32_16x16x32_bf16 v[110:113], v[148:151], v[188:191], v[110:113]
	v_mfma_f32_16x16x32_bf16 v[106:109], v[156:159], v[188:191], v[106:109]
	v_mfma_f32_16x16x32_bf16 v[94:97], v[148:151], v[210:213], v[94:97]
	v_mfma_f32_16x16x32_bf16 v[90:93], v[156:159], v[210:213], v[90:93]
	v_mfma_f32_16x16x32_bf16 v[78:81], v[148:151], v[218:221], v[78:81]
	v_mfma_f32_16x16x32_bf16 v[74:77], v[156:159], v[218:221], v[74:77]
	s_setprio 0
	s_setprio 1
	v_mfma_f32_16x16x32_bf16 v[118:121], v[160:163], v[176:179], v[118:121]
	v_mfma_f32_16x16x32_bf16 v[114:117], v[168:171], v[176:179], v[114:117]
	v_mfma_f32_16x16x32_bf16 v[102:105], v[160:163], v[184:187], v[102:105]
	v_mfma_f32_16x16x32_bf16 v[98:101], v[168:171], v[184:187], v[98:101]
	v_mfma_f32_16x16x32_bf16 v[86:89], v[160:163], v[192:195], v[86:89]
	v_mfma_f32_16x16x32_bf16 v[82:85], v[168:171], v[192:195], v[82:85]
	v_mfma_f32_16x16x32_bf16 v[70:73], v[160:163], v[214:217], v[70:73]
	v_mfma_f32_16x16x32_bf16 v[66:69], v[168:171], v[214:217], v[66:69]
	v_mfma_f32_16x16x32_bf16 v[118:121], v[164:167], v[180:183], v[118:121]
	v_mfma_f32_16x16x32_bf16 v[114:117], v[172:175], v[180:183], v[114:117]
	v_mfma_f32_16x16x32_bf16 v[102:105], v[164:167], v[188:191], v[102:105]
	v_mfma_f32_16x16x32_bf16 v[98:101], v[172:175], v[188:191], v[98:101]
	v_mfma_f32_16x16x32_bf16 v[86:89], v[164:167], v[210:213], v[86:89]
	v_mfma_f32_16x16x32_bf16 v[82:85], v[172:175], v[210:213], v[82:85]
	v_mfma_f32_16x16x32_bf16 v[70:73], v[164:167], v[218:221], v[70:73]
	v_mfma_f32_16x16x32_bf16 v[66:69], v[172:175], v[218:221], v[66:69]
	s_setprio 0
	s_barrier
; #define PG8_STAGE(bufoff, gbase, voff) do { _Pragma("unroll") for (int _i = 0; _i < 2; ++_i) \
;         __builtin_amdgcn_global_load_lds((const unsigned*)((const char*)(gbase) + (voff)[_i]), (PG8_LAS unsigned*)(lds + (bufoff) + ldsw + _i * 8192), 16, 0, 0); } while (0)
; #define PG8_LDA(dst, b, h) do { _Pragma("unroll") for (int m = 0; m < 4; ++m) _Pragma("unroll") for (int k = 0; k < 2; ++k) dst[m][k] = *(const PG8_LAS bf16x8*)(lds + PG8_SA(b, h) + aoff + m * 2048 + k * 1024); } while (0)
; #define PG8_MMA(ai, bj, At, Bt) do { __builtin_amdgcn_s_setprio(1); _Pragma("unroll") for (int m = 0; m < 4; ++m) _Pragma("unroll") for (int n = 0; n < 2; ++n) _Pragma("unroll") for (int k = 0; k < 2; ++k) \
;         acc[ai][bj][m][n] = __builtin_amdgcn_mfma_f32_16x16x32_bf16(Bt[n][k], At[m][k], acc[ai][bj][m][n], 0, 0, 0); __builtin_amdgcn_s_setprio(0); } while (0)
; #define PG8_WAIT_V(n) asm volatile("s_waitcnt vmcnt(" #n ")" ::: "memory")
; #define PG8_WAIT_L(n) asm volatile("s_waitcnt lgkmcnt(" #n ")" ::: "memory")
; #define PG8_BAR __builtin_amdgcn_s_barrier()
; #define PG8_SCHED __builtin_amdgcn_sched_barrier(0)
; template <class Epi, class Sched, bool ALIGN_EPI = false, bool SP2 = false>
; __device__ __forceinline__ void gemm_phase(PG8_LAS unsigned char* lds, const Gemm g, const Sched& S, const Epi& E) {
;     ...
;             PG8_LDA(At, 1, 1); PG8_STAGE(PG8_SB(1, 0), b3, voffB); PG8_STAGE(PG8_SB(1, 1), b3 + hstepB, voffB); PG8_STAGE(PG8_SA(1, 0), a3, voffA);
;             PG8_WAIT_V(8); PG8_WAIT_L(0); PG8_BAR; PG8_MMA(1, 0, At, B0); PG8_MMA(1, 1, At, B1); PG8_BAR; PG8_SCHED;
	s_add_i32 s20, s80, s31
	v_lshl_add_u64 v[222:223], v[222:223], 0, s[48:49]
	s_mov_b32 m0, s20
	ds_read_b128 v[176:179], v143 offset:49152
	ds_read_b128 v[180:183], v143 offset:50176
	ds_read_b128 v[184:187], v143 offset:51200
	ds_read_b128 v[188:191], v143 offset:52224
	ds_read_b128 v[192:195], v143 offset:53248
	ds_read_b128 v[210:213], v143 offset:54272
	ds_read_b128 v[214:217], v143 offset:55296
	ds_read_b128 v[218:221], v143 offset:56320
	global_load_lds_dwordx4 v[222:223], off
	s_add_i32 m0, s20, 0x2000
	s_add_u32 s18, s18, 0x10080
	v_lshl_add_u64 v[222:223], v[230:231], 0, s[48:49]
	s_addc_u32 s19, s19, 0
	s_add_i32 s20, s81, s31
	global_load_lds_dwordx4 v[222:223], off
	v_lshl_add_u64 v[222:223], s[18:19], 0, v[64:65]
	s_mov_b32 m0, s20
	s_nop 0
	global_load_lds_dwordx4 v[222:223], off
	v_lshl_add_u64 v[222:223], s[18:19], 0, v[136:137]
	s_add_i32 m0, s20, 0x2000
	s_nop 0
	global_load_lds_dwordx4 v[222:223], off
	v_lshl_add_u64 v[222:223], v[232:233], 0, s[48:49]
	s_mov_b32 m0, s84
	s_nop 0
	global_load_lds_dwordx4 v[222:223], off
	v_lshl_add_u64 v[222:223], v[242:243], 0, s[48:49]
	s_mov_b32 m0, s85
	s_nop 0
	global_load_lds_dwordx4 v[222:223], off
	s_waitcnt vmcnt(8)
	s_waitcnt lgkmcnt(0)
	s_barrier
	s_setprio 1
	v_mfma_f32_16x16x32_bf16 v[60:63], v[144:147], v[176:179], v[60:63]
	v_mfma_f32_16x16x32_bf16 v[56:59], v[152:155], v[176:179], v[56:59]
	v_mfma_f32_16x16x32_bf16 v[44:47], v[144:147], v[184:187], v[44:47]
	v_mfma_f32_16x16x32_bf16 v[40:43], v[152:155], v[184:187], v[40:43]
	v_mfma_f32_16x16x32_bf16 v[28:31], v[144:147], v[192:195], v[28:31]
	v_mfma_f32_16x16x32_bf16 v[24:27], v[152:155], v[192:195], v[24:27]
	v_mfma_f32_16x16x32_bf16 v[12:15], v[144:147], v[214:217], v[12:15]
	v_mfma_f32_16x16x32_bf16 v[8:11], v[152:155], v[214:217], v[8:11]
	v_mfma_f32_16x16x32_bf16 v[60:63], v[148:151], v[180:183], v[60:63]
	v_mfma_f32_16x16x32_bf16 v[56:59], v[156:159], v[180:183], v[56:59]
	v_mfma_f32_16x16x32_bf16 v[44:47], v[148:151], v[188:191], v[44:47]
	v_mfma_f32_16x16x32_bf16 v[40:43], v[156:159], v[188:191], v[40:43]
	v_mfma_f32_16x16x32_bf16 v[28:31], v[148:151], v[210:213], v[28:31]
	v_mfma_f32_16x16x32_bf16 v[24:27], v[156:159], v[210:213], v[24:27]
	v_mfma_f32_16x16x32_bf16 v[12:15], v[148:151], v[218:221], v[12:15]
	v_mfma_f32_16x16x32_bf16 v[8:11], v[156:159], v[218:221], v[8:11]
	s_setprio 0
	s_setprio 1
	v_mfma_f32_16x16x32_bf16 v[52:55], v[160:163], v[176:179], v[52:55]
	v_mfma_f32_16x16x32_bf16 v[48:51], v[168:171], v[176:179], v[48:51]
	v_mfma_f32_16x16x32_bf16 v[36:39], v[160:163], v[184:187], v[36:39]
	v_mfma_f32_16x16x32_bf16 v[32:35], v[168:171], v[184:187], v[32:35]
	v_mfma_f32_16x16x32_bf16 v[20:23], v[160:163], v[192:195], v[20:23]
	v_mfma_f32_16x16x32_bf16 v[16:19], v[168:171], v[192:195], v[16:19]
	v_mfma_f32_16x16x32_bf16 v[4:7], v[160:163], v[214:217], v[4:7]
	v_mfma_f32_16x16x32_bf16 v[0:3], v[168:171], v[214:217], v[0:3]
	v_mfma_f32_16x16x32_bf16 v[52:55], v[164:167], v[180:183], v[52:55]
	v_mfma_f32_16x16x32_bf16 v[48:51], v[172:175], v[180:183], v[48:51]
	v_mfma_f32_16x16x32_bf16 v[36:39], v[164:167], v[188:191], v[36:39]
	v_mfma_f32_16x16x32_bf16 v[32:35], v[172:175], v[188:191], v[32:35]
	v_mfma_f32_16x16x32_bf16 v[20:23], v[164:167], v[210:213], v[20:23]
	v_mfma_f32_16x16x32_bf16 v[16:19], v[172:175], v[210:213], v[16:19]
	v_mfma_f32_16x16x32_bf16 v[4:7], v[164:167], v[218:221], v[4:7]
	v_mfma_f32_16x16x32_bf16 v[0:3], v[172:175], v[218:221], v[0:3]
	s_setprio 0
	s_barrier
	s_add_u32 s16, s16, 0x100
	s_addc_u32 s17, s17, 0
	s_cmp_ge_i32 s24, s87
	s_mov_b32 s18, s24
	s_cbranch_scc0 .LBB0_1297

; #define PG8_STAGE(bufoff, gbase, voff) do { _Pragma("unroll") for (int _i = 0; _i < 2; ++_i) \
;         __builtin_amdgcn_global_load_lds((const unsigned*)((const char*)(gbase) + (voff)[_i]), (PG8_LAS unsigned*)(lds + (bufoff) + ldsw + _i * 8192), 16, 0, 0); } while (0)
; #define PG8_LDA(dst, b, h) do { _Pragma("unroll") for (int m = 0; m < 4; ++m) _Pragma("unroll") for (int k = 0; k < 2; ++k) dst[m][k] = *(const PG8_LAS bf16x8*)(lds + PG8_SA(b, h) + aoff + m * 2048 + k * 1024); } while (0)
; #define PG8_LDB(dst, b, h) do { _Pragma("unroll") for (int n = 0; n < 2; ++n) _Pragma("unroll") for (int k = 0; k < 2; ++k) dst[n][k] = *(const PG8_LAS bf16x8*)(lds + PG8_SB(b, h) + boff + n * 2048 + k * 1024); } while (0)
; #define PG8_MMA(ai, bj, At, Bt) do { __builtin_amdgcn_s_setprio(1); _Pragma("unroll") for (int m = 0; m < 4; ++m) _Pragma("unroll") for (int n = 0; n < 2; ++n) _Pragma("unroll") for (int k = 0; k < 2; ++k) \
;         acc[ai][bj][m][n] = __builtin_amdgcn_mfma_f32_16x16x32_bf16(Bt[n][k], At[m][k], acc[ai][bj][m][n], 0, 0, 0); __builtin_amdgcn_s_setprio(0); } while (0)
; #define PG8_WAIT_V(n) asm volatile("s_waitcnt vmcnt(" #n ")" ::: "memory")
; #define PG8_WAIT_L(n) asm volatile("s_waitcnt lgkmcnt(" #n ")" ::: "memory")
; #define PG8_BAR __builtin_amdgcn_s_barrier()
; #define PG8_SCHED __builtin_amdgcn_sched_barrier(0)
; template <class Epi, class Sched, bool ALIGN_EPI = false, bool SP2 = false>
; __device__ __forceinline__ void gemm_phase(PG8_LAS unsigned char* lds, const Gemm g, const Sched& S, const Epi& E) {
;     ...
;         for (int t = 0; t < nt; t += 2) {
;             const bool last = (t == nt - 2);
;             const char* a1 = cA + (size_t)(t + 1) * kstep;
;             const char* a2 = last ? nA : cA + (size_t)(t + 2) * kstep; const char* b2 = last ? nB : cB + (size_t)(t + 2) * kstep;
;             const char* a3 = a2 + kstep; const char* b3 = b2 + kstep;
;             if (last && has_next) S.a_ready(nxt);
;             if constexpr (SP2) {
;             PG8_LDB(B0, 0, 0); PG8_LDB(B1, 0, 1); PG8_SCHED; PG8_LDA(At, 0, 0); PG8_STAGE(PG8_SA(1, 1), a1 + hstepA, voffA);
;             PG8_WAIT_V(8); PG8_WAIT_L(0); PG8_BAR; PG8_MMA(0, 0, At, B0); PG8_MMA(0, 1, At, B1); PG8_BAR; PG8_SCHED;
;             PG8_LDA(At, 0, 1); PG8_STAGE(PG8_SB(0, 0), b2, voffB); PG8_STAGE(PG8_SB(0, 1), b2 + hstepB, voffB); PG8_STAGE(PG8_SA(0, 0), a2, voffA);
.LBB0_1368:
	s_add_u32 s8, s6, 0xf69c0080
	s_addc_u32 s9, s7, -1
	s_cmp_lg_u32 s43, 12
	s_cselect_b32 s8, s8, 0
	s_cselect_b32 s9, s9, 0
	s_add_u32 s10, s2, s8
	s_addc_u32 s11, s3, s9
	s_add_i32 s41, 0, 0x10000
	s_add_u32 s8, s0, s8
	v_add_u32_e32 v141, s41, v139
	s_addc_u32 s9, s1, s9
	s_add_i32 s60, 0, 0x14000
	ds_read_b128 v[142:145], v141
	ds_read_b128 v[146:149], v141 offset:1024
	ds_read_b128 v[150:153], v141 offset:2048
	ds_read_b128 v[154:157], v141 offset:3072
	v_add_u32_e32 v141, s60, v139
	ds_read_b128 v[158:161], v141
	ds_read_b128 v[162:165], v141 offset:1024
	ds_read_b128 v[166:169], v141 offset:2048
	ds_read_b128 v[170:173], v141 offset:3072
	v_lshl_add_u64 v[222:223], v[132:133], 0, s[6:7]
	s_add_i32 m0, s23, 0xc000
	ds_read_b128 v[174:177], v140
	ds_read_b128 v[180:183], v140 offset:1024
	ds_read_b128 v[184:187], v140 offset:2048
	ds_read_b128 v[188:191], v140 offset:3072
	ds_read_b128 v[192:195], v140 offset:4096
	ds_read_b128 v[210:213], v140 offset:5120
	ds_read_b128 v[214:217], v140 offset:6144
	ds_read_b128 v[218:221], v140 offset:7168
	global_load_lds_dwordx4 v[222:223], off
	v_lshl_add_u64 v[222:223], v[134:135], 0, s[6:7]
	s_add_i32 m0, s23, 0xe000
	s_nop 0
	global_load_lds_dwordx4 v[222:223], off
	s_waitcnt vmcnt(8)
	s_waitcnt lgkmcnt(0)
	s_barrier
	s_setprio 1
	v_mfma_f32_16x16x32_bf16 v[126:129], v[142:145], v[174:177], v[126:129]
	v_mfma_f32_16x16x32_bf16 v[122:125], v[150:153], v[174:177], v[122:125]
	v_mfma_f32_16x16x32_bf16 v[110:113], v[142:145], v[184:187], v[110:113]
	v_mfma_f32_16x16x32_bf16 v[106:109], v[150:153], v[184:187], v[106:109]
	v_mfma_f32_16x16x32_bf16 v[94:97], v[142:145], v[192:195], v[94:97]
	v_mfma_f32_16x16x32_bf16 v[90:93], v[150:153], v[192:195], v[90:93]
	v_mfma_f32_16x16x32_bf16 v[78:81], v[142:145], v[214:217], v[78:81]
	v_mfma_f32_16x16x32_bf16 v[74:77], v[150:153], v[214:217], v[74:77]
	v_mfma_f32_16x16x32_bf16 v[126:129], v[146:149], v[180:183], v[126:129]
	v_mfma_f32_16x16x32_bf16 v[122:125], v[154:157], v[180:183], v[122:125]
	v_mfma_f32_16x16x32_bf16 v[110:113], v[146:149], v[188:191], v[110:113]
	v_mfma_f32_16x16x32_bf16 v[106:109], v[154:157], v[188:191], v[106:109]
	v_mfma_f32_16x16x32_bf16 v[94:97], v[146:149], v[210:213], v[94:97]
	v_mfma_f32_16x16x32_bf16 v[90:93], v[154:157], v[210:213], v[90:93]
	v_mfma_f32_16x16x32_bf16 v[78:81], v[146:149], v[218:221], v[78:81]
	v_mfma_f32_16x16x32_bf16 v[74:77], v[154:157], v[218:221], v[74:77]
	s_setprio 0
	s_setprio 1
	v_mfma_f32_16x16x32_bf16 v[118:121], v[158:161], v[174:177], v[118:121]
	v_mfma_f32_16x16x32_bf16 v[114:117], v[166:169], v[174:177], v[114:117]
	v_mfma_f32_16x16x32_bf16 v[102:105], v[158:161], v[184:187], v[102:105]
	v_mfma_f32_16x16x32_bf16 v[98:101], v[166:169], v[184:187], v[98:101]
	v_mfma_f32_16x16x32_bf16 v[86:89], v[158:161], v[192:195], v[86:89]
	v_mfma_f32_16x16x32_bf16 v[82:85], v[166:169], v[192:195], v[82:85]
	v_mfma_f32_16x16x32_bf16 v[70:73], v[158:161], v[214:217], v[70:73]
	v_mfma_f32_16x16x32_bf16 v[66:69], v[166:169], v[214:217], v[66:69]
	v_mfma_f32_16x16x32_bf16 v[118:121], v[162:165], v[180:183], v[118:121]
	v_mfma_f32_16x16x32_bf16 v[114:117], v[170:173], v[180:183], v[114:117]
	v_mfma_f32_16x16x32_bf16 v[102:105], v[162:165], v[188:191], v[102:105]
	v_mfma_f32_16x16x32_bf16 v[98:101], v[170:173], v[188:191], v[98:101]
	v_mfma_f32_16x16x32_bf16 v[86:89], v[162:165], v[210:213], v[86:89]
	v_mfma_f32_16x16x32_bf16 v[82:85], v[170:173], v[210:213], v[82:85]
	v_mfma_f32_16x16x32_bf16 v[70:73], v[162:165], v[218:221], v[70:73]
	v_mfma_f32_16x16x32_bf16 v[66:69], v[170:173], v[218:221], v[66:69]
	s_setprio 0
	s_barrier
	s_add_i32 s41, s41, s22
	v_lshl_add_u64 v[222:223], s[8:9], 0, v[64:65]
	s_mov_b32 m0, s41
	ds_read_b128 v[174:177], v140 offset:16384
	ds_read_b128 v[180:183], v140 offset:17408
	ds_read_b128 v[184:187], v140 offset:18432
	ds_read_b128 v[188:191], v140 offset:19456
	ds_read_b128 v[192:195], v140 offset:20480
	ds_read_b128 v[210:213], v140 offset:21504
	ds_read_b128 v[214:217], v140 offset:22528
	ds_read_b128 v[218:221], v140 offset:23552
	global_load_lds_dwordx4 v[222:223], off
	s_add_i32 m0, s41, 0x2000
	s_add_u32 s44, s8, 0x40000
	v_lshl_add_u64 v[230:231], s[8:9], 0, v[130:131]
	s_addc_u32 s45, s9, 0
	s_add_i32 s41, s60, s22
	global_load_lds_dwordx4 v[230:231], off
	v_lshl_add_u64 v[232:233], s[44:45], 0, v[64:65]
	s_mov_b32 m0, s41
	v_lshl_add_u64 v[242:243], s[10:11], 0, v[130:131]
	global_load_lds_dwordx4 v[232:233], off
	v_lshl_add_u64 v[232:233], s[44:45], 0, v[130:131]
	s_add_i32 m0, s41, 0x2000
	s_nop 0
	global_load_lds_dwordx4 v[232:233], off
	v_lshl_add_u64 v[232:233], s[10:11], 0, v[64:65]
	s_mov_b32 m0, s23
	s_nop 0
	global_load_lds_dwordx4 v[232:233], off
	s_mov_b32 m0, s25
	s_nop 0
	global_load_lds_dwordx4 v[242:243], off
	s_waitcnt vmcnt(8)
	s_waitcnt lgkmcnt(0)
	s_barrier
; #define PG8_STAGE(bufoff, gbase, voff) do { _Pragma("unroll") for (int _i = 0; _i < 2; ++_i) \
;         __builtin_amdgcn_global_load_lds((const unsigned*)((const char*)(gbase) + (voff)[_i]), (PG8_LAS unsigned*)(lds + (bufoff) + ldsw + _i * 8192), 16, 0, 0); } while (0)
; #define PG8_LDA(dst, b, h) do { _Pragma("unroll") for (int m = 0; m < 4; ++m) _Pragma("unroll") for (int k = 0; k < 2; ++k) dst[m][k] = *(const PG8_LAS bf16x8*)(lds + PG8_SA(b, h) + aoff + m * 2048 + k * 1024); } while (0)
; #define PG8_LDB(dst, b, h) do { _Pragma("unroll") for (int n = 0; n < 2; ++n) _Pragma("unroll") for (int k = 0; k < 2; ++k) dst[n][k] = *(const PG8_LAS bf16x8*)(lds + PG8_SB(b, h) + boff + n * 2048 + k * 1024); } while (0)
; #define PG8_MMA(ai, bj, At, Bt) do { __builtin_amdgcn_s_setprio(1); _Pragma("unroll") for (int m = 0; m < 4; ++m) _Pragma("unroll") for (int n = 0; n < 2; ++n) _Pragma("unroll") for (int k = 0; k < 2; ++k) \
;         acc[ai][bj][m][n] = __builtin_amdgcn_mfma_f32_16x16x32_bf16(Bt[n][k], At[m][k], acc[ai][bj][m][n], 0, 0, 0); __builtin_amdgcn_s_setprio(0); } while (0)
; #define PG8_WAIT_V(n) asm volatile("s_waitcnt vmcnt(" #n ")" ::: "memory")
; #define PG8_WAIT_L(n) asm volatile("s_waitcnt lgkmcnt(" #n ")" ::: "memory")
; #define PG8_BAR __builtin_amdgcn_s_barrier()
; #define PG8_SCHED __builtin_amdgcn_sched_barrier(0)
; template <class Epi, class Sched, bool ALIGN_EPI = false, bool SP2 = false>
; __device__ __forceinline__ void gemm_phase(PG8_LAS unsigned char* lds, const Gemm g, const Sched& S, const Epi& E) {
;     ...
;             PG8_WAIT_V(8); PG8_WAIT_L(0); PG8_BAR; PG8_MMA(1, 0, At, B0); PG8_MMA(1, 1, At, B1); PG8_BAR; PG8_SCHED;
;             PG8_LDB(B0, 1, 0); PG8_LDB(B1, 1, 1); PG8_SCHED; PG8_LDA(At, 1, 0); PG8_STAGE(PG8_SA(0, 1), a2 + hstepA, voffA);
;             PG8_WAIT_V(8); PG8_WAIT_L(0); PG8_BAR; PG8_MMA(0, 0, At, B0); PG8_MMA(0, 1, At, B1); PG8_BAR; PG8_SCHED;
	s_setprio 1
	v_mfma_f32_16x16x32_bf16 v[60:63], v[142:145], v[174:177], v[60:63]
	v_mfma_f32_16x16x32_bf16 v[56:59], v[150:153], v[174:177], v[56:59]
	v_mfma_f32_16x16x32_bf16 v[44:47], v[142:145], v[184:187], v[44:47]
	v_mfma_f32_16x16x32_bf16 v[40:43], v[150:153], v[184:187], v[40:43]
	v_mfma_f32_16x16x32_bf16 v[28:31], v[142:145], v[192:195], v[28:31]
	v_mfma_f32_16x16x32_bf16 v[24:27], v[150:153], v[192:195], v[24:27]
	v_mfma_f32_16x16x32_bf16 v[12:15], v[142:145], v[214:217], v[12:15]
	v_mfma_f32_16x16x32_bf16 v[8:11], v[150:153], v[214:217], v[8:11]
	v_mfma_f32_16x16x32_bf16 v[60:63], v[146:149], v[180:183], v[60:63]
	v_mfma_f32_16x16x32_bf16 v[56:59], v[154:157], v[180:183], v[56:59]
	v_mfma_f32_16x16x32_bf16 v[44:47], v[146:149], v[188:191], v[44:47]
	v_mfma_f32_16x16x32_bf16 v[40:43], v[154:157], v[188:191], v[40:43]
	v_mfma_f32_16x16x32_bf16 v[28:31], v[146:149], v[210:213], v[28:31]
	v_mfma_f32_16x16x32_bf16 v[24:27], v[154:157], v[210:213], v[24:27]
	v_mfma_f32_16x16x32_bf16 v[12:15], v[146:149], v[218:221], v[12:15]
	v_mfma_f32_16x16x32_bf16 v[8:11], v[154:157], v[218:221], v[8:11]
	s_setprio 0
	s_setprio 1
	v_mfma_f32_16x16x32_bf16 v[52:55], v[158:161], v[174:177], v[52:55]
	v_mfma_f32_16x16x32_bf16 v[48:51], v[166:169], v[174:177], v[48:51]
	v_mfma_f32_16x16x32_bf16 v[36:39], v[158:161], v[184:187], v[36:39]
	v_mfma_f32_16x16x32_bf16 v[32:35], v[166:169], v[184:187], v[32:35]
	v_mfma_f32_16x16x32_bf16 v[20:23], v[158:161], v[192:195], v[20:23]
	v_mfma_f32_16x16x32_bf16 v[16:19], v[166:169], v[192:195], v[16:19]
	v_mfma_f32_16x16x32_bf16 v[4:7], v[158:161], v[214:217], v[4:7]
	v_mfma_f32_16x16x32_bf16 v[0:3], v[166:169], v[214:217], v[0:3]
	v_mfma_f32_16x16x32_bf16 v[52:55], v[162:165], v[180:183], v[52:55]
	v_mfma_f32_16x16x32_bf16 v[48:51], v[170:173], v[180:183], v[48:51]
	v_mfma_f32_16x16x32_bf16 v[36:39], v[162:165], v[188:191], v[36:39]
	v_mfma_f32_16x16x32_bf16 v[32:35], v[170:173], v[188:191], v[32:35]
	v_mfma_f32_16x16x32_bf16 v[20:23], v[162:165], v[210:213], v[20:23]
	v_mfma_f32_16x16x32_bf16 v[16:19], v[170:173], v[210:213], v[16:19]
	v_mfma_f32_16x16x32_bf16 v[4:7], v[162:165], v[218:221], v[4:7]
	v_mfma_f32_16x16x32_bf16 v[0:3], v[170:173], v[218:221], v[0:3]
	s_setprio 0
	s_barrier
	s_add_i32 s41, 0, 0x18000
	v_add_u32_e32 v141, s41, v139
	s_add_i32 s44, 0, 0x1c000
	ds_read_b128 v[142:145], v141
	ds_read_b128 v[146:149], v141 offset:1024
	ds_read_b128 v[150:153], v141 offset:2048
	ds_read_b128 v[154:157], v141 offset:3072
	v_add_u32_e32 v141, s44, v139
	ds_read_b128 v[158:161], v141
	ds_read_b128 v[162:165], v141 offset:1024
	ds_read_b128 v[166:169], v141 offset:2048
	ds_read_b128 v[170:173], v141 offset:3072
	s_add_u32 s10, s10, 0x40000
	s_addc_u32 s11, s11, 0
	s_mov_b32 m0, s31
	v_lshl_add_u64 v[244:245], s[10:11], 0, v[64:65]
	ds_read_b128 v[174:177], v140 offset:32768
	ds_read_b128 v[180:183], v140 offset:33792
	ds_read_b128 v[184:187], v140 offset:34816
	ds_read_b128 v[188:191], v140 offset:35840
	ds_read_b128 v[192:195], v140 offset:36864
	ds_read_b128 v[210:213], v140 offset:37888
	ds_read_b128 v[214:217], v140 offset:38912
	ds_read_b128 v[218:221], v140 offset:39936
	global_load_lds_dwordx4 v[244:245], off
	v_lshl_add_u64 v[244:245], s[10:11], 0, v[130:131]
	s_mov_b32 m0, s34
	s_nop 0
	global_load_lds_dwordx4 v[244:245], off
	s_waitcnt vmcnt(8)
	s_waitcnt lgkmcnt(0)
	s_barrier
	s_setprio 1
	v_mfma_f32_16x16x32_bf16 v[126:129], v[142:145], v[174:177], v[126:129]
	v_mfma_f32_16x16x32_bf16 v[122:125], v[150:153], v[174:177], v[122:125]
	v_mfma_f32_16x16x32_bf16 v[110:113], v[142:145], v[184:187], v[110:113]
	v_mfma_f32_16x16x32_bf16 v[106:109], v[150:153], v[184:187], v[106:109]
	v_mfma_f32_16x16x32_bf16 v[94:97], v[142:145], v[192:195], v[94:97]
	v_mfma_f32_16x16x32_bf16 v[90:93], v[150:153], v[192:195], v[90:93]
	v_mfma_f32_16x16x32_bf16 v[78:81], v[142:145], v[214:217], v[78:81]
	v_mfma_f32_16x16x32_bf16 v[74:77], v[150:153], v[214:217], v[74:77]
	v_mfma_f32_16x16x32_bf16 v[126:129], v[146:149], v[180:183], v[126:129]
	v_mfma_f32_16x16x32_bf16 v[122:125], v[154:157], v[180:183], v[122:125]
	v_mfma_f32_16x16x32_bf16 v[110:113], v[146:149], v[188:191], v[110:113]
	v_mfma_f32_16x16x32_bf16 v[106:109], v[154:157], v[188:191], v[106:109]
	v_mfma_f32_16x16x32_bf16 v[94:97], v[146:149], v[210:213], v[94:97]
	v_mfma_f32_16x16x32_bf16 v[90:93], v[154:157], v[210:213], v[90:93]
	v_mfma_f32_16x16x32_bf16 v[78:81], v[146:149], v[218:221], v[78:81]
	v_mfma_f32_16x16x32_bf16 v[74:77], v[154:157], v[218:221], v[74:77]
	s_setprio 0
	s_setprio 1
	v_mfma_f32_16x16x32_bf16 v[118:121], v[158:161], v[174:177], v[118:121]
	v_mfma_f32_16x16x32_bf16 v[114:117], v[166:169], v[174:177], v[114:117]
	v_mfma_f32_16x16x32_bf16 v[102:105], v[158:161], v[184:187], v[102:105]
	v_mfma_f32_16x16x32_bf16 v[98:101], v[166:169], v[184:187], v[98:101]
	v_mfma_f32_16x16x32_bf16 v[86:89], v[158:161], v[192:195], v[86:89]
	v_mfma_f32_16x16x32_bf16 v[82:85], v[166:169], v[192:195], v[82:85]
	v_mfma_f32_16x16x32_bf16 v[70:73], v[158:161], v[214:217], v[70:73]
	v_mfma_f32_16x16x32_bf16 v[66:69], v[166:169], v[214:217], v[66:69]
	v_mfma_f32_16x16x32_bf16 v[118:121], v[162:165], v[180:183], v[118:121]
	v_mfma_f32_16x16x32_bf16 v[114:117], v[170:173], v[180:183], v[114:117]
	v_mfma_f32_16x16x32_bf16 v[102:105], v[162:165], v[188:191], v[102:105]
	v_mfma_f32_16x16x32_bf16 v[98:101], v[170:173], v[188:191], v[98:101]
	v_mfma_f32_16x16x32_bf16 v[86:89], v[162:165], v[210:213], v[86:89]
	v_mfma_f32_16x16x32_bf16 v[82:85], v[170:173], v[210:213], v[82:85]
	v_mfma_f32_16x16x32_bf16 v[70:73], v[162:165], v[218:221], v[70:73]
	v_mfma_f32_16x16x32_bf16 v[66:69], v[170:173], v[218:221], v[66:69]
	s_setprio 0
	s_barrier
; #define PG8_STAGE(bufoff, gbase, voff) do { _Pragma("unroll") for (int _i = 0; _i < 2; ++_i) \
;         __builtin_amdgcn_global_load_lds((const unsigned*)((const char*)(gbase) + (voff)[_i]), (PG8_LAS unsigned*)(lds + (bufoff) + ldsw + _i * 8192), 16, 0, 0); } while (0)
; #define PG8_LDA(dst, b, h) do { _Pragma("unroll") for (int m = 0; m < 4; ++m) _Pragma("unroll") for (int k = 0; k < 2; ++k) dst[m][k] = *(const PG8_LAS bf16x8*)(lds + PG8_SA(b, h) + aoff + m * 2048 + k * 1024); } while (0)
; #define PG8_MMA(ai, bj, At, Bt) do { __builtin_amdgcn_s_setprio(1); _Pragma("unroll") for (int m = 0; m < 4; ++m) _Pragma("unroll") for (int n = 0; n < 2; ++n) _Pragma("unroll") for (int k = 0; k < 2; ++k) \
;         acc[ai][bj][m][n] = __builtin_amdgcn_mfma_f32_16x16x32_bf16(Bt[n][k], At[m][k], acc[ai][bj][m][n], 0, 0, 0); __builtin_amdgcn_s_setprio(0); } while (0)
; #define PG8_WAIT_V(n) asm volatile("s_waitcnt vmcnt(" #n ")" ::: "memory")
; #define PG8_WAIT_L(n) asm volatile("s_waitcnt lgkmcnt(" #n ")" ::: "memory")
; #define PG8_BAR __builtin_amdgcn_s_barrier()
; #define PG8_SCHED __builtin_amdgcn_sched_barrier(0)
; template <class Epi, class Sched, bool ALIGN_EPI = false, bool SP2 = false>
; __device__ __forceinline__ void gemm_phase(PG8_LAS unsigned char* lds, const Gemm g, const Sched& S, const Epi& E) {
;     ...
;             PG8_LDA(At, 1, 1); PG8_STAGE(PG8_SB(1, 0), b3, voffB); PG8_STAGE(PG8_SB(1, 1), b3 + hstepB, voffB); PG8_STAGE(PG8_SA(1, 0), a3, voffA);
;             PG8_WAIT_V(8); PG8_WAIT_L(0); PG8_BAR; PG8_MMA(1, 0, At, B0); PG8_MMA(1, 1, At, B1); PG8_BAR; PG8_SCHED;
;     ...
;     PG8_WAIT_V(0);
;     if constexpr (!ALIGN_EPI) { if (wr == 0) PG8_BAR; }
	s_add_i32 s10, s41, s22
	v_lshl_add_u64 v[222:223], v[222:223], 0, s[48:49]
	s_mov_b32 m0, s10
	ds_read_b128 v[174:177], v140 offset:49152
	ds_read_b128 v[180:183], v140 offset:50176
	ds_read_b128 v[184:187], v140 offset:51200
	ds_read_b128 v[188:191], v140 offset:52224
	ds_read_b128 v[192:195], v140 offset:53248
	ds_read_b128 v[210:213], v140 offset:54272
	ds_read_b128 v[214:217], v140 offset:55296
	ds_read_b128 v[218:221], v140 offset:56320
	global_load_lds_dwordx4 v[222:223], off
	s_add_i32 m0, s10, 0x2000
	s_add_u32 s8, s8, 0x40080
	v_lshl_add_u64 v[222:223], v[230:231], 0, s[48:49]
	s_addc_u32 s9, s9, 0
	s_add_i32 s10, s44, s22
	global_load_lds_dwordx4 v[222:223], off
	v_lshl_add_u64 v[222:223], s[8:9], 0, v[64:65]
	s_mov_b32 m0, s10
	s_nop 0
	global_load_lds_dwordx4 v[222:223], off
	v_lshl_add_u64 v[222:223], s[8:9], 0, v[130:131]
	s_add_i32 m0, s10, 0x2000
	s_nop 0
	global_load_lds_dwordx4 v[222:223], off
	v_lshl_add_u64 v[222:223], v[232:233], 0, s[48:49]
	s_mov_b32 m0, s38
	s_nop 0
	global_load_lds_dwordx4 v[222:223], off
	v_lshl_add_u64 v[222:223], v[242:243], 0, s[48:49]
	s_mov_b32 m0, s39
	s_nop 0
	global_load_lds_dwordx4 v[222:223], off
	s_waitcnt vmcnt(8)
	s_waitcnt lgkmcnt(0)
	s_barrier
	s_setprio 1
	v_mfma_f32_16x16x32_bf16 v[60:63], v[142:145], v[174:177], v[60:63]
	v_mfma_f32_16x16x32_bf16 v[56:59], v[150:153], v[174:177], v[56:59]
	v_mfma_f32_16x16x32_bf16 v[44:47], v[142:145], v[184:187], v[44:47]
	v_mfma_f32_16x16x32_bf16 v[40:43], v[150:153], v[184:187], v[40:43]
	v_mfma_f32_16x16x32_bf16 v[28:31], v[142:145], v[192:195], v[28:31]
	v_mfma_f32_16x16x32_bf16 v[24:27], v[150:153], v[192:195], v[24:27]
	v_mfma_f32_16x16x32_bf16 v[12:15], v[142:145], v[214:217], v[12:15]
	v_mfma_f32_16x16x32_bf16 v[8:11], v[150:153], v[214:217], v[8:11]
	v_mfma_f32_16x16x32_bf16 v[60:63], v[146:149], v[180:183], v[60:63]
	v_mfma_f32_16x16x32_bf16 v[56:59], v[154:157], v[180:183], v[56:59]
	v_mfma_f32_16x16x32_bf16 v[44:47], v[146:149], v[188:191], v[44:47]
	v_mfma_f32_16x16x32_bf16 v[40:43], v[154:157], v[188:191], v[40:43]
	v_mfma_f32_16x16x32_bf16 v[28:31], v[146:149], v[210:213], v[28:31]
	v_mfma_f32_16x16x32_bf16 v[24:27], v[154:157], v[210:213], v[24:27]
	v_mfma_f32_16x16x32_bf16 v[12:15], v[146:149], v[218:221], v[12:15]
	v_mfma_f32_16x16x32_bf16 v[8:11], v[154:157], v[218:221], v[8:11]
	s_setprio 0
	s_setprio 1
	v_mfma_f32_16x16x32_bf16 v[52:55], v[158:161], v[174:177], v[52:55]
	v_mfma_f32_16x16x32_bf16 v[48:51], v[166:169], v[174:177], v[48:51]
	v_mfma_f32_16x16x32_bf16 v[36:39], v[158:161], v[184:187], v[36:39]
	v_mfma_f32_16x16x32_bf16 v[32:35], v[166:169], v[184:187], v[32:35]
	v_mfma_f32_16x16x32_bf16 v[20:23], v[158:161], v[192:195], v[20:23]
	v_mfma_f32_16x16x32_bf16 v[16:19], v[166:169], v[192:195], v[16:19]
	v_mfma_f32_16x16x32_bf16 v[4:7], v[158:161], v[214:217], v[4:7]
	v_mfma_f32_16x16x32_bf16 v[0:3], v[166:169], v[214:217], v[0:3]
	v_mfma_f32_16x16x32_bf16 v[52:55], v[162:165], v[180:183], v[52:55]
	v_mfma_f32_16x16x32_bf16 v[48:51], v[170:173], v[180:183], v[48:51]
	v_mfma_f32_16x16x32_bf16 v[36:39], v[162:165], v[188:191], v[36:39]
	v_mfma_f32_16x16x32_bf16 v[32:35], v[170:173], v[188:191], v[32:35]
	v_mfma_f32_16x16x32_bf16 v[20:23], v[162:165], v[210:213], v[20:23]
	v_mfma_f32_16x16x32_bf16 v[16:19], v[170:173], v[210:213], v[16:19]
	v_mfma_f32_16x16x32_bf16 v[4:7], v[162:165], v[218:221], v[4:7]
	v_mfma_f32_16x16x32_bf16 v[0:3], v[170:173], v[218:221], v[0:3]
	s_setprio 0
	s_barrier
	s_add_i32 s43, s43, 2
	s_add_u32 s6, s6, 0x100
	s_addc_u32 s7, s7, 0
	s_cmp_lt_u32 s43, 14
	s_cbranch_scc1 .LBB0_1368
	s_waitcnt vmcnt(0)
	s_cmpk_gt_u32 s21, 0xff
	s_cbranch_scc1 .LBB0_1371
	s_barrier

; #define PG8_STAGE(bufoff, gbase, voff) do { _Pragma("unroll") for (int _i = 0; _i < 2; ++_i) \
;         __builtin_amdgcn_global_load_lds((const unsigned*)((const char*)(gbase) + (voff)[_i]), (PG8_LAS unsigned*)(lds + (bufoff) + ldsw + _i * 8192), 16, 0, 0); } while (0)
; #define PG8_LDA(dst, b, h) do { _Pragma("unroll") for (int m = 0; m < 4; ++m) _Pragma("unroll") for (int k = 0; k < 2; ++k) dst[m][k] = *(const PG8_LAS bf16x8*)(lds + PG8_SA(b, h) + aoff + m * 2048 + k * 1024); } while (0)
; #define PG8_LDB(dst, b, h) do { _Pragma("unroll") for (int n = 0; n < 2; ++n) _Pragma("unroll") for (int k = 0; k < 2; ++k) dst[n][k] = *(const PG8_LAS bf16x8*)(lds + PG8_SB(b, h) + boff + n * 2048 + k * 1024); } while (0)
; #define PG8_MMA(ai, bj, At, Bt) do { __builtin_amdgcn_s_setprio(1); _Pragma("unroll") for (int m = 0; m < 4; ++m) _Pragma("unroll") for (int n = 0; n < 2; ++n) _Pragma("unroll") for (int k = 0; k < 2; ++k) \
;         acc[ai][bj][m][n] = __builtin_amdgcn_mfma_f32_16x16x32_bf16(Bt[n][k], At[m][k], acc[ai][bj][m][n], 0, 0, 0); __builtin_amdgcn_s_setprio(0); } while (0)
; #define PG8_WAIT_V(n) asm volatile("s_waitcnt vmcnt(" #n ")" ::: "memory")
; #define PG8_WAIT_L(n) asm volatile("s_waitcnt lgkmcnt(" #n ")" ::: "memory")
; #define PG8_BAR __builtin_amdgcn_s_barrier()
; #define PG8_SCHED __builtin_amdgcn_sched_barrier(0)
; template <class Epi, class Sched, bool ALIGN_EPI = false, bool SP2 = false>
; __device__ __forceinline__ void gemm_phase(PG8_LAS unsigned char* lds, const Gemm g, const Sched& S, const Epi& E) {
;     ...
;         for (int t = 0; t < nt; t += 2) {
;             const bool last = (t == nt - 2);
;             const char* a1 = cA + (size_t)(t + 1) * kstep;
;             const char* a2 = last ? nA : cA + (size_t)(t + 2) * kstep; const char* b2 = last ? nB : cB + (size_t)(t + 2) * kstep;
;             const char* a3 = a2 + kstep; const char* b3 = b2 + kstep;
;             if (last && has_next) S.a_ready(nxt);
;             if constexpr (SP2) {
;             PG8_LDB(B0, 0, 0); PG8_LDB(B1, 0, 1); PG8_SCHED; PG8_LDA(At, 0, 0); PG8_STAGE(PG8_SA(1, 1), a1 + hstepA, voffA);
;             PG8_WAIT_V(8); PG8_WAIT_L(0); PG8_BAR; PG8_MMA(0, 0, At, B0); PG8_MMA(0, 1, At, B1); PG8_BAR; PG8_SCHED;
;             PG8_LDA(At, 0, 1); PG8_STAGE(PG8_SB(0, 0), b2, voffB); PG8_STAGE(PG8_SB(0, 1), b2 + hstepB, voffB); PG8_STAGE(PG8_SA(0, 0), a2, voffA);
.LBB0_1450:
	s_add_u32 s20, s18, 0xfffc0080
	s_addc_u32 s21, s19, -1
	s_add_i32 s41, 0, 0x10000
	s_cmp_eq_u32 s43, 12
	s_cselect_b32 s31, s13, s21
	s_cselect_b32 s30, s22, s20
	v_add_u32_e32 v64, s41, v175
	s_cselect_b32 s21, s11, s25
	s_cselect_b32 s20, s23, s24
	s_add_i32 s73, 0, 0x14000
	ds_read_b128 v[130:133], v64
	ds_read_b128 v[134:137], v64 offset:1024
	ds_read_b128 v[138:141], v64 offset:2048
	ds_read_b128 v[142:145], v64 offset:3072
	v_add_u32_e32 v64, s73, v175
	ds_read_b128 v[158:161], v64
	ds_read_b128 v[162:165], v64 offset:1024
	ds_read_b128 v[166:169], v64 offset:2048
	ds_read_b128 v[178:181], v64 offset:3072
	v_lshl_add_u64 v[172:173], s[18:19], 0, v[154:155]
	s_add_i32 m0, s63, 0xc000
	ds_read_b128 v[184:187], v183
	ds_read_b128 v[188:191], v183 offset:1024
	ds_read_b128 v[192:195], v183 offset:2048
	ds_read_b128 v[210:213], v183 offset:3072
	ds_read_b128 v[214:217], v183 offset:4096
	ds_read_b128 v[218:221], v183 offset:5120
	ds_read_b128 v[242:245], v183 offset:6144
	ds_read_b128 v[246:249], v183 offset:7168
	global_load_lds_dwordx4 v[172:173], off
	v_lshl_add_u64 v[172:173], s[18:19], 0, v[156:157]
	s_add_i32 m0, s63, 0xe000
	s_nop 0
	global_load_lds_dwordx4 v[172:173], off
	s_waitcnt vmcnt(8)
	s_waitcnt lgkmcnt(0)
	s_barrier
	s_setprio 1
	v_mfma_f32_16x16x32_bf16 v[126:129], v[130:133], v[184:187], v[126:129]
	v_mfma_f32_16x16x32_bf16 v[122:125], v[138:141], v[184:187], v[122:125]
	v_mfma_f32_16x16x32_bf16 v[110:113], v[130:133], v[192:195], v[110:113]
	v_mfma_f32_16x16x32_bf16 v[106:109], v[138:141], v[192:195], v[106:109]
	v_mfma_f32_16x16x32_bf16 v[94:97], v[130:133], v[214:217], v[94:97]
	v_mfma_f32_16x16x32_bf16 v[90:93], v[138:141], v[214:217], v[90:93]
	v_mfma_f32_16x16x32_bf16 v[78:81], v[130:133], v[242:245], v[78:81]
	v_mfma_f32_16x16x32_bf16 v[74:77], v[138:141], v[242:245], v[74:77]
	v_mfma_f32_16x16x32_bf16 v[126:129], v[134:137], v[188:191], v[126:129]
	v_mfma_f32_16x16x32_bf16 v[122:125], v[142:145], v[188:191], v[122:125]
	v_mfma_f32_16x16x32_bf16 v[110:113], v[134:137], v[210:213], v[110:113]
	v_mfma_f32_16x16x32_bf16 v[106:109], v[142:145], v[210:213], v[106:109]
	v_mfma_f32_16x16x32_bf16 v[94:97], v[134:137], v[218:221], v[94:97]
	v_mfma_f32_16x16x32_bf16 v[90:93], v[142:145], v[218:221], v[90:93]
	v_mfma_f32_16x16x32_bf16 v[78:81], v[134:137], v[246:249], v[78:81]
	v_mfma_f32_16x16x32_bf16 v[74:77], v[142:145], v[246:249], v[74:77]
	s_setprio 0
	s_setprio 1
	v_mfma_f32_16x16x32_bf16 v[118:121], v[158:161], v[184:187], v[118:121]
	v_mfma_f32_16x16x32_bf16 v[114:117], v[166:169], v[184:187], v[114:117]
	v_mfma_f32_16x16x32_bf16 v[102:105], v[158:161], v[192:195], v[102:105]
	v_mfma_f32_16x16x32_bf16 v[98:101], v[166:169], v[192:195], v[98:101]
	v_mfma_f32_16x16x32_bf16 v[86:89], v[158:161], v[214:217], v[86:89]
	v_mfma_f32_16x16x32_bf16 v[82:85], v[166:169], v[214:217], v[82:85]
	v_mfma_f32_16x16x32_bf16 v[70:73], v[158:161], v[242:245], v[70:73]
	v_mfma_f32_16x16x32_bf16 v[66:69], v[166:169], v[242:245], v[66:69]
	v_mfma_f32_16x16x32_bf16 v[118:121], v[162:165], v[188:191], v[118:121]
	v_mfma_f32_16x16x32_bf16 v[114:117], v[178:181], v[188:191], v[114:117]
	v_mfma_f32_16x16x32_bf16 v[102:105], v[162:165], v[210:213], v[102:105]
	v_mfma_f32_16x16x32_bf16 v[98:101], v[178:181], v[210:213], v[98:101]
	v_mfma_f32_16x16x32_bf16 v[86:89], v[162:165], v[218:221], v[86:89]
	v_mfma_f32_16x16x32_bf16 v[82:85], v[178:181], v[218:221], v[82:85]
	v_mfma_f32_16x16x32_bf16 v[70:73], v[162:165], v[246:249], v[70:73]
	v_mfma_f32_16x16x32_bf16 v[66:69], v[178:181], v[246:249], v[66:69]
	s_setprio 0
	s_barrier
	s_add_i32 s41, s41, s45
	v_lshl_add_u64 v[172:173], s[20:21], 0, v[150:151]
	s_mov_b32 m0, s41
	ds_read_b128 v[184:187], v183 offset:16384
	ds_read_b128 v[188:191], v183 offset:17408
	ds_read_b128 v[192:195], v183 offset:18432
	ds_read_b128 v[210:213], v183 offset:19456
	ds_read_b128 v[214:217], v183 offset:20480
	ds_read_b128 v[218:221], v183 offset:21504
	ds_read_b128 v[242:245], v183 offset:22528
	ds_read_b128 v[246:249], v183 offset:23552
	global_load_lds_dwordx4 v[172:173], off
	s_add_i32 m0, s41, 0x2000
	s_add_u32 s60, s20, 0x40000
	v_lshl_add_u64 v[222:223], s[20:21], 0, v[146:147]
	s_addc_u32 s61, s21, 0
	s_add_i32 s41, s73, s45
	global_load_lds_dwordx4 v[222:223], off
	v_lshl_add_u64 v[230:231], s[60:61], 0, v[150:151]
	s_mov_b32 m0, s41
	v_lshl_add_u64 v[232:233], s[30:31], 0, v[148:149]
	global_load_lds_dwordx4 v[230:231], off
	v_lshl_add_u64 v[230:231], s[60:61], 0, v[146:147]
	s_add_i32 m0, s41, 0x2000
	s_nop 0
	global_load_lds_dwordx4 v[230:231], off
	v_lshl_add_u64 v[230:231], s[30:31], 0, v[152:153]
	s_mov_b32 m0, s63
	s_nop 0
	global_load_lds_dwordx4 v[230:231], off
	s_mov_b32 m0, s64
	s_nop 0
	global_load_lds_dwordx4 v[232:233], off
	s_waitcnt vmcnt(8)
	s_waitcnt lgkmcnt(0)
	s_barrier
; #define PG8_STAGE(bufoff, gbase, voff) do { _Pragma("unroll") for (int _i = 0; _i < 2; ++_i) \
;         __builtin_amdgcn_global_load_lds((const unsigned*)((const char*)(gbase) + (voff)[_i]), (PG8_LAS unsigned*)(lds + (bufoff) + ldsw + _i * 8192), 16, 0, 0); } while (0)
; #define PG8_LDA(dst, b, h) do { _Pragma("unroll") for (int m = 0; m < 4; ++m) _Pragma("unroll") for (int k = 0; k < 2; ++k) dst[m][k] = *(const PG8_LAS bf16x8*)(lds + PG8_SA(b, h) + aoff + m * 2048 + k * 1024); } while (0)
; #define PG8_LDB(dst, b, h) do { _Pragma("unroll") for (int n = 0; n < 2; ++n) _Pragma("unroll") for (int k = 0; k < 2; ++k) dst[n][k] = *(const PG8_LAS bf16x8*)(lds + PG8_SB(b, h) + boff + n * 2048 + k * 1024); } while (0)
; #define PG8_MMA(ai, bj, At, Bt) do { __builtin_amdgcn_s_setprio(1); _Pragma("unroll") for (int m = 0; m < 4; ++m) _Pragma("unroll") for (int n = 0; n < 2; ++n) _Pragma("unroll") for (int k = 0; k < 2; ++k) \
;         acc[ai][bj][m][n] = __builtin_amdgcn_mfma_f32_16x16x32_bf16(Bt[n][k], At[m][k], acc[ai][bj][m][n], 0, 0, 0); __builtin_amdgcn_s_setprio(0); } while (0)
; #define PG8_WAIT_V(n) asm volatile("s_waitcnt vmcnt(" #n ")" ::: "memory")
; #define PG8_WAIT_L(n) asm volatile("s_waitcnt lgkmcnt(" #n ")" ::: "memory")
; #define PG8_BAR __builtin_amdgcn_s_barrier()
; #define PG8_SCHED __builtin_amdgcn_sched_barrier(0)
; template <class Epi, class Sched, bool ALIGN_EPI = false, bool SP2 = false>
; __device__ __forceinline__ void gemm_phase(PG8_LAS unsigned char* lds, const Gemm g, const Sched& S, const Epi& E) {
;     ...
;             PG8_WAIT_V(8); PG8_WAIT_L(0); PG8_BAR; PG8_MMA(1, 0, At, B0); PG8_MMA(1, 1, At, B1); PG8_BAR; PG8_SCHED;
;             PG8_LDB(B0, 1, 0); PG8_LDB(B1, 1, 1); PG8_SCHED; PG8_LDA(At, 1, 0); PG8_STAGE(PG8_SA(0, 1), a2 + hstepA, voffA);
;             PG8_WAIT_V(8); PG8_WAIT_L(0); PG8_BAR; PG8_MMA(0, 0, At, B0); PG8_MMA(0, 1, At, B1); PG8_BAR; PG8_SCHED;
	s_setprio 1
	v_mfma_f32_16x16x32_bf16 v[60:63], v[130:133], v[184:187], v[60:63]
	v_mfma_f32_16x16x32_bf16 v[56:59], v[138:141], v[184:187], v[56:59]
	v_mfma_f32_16x16x32_bf16 v[44:47], v[130:133], v[192:195], v[44:47]
	v_mfma_f32_16x16x32_bf16 v[40:43], v[138:141], v[192:195], v[40:43]
	v_mfma_f32_16x16x32_bf16 v[28:31], v[130:133], v[214:217], v[28:31]
	v_mfma_f32_16x16x32_bf16 v[24:27], v[138:141], v[214:217], v[24:27]
	v_mfma_f32_16x16x32_bf16 v[12:15], v[130:133], v[242:245], v[12:15]
	v_mfma_f32_16x16x32_bf16 v[8:11], v[138:141], v[242:245], v[8:11]
	v_mfma_f32_16x16x32_bf16 v[60:63], v[134:137], v[188:191], v[60:63]
	v_mfma_f32_16x16x32_bf16 v[56:59], v[142:145], v[188:191], v[56:59]
	v_mfma_f32_16x16x32_bf16 v[44:47], v[134:137], v[210:213], v[44:47]
	v_mfma_f32_16x16x32_bf16 v[40:43], v[142:145], v[210:213], v[40:43]
	v_mfma_f32_16x16x32_bf16 v[28:31], v[134:137], v[218:221], v[28:31]
	v_mfma_f32_16x16x32_bf16 v[24:27], v[142:145], v[218:221], v[24:27]
	v_mfma_f32_16x16x32_bf16 v[12:15], v[134:137], v[246:249], v[12:15]
	v_mfma_f32_16x16x32_bf16 v[8:11], v[142:145], v[246:249], v[8:11]
	s_setprio 0
	s_setprio 1
	v_mfma_f32_16x16x32_bf16 v[52:55], v[158:161], v[184:187], v[52:55]
	v_mfma_f32_16x16x32_bf16 v[48:51], v[166:169], v[184:187], v[48:51]
	v_mfma_f32_16x16x32_bf16 v[36:39], v[158:161], v[192:195], v[36:39]
	v_mfma_f32_16x16x32_bf16 v[32:35], v[166:169], v[192:195], v[32:35]
	v_mfma_f32_16x16x32_bf16 v[20:23], v[158:161], v[214:217], v[20:23]
	v_mfma_f32_16x16x32_bf16 v[16:19], v[166:169], v[214:217], v[16:19]
	v_mfma_f32_16x16x32_bf16 v[4:7], v[158:161], v[242:245], v[4:7]
	v_mfma_f32_16x16x32_bf16 v[0:3], v[166:169], v[242:245], v[0:3]
	v_mfma_f32_16x16x32_bf16 v[52:55], v[162:165], v[188:191], v[52:55]
	v_mfma_f32_16x16x32_bf16 v[48:51], v[178:181], v[188:191], v[48:51]
	v_mfma_f32_16x16x32_bf16 v[36:39], v[162:165], v[210:213], v[36:39]
	v_mfma_f32_16x16x32_bf16 v[32:35], v[178:181], v[210:213], v[32:35]
	v_mfma_f32_16x16x32_bf16 v[20:23], v[162:165], v[218:221], v[20:23]
	v_mfma_f32_16x16x32_bf16 v[16:19], v[178:181], v[218:221], v[16:19]
	v_mfma_f32_16x16x32_bf16 v[4:7], v[162:165], v[246:249], v[4:7]
	v_mfma_f32_16x16x32_bf16 v[0:3], v[178:181], v[246:249], v[0:3]
	s_setprio 0
	s_barrier
	s_add_i32 s41, 0, 0x18000
	v_add_u32_e32 v64, s41, v175
	s_add_i32 s60, 0, 0x1c000
	ds_read_b128 v[130:133], v64
	ds_read_b128 v[134:137], v64 offset:1024
	ds_read_b128 v[138:141], v64 offset:2048
	ds_read_b128 v[142:145], v64 offset:3072
	v_add_u32_e32 v64, s60, v175
	ds_read_b128 v[158:161], v64
	ds_read_b128 v[162:165], v64 offset:1024
	ds_read_b128 v[166:169], v64 offset:2048
	ds_read_b128 v[178:181], v64 offset:3072
	s_add_u32 s30, s30, 0x40000
	s_addc_u32 s31, s31, 0
	s_mov_b32 m0, s65
	v_lshl_add_u64 v[250:251], s[30:31], 0, v[152:153]
	ds_read_b128 v[184:187], v183 offset:32768
	ds_read_b128 v[188:191], v183 offset:33792
	ds_read_b128 v[192:195], v183 offset:34816
	ds_read_b128 v[210:213], v183 offset:35840
	ds_read_b128 v[214:217], v183 offset:36864
	ds_read_b128 v[218:221], v183 offset:37888
	ds_read_b128 v[242:245], v183 offset:38912
	ds_read_b128 v[246:249], v183 offset:39936
	global_load_lds_dwordx4 v[250:251], off
	v_lshl_add_u64 v[250:251], s[30:31], 0, v[148:149]
	s_mov_b32 m0, s68
	s_nop 0
	global_load_lds_dwordx4 v[250:251], off
	s_waitcnt vmcnt(8)
	s_waitcnt lgkmcnt(0)
	s_barrier
	s_setprio 1
	v_mfma_f32_16x16x32_bf16 v[126:129], v[130:133], v[184:187], v[126:129]
	v_mfma_f32_16x16x32_bf16 v[122:125], v[138:141], v[184:187], v[122:125]
	v_mfma_f32_16x16x32_bf16 v[110:113], v[130:133], v[192:195], v[110:113]
	v_mfma_f32_16x16x32_bf16 v[106:109], v[138:141], v[192:195], v[106:109]
	v_mfma_f32_16x16x32_bf16 v[94:97], v[130:133], v[214:217], v[94:97]
	v_mfma_f32_16x16x32_bf16 v[90:93], v[138:141], v[214:217], v[90:93]
	v_mfma_f32_16x16x32_bf16 v[78:81], v[130:133], v[242:245], v[78:81]
	v_mfma_f32_16x16x32_bf16 v[74:77], v[138:141], v[242:245], v[74:77]
	v_mfma_f32_16x16x32_bf16 v[126:129], v[134:137], v[188:191], v[126:129]
	v_mfma_f32_16x16x32_bf16 v[122:125], v[142:145], v[188:191], v[122:125]
	v_mfma_f32_16x16x32_bf16 v[110:113], v[134:137], v[210:213], v[110:113]
	v_mfma_f32_16x16x32_bf16 v[106:109], v[142:145], v[210:213], v[106:109]
	v_mfma_f32_16x16x32_bf16 v[94:97], v[134:137], v[218:221], v[94:97]
	v_mfma_f32_16x16x32_bf16 v[90:93], v[142:145], v[218:221], v[90:93]
	v_mfma_f32_16x16x32_bf16 v[78:81], v[134:137], v[246:249], v[78:81]
	v_mfma_f32_16x16x32_bf16 v[74:77], v[142:145], v[246:249], v[74:77]
	s_setprio 0
	s_setprio 1
	v_mfma_f32_16x16x32_bf16 v[118:121], v[158:161], v[184:187], v[118:121]
	v_mfma_f32_16x16x32_bf16 v[114:117], v[166:169], v[184:187], v[114:117]
	v_mfma_f32_16x16x32_bf16 v[102:105], v[158:161], v[192:195], v[102:105]
	v_mfma_f32_16x16x32_bf16 v[98:101], v[166:169], v[192:195], v[98:101]
	v_mfma_f32_16x16x32_bf16 v[86:89], v[158:161], v[214:217], v[86:89]
	v_mfma_f32_16x16x32_bf16 v[82:85], v[166:169], v[214:217], v[82:85]
	v_mfma_f32_16x16x32_bf16 v[70:73], v[158:161], v[242:245], v[70:73]
	v_mfma_f32_16x16x32_bf16 v[66:69], v[166:169], v[242:245], v[66:69]
	v_mfma_f32_16x16x32_bf16 v[118:121], v[162:165], v[188:191], v[118:121]
	v_mfma_f32_16x16x32_bf16 v[114:117], v[178:181], v[188:191], v[114:117]
	v_mfma_f32_16x16x32_bf16 v[102:105], v[162:165], v[210:213], v[102:105]
	v_mfma_f32_16x16x32_bf16 v[98:101], v[178:181], v[210:213], v[98:101]
	v_mfma_f32_16x16x32_bf16 v[86:89], v[162:165], v[218:221], v[86:89]
	v_mfma_f32_16x16x32_bf16 v[82:85], v[178:181], v[218:221], v[82:85]
	v_mfma_f32_16x16x32_bf16 v[70:73], v[162:165], v[246:249], v[70:73]
	v_mfma_f32_16x16x32_bf16 v[66:69], v[178:181], v[246:249], v[66:69]
	s_setprio 0
	s_barrier
; #define PG8_STAGE(bufoff, gbase, voff) do { _Pragma("unroll") for (int _i = 0; _i < 2; ++_i) \
;         __builtin_amdgcn_global_load_lds((const unsigned*)((const char*)(gbase) + (voff)[_i]), (PG8_LAS unsigned*)(lds + (bufoff) + ldsw + _i * 8192), 16, 0, 0); } while (0)
; #define PG8_LDA(dst, b, h) do { _Pragma("unroll") for (int m = 0; m < 4; ++m) _Pragma("unroll") for (int k = 0; k < 2; ++k) dst[m][k] = *(const PG8_LAS bf16x8*)(lds + PG8_SA(b, h) + aoff + m * 2048 + k * 1024); } while (0)
; #define PG8_MMA(ai, bj, At, Bt) do { __builtin_amdgcn_s_setprio(1); _Pragma("unroll") for (int m = 0; m < 4; ++m) _Pragma("unroll") for (int n = 0; n < 2; ++n) _Pragma("unroll") for (int k = 0; k < 2; ++k) \
;         acc[ai][bj][m][n] = __builtin_amdgcn_mfma_f32_16x16x32_bf16(Bt[n][k], At[m][k], acc[ai][bj][m][n], 0, 0, 0); __builtin_amdgcn_s_setprio(0); } while (0)
; #define PG8_WAIT_V(n) asm volatile("s_waitcnt vmcnt(" #n ")" ::: "memory")
; #define PG8_WAIT_L(n) asm volatile("s_waitcnt lgkmcnt(" #n ")" ::: "memory")
; #define PG8_BAR __builtin_amdgcn_s_barrier()
; #define PG8_SCHED __builtin_amdgcn_sched_barrier(0)
; template <class Epi, class Sched, bool ALIGN_EPI = false, bool SP2 = false>
; __device__ __forceinline__ void gemm_phase(PG8_LAS unsigned char* lds, const Gemm g, const Sched& S, const Epi& E) {
;     ...
;             PG8_LDA(At, 1, 1); PG8_STAGE(PG8_SB(1, 0), b3, voffB); PG8_STAGE(PG8_SB(1, 1), b3 + hstepB, voffB); PG8_STAGE(PG8_SA(1, 0), a3, voffA);
;             PG8_WAIT_V(8); PG8_WAIT_L(0); PG8_BAR; PG8_MMA(1, 0, At, B0); PG8_MMA(1, 1, At, B1); PG8_BAR; PG8_SCHED;
;     ...
;         if constexpr (ALIGN_EPI) { if (wr == 0) PG8_BAR; }
	s_add_i32 s30, s41, s45
	v_lshl_add_u64 v[172:173], v[172:173], 0, s[48:49]
	s_mov_b32 m0, s30
	ds_read_b128 v[184:187], v183 offset:49152
	ds_read_b128 v[188:191], v183 offset:50176
	ds_read_b128 v[192:195], v183 offset:51200
	ds_read_b128 v[210:213], v183 offset:52224
	ds_read_b128 v[214:217], v183 offset:53248
	ds_read_b128 v[218:221], v183 offset:54272
	ds_read_b128 v[242:245], v183 offset:55296
	ds_read_b128 v[246:249], v183 offset:56320
	global_load_lds_dwordx4 v[172:173], off
	s_add_i32 m0, s30, 0x2000
	s_add_u32 s20, s20, 0x40080
	v_lshl_add_u64 v[172:173], v[222:223], 0, s[48:49]
	s_addc_u32 s21, s21, 0
	s_add_i32 s30, s60, s45
	global_load_lds_dwordx4 v[172:173], off
	v_lshl_add_u64 v[172:173], s[20:21], 0, v[150:151]
	s_mov_b32 m0, s30
	s_nop 0
	global_load_lds_dwordx4 v[172:173], off
	v_lshl_add_u64 v[172:173], s[20:21], 0, v[146:147]
	s_add_i32 m0, s30, 0x2000
	s_nop 0
	global_load_lds_dwordx4 v[172:173], off
	v_lshl_add_u64 v[172:173], v[230:231], 0, s[48:49]
	s_mov_b32 m0, s69
	s_nop 0
	global_load_lds_dwordx4 v[172:173], off
	v_lshl_add_u64 v[172:173], v[232:233], 0, s[48:49]
	s_mov_b32 m0, s70
	s_nop 0
	global_load_lds_dwordx4 v[172:173], off
	s_waitcnt vmcnt(8)
	s_waitcnt lgkmcnt(0)
	s_barrier
	s_setprio 1
	v_mfma_f32_16x16x32_bf16 v[60:63], v[130:133], v[184:187], v[60:63]
	v_mfma_f32_16x16x32_bf16 v[56:59], v[138:141], v[184:187], v[56:59]
	v_mfma_f32_16x16x32_bf16 v[44:47], v[130:133], v[192:195], v[44:47]
	v_mfma_f32_16x16x32_bf16 v[40:43], v[138:141], v[192:195], v[40:43]
	v_mfma_f32_16x16x32_bf16 v[28:31], v[130:133], v[214:217], v[28:31]
	v_mfma_f32_16x16x32_bf16 v[24:27], v[138:141], v[214:217], v[24:27]
	v_mfma_f32_16x16x32_bf16 v[12:15], v[130:133], v[242:245], v[12:15]
	v_mfma_f32_16x16x32_bf16 v[8:11], v[138:141], v[242:245], v[8:11]
	v_mfma_f32_16x16x32_bf16 v[60:63], v[134:137], v[188:191], v[60:63]
	v_mfma_f32_16x16x32_bf16 v[56:59], v[142:145], v[188:191], v[56:59]
	v_mfma_f32_16x16x32_bf16 v[44:47], v[134:137], v[210:213], v[44:47]
	v_mfma_f32_16x16x32_bf16 v[40:43], v[142:145], v[210:213], v[40:43]
	v_mfma_f32_16x16x32_bf16 v[28:31], v[134:137], v[218:221], v[28:31]
	v_mfma_f32_16x16x32_bf16 v[24:27], v[142:145], v[218:221], v[24:27]
	v_mfma_f32_16x16x32_bf16 v[12:15], v[134:137], v[246:249], v[12:15]
	v_mfma_f32_16x16x32_bf16 v[8:11], v[142:145], v[246:249], v[8:11]
	s_setprio 0
	s_setprio 1
	v_mfma_f32_16x16x32_bf16 v[52:55], v[158:161], v[184:187], v[52:55]
	v_mfma_f32_16x16x32_bf16 v[48:51], v[166:169], v[184:187], v[48:51]
	v_mfma_f32_16x16x32_bf16 v[36:39], v[158:161], v[192:195], v[36:39]
	v_mfma_f32_16x16x32_bf16 v[32:35], v[166:169], v[192:195], v[32:35]
	v_mfma_f32_16x16x32_bf16 v[20:23], v[158:161], v[214:217], v[20:23]
	v_mfma_f32_16x16x32_bf16 v[16:19], v[166:169], v[214:217], v[16:19]
	v_mfma_f32_16x16x32_bf16 v[4:7], v[158:161], v[242:245], v[4:7]
	v_mfma_f32_16x16x32_bf16 v[0:3], v[166:169], v[242:245], v[0:3]
	v_mfma_f32_16x16x32_bf16 v[52:55], v[162:165], v[188:191], v[52:55]
	v_mfma_f32_16x16x32_bf16 v[48:51], v[178:181], v[188:191], v[48:51]
	v_mfma_f32_16x16x32_bf16 v[36:39], v[162:165], v[210:213], v[36:39]
	v_mfma_f32_16x16x32_bf16 v[32:35], v[178:181], v[210:213], v[32:35]
	v_mfma_f32_16x16x32_bf16 v[20:23], v[162:165], v[218:221], v[20:23]
	v_mfma_f32_16x16x32_bf16 v[16:19], v[178:181], v[218:221], v[16:19]
	v_mfma_f32_16x16x32_bf16 v[4:7], v[162:165], v[246:249], v[4:7]
	v_mfma_f32_16x16x32_bf16 v[0:3], v[178:181], v[246:249], v[0:3]
	s_setprio 0
	s_barrier
	s_add_i32 s43, s43, 2
	s_add_u32 s18, s18, 0x100
	s_addc_u32 s19, s19, 0
	s_add_u32 s24, s24, 0x100
	s_addc_u32 s25, s25, 0
	s_cmp_gt_u32 s43, 13
	s_cbranch_scc0 .LBB0_1450
	s_and_b64 vcc, exec, s[8:9]
	s_cbranch_vccz .LBB0_1453
	s_barrier

; #define PG8_STAGE(bufoff, gbase, voff) do { _Pragma("unroll") for (int _i = 0; _i < 2; ++_i) \
;         __builtin_amdgcn_global_load_lds((const unsigned*)((const char*)(gbase) + (voff)[_i]), (PG8_LAS unsigned*)(lds + (bufoff) + ldsw + _i * 8192), 16, 0, 0); } while (0)
; #define PG8_LDA(dst, b, h) do { _Pragma("unroll") for (int m = 0; m < 4; ++m) _Pragma("unroll") for (int k = 0; k < 2; ++k) dst[m][k] = *(const PG8_LAS bf16x8*)(lds + PG8_SA(b, h) + aoff + m * 2048 + k * 1024); } while (0)
; #define PG8_LDB(dst, b, h) do { _Pragma("unroll") for (int n = 0; n < 2; ++n) _Pragma("unroll") for (int k = 0; k < 2; ++k) dst[n][k] = *(const PG8_LAS bf16x8*)(lds + PG8_SB(b, h) + boff + n * 2048 + k * 1024); } while (0)
; #define PG8_MMA(ai, bj, At, Bt) do { __builtin_amdgcn_s_setprio(1); _Pragma("unroll") for (int m = 0; m < 4; ++m) _Pragma("unroll") for (int n = 0; n < 2; ++n) _Pragma("unroll") for (int k = 0; k < 2; ++k) \
;         acc[ai][bj][m][n] = __builtin_amdgcn_mfma_f32_16x16x32_bf16(Bt[n][k], At[m][k], acc[ai][bj][m][n], 0, 0, 0); __builtin_amdgcn_s_setprio(0); } while (0)
; #define PG8_WAIT_V(n) asm volatile("s_waitcnt vmcnt(" #n ")" ::: "memory")
; #define PG8_WAIT_L(n) asm volatile("s_waitcnt lgkmcnt(" #n ")" ::: "memory")
; #define PG8_BAR __builtin_amdgcn_s_barrier()
; #define PG8_SCHED __builtin_amdgcn_sched_barrier(0)
; template <class Epi, class Sched, bool ALIGN_EPI = false, bool SP2 = false>
; __device__ __forceinline__ void gemm_phase(PG8_LAS unsigned char* lds, const Gemm g, const Sched& S, const Epi& E) {
;     ...
;         for (int t = 0; t < nt; t += 2) {
;             const bool last = (t == nt - 2);
;             const char* a1 = cA + (size_t)(t + 1) * kstep;
;             const char* a2 = last ? nA : cA + (size_t)(t + 2) * kstep; const char* b2 = last ? nB : cB + (size_t)(t + 2) * kstep;
;             const char* a3 = a2 + kstep; const char* b3 = b2 + kstep;
;             if (last && has_next) S.a_ready(nxt);
;             if constexpr (SP2) {
;             PG8_LDB(B0, 0, 0); PG8_LDB(B1, 0, 1); PG8_SCHED; PG8_LDA(At, 0, 0); PG8_STAGE(PG8_SA(1, 1), a1 + hstepA, voffA);
;             PG8_WAIT_V(8); PG8_WAIT_L(0); PG8_BAR; PG8_MMA(0, 0, At, B0); PG8_MMA(0, 1, At, B1); PG8_BAR; PG8_SCHED;
;             PG8_LDA(At, 0, 1); PG8_STAGE(PG8_SB(0, 0), b2, voffB); PG8_STAGE(PG8_SB(0, 1), b2 + hstepB, voffB); PG8_STAGE(PG8_SA(0, 0), a2, voffA);
.LBB0_1522:
	s_add_u32 s8, s6, 0xf9950080
	s_addc_u32 s9, s7, -1
	s_cmp_lg_u32 s38, 40
	s_cselect_b32 s8, s8, 0
	s_cselect_b32 s9, s9, 0
	s_add_u32 s10, s4, s8
	s_addc_u32 s11, s5, s9
	s_add_i32 s39, 0, 0x10000
	s_add_u32 s8, s2, s8
	v_add_u32_e32 v141, s39, v139
	s_addc_u32 s9, s3, s9
	s_add_i32 s41, 0, 0x14000
	ds_read_b128 v[142:145], v141
	ds_read_b128 v[146:149], v141 offset:1024
	ds_read_b128 v[150:153], v141 offset:2048
	ds_read_b128 v[154:157], v141 offset:3072
	v_add_u32_e32 v141, s41, v139
	ds_read_b128 v[158:161], v141
	ds_read_b128 v[162:165], v141 offset:1024
	ds_read_b128 v[166:169], v141 offset:2048
	ds_read_b128 v[170:173], v141 offset:3072
	v_lshl_add_u64 v[222:223], v[132:133], 0, s[6:7]
	s_add_i32 m0, s21, 0xc000
	ds_read_b128 v[174:177], v140
	ds_read_b128 v[180:183], v140 offset:1024
	ds_read_b128 v[184:187], v140 offset:2048
	ds_read_b128 v[188:191], v140 offset:3072
	ds_read_b128 v[192:195], v140 offset:4096
	ds_read_b128 v[210:213], v140 offset:5120
	ds_read_b128 v[214:217], v140 offset:6144
	ds_read_b128 v[218:221], v140 offset:7168
	global_load_lds_dwordx4 v[222:223], off
	v_lshl_add_u64 v[222:223], v[134:135], 0, s[6:7]
	s_add_i32 m0, s21, 0xe000
	s_nop 0
	global_load_lds_dwordx4 v[222:223], off
	s_waitcnt vmcnt(8)
	s_waitcnt lgkmcnt(0)
	s_barrier
	s_setprio 1
	v_mfma_f32_16x16x32_bf16 v[126:129], v[142:145], v[174:177], v[126:129]
	v_mfma_f32_16x16x32_bf16 v[122:125], v[150:153], v[174:177], v[122:125]
	v_mfma_f32_16x16x32_bf16 v[110:113], v[142:145], v[184:187], v[110:113]
	v_mfma_f32_16x16x32_bf16 v[106:109], v[150:153], v[184:187], v[106:109]
	v_mfma_f32_16x16x32_bf16 v[94:97], v[142:145], v[192:195], v[94:97]
	v_mfma_f32_16x16x32_bf16 v[90:93], v[150:153], v[192:195], v[90:93]
	v_mfma_f32_16x16x32_bf16 v[78:81], v[142:145], v[214:217], v[78:81]
	v_mfma_f32_16x16x32_bf16 v[74:77], v[150:153], v[214:217], v[74:77]
	v_mfma_f32_16x16x32_bf16 v[126:129], v[146:149], v[180:183], v[126:129]
	v_mfma_f32_16x16x32_bf16 v[122:125], v[154:157], v[180:183], v[122:125]
	v_mfma_f32_16x16x32_bf16 v[110:113], v[146:149], v[188:191], v[110:113]
	v_mfma_f32_16x16x32_bf16 v[106:109], v[154:157], v[188:191], v[106:109]
	v_mfma_f32_16x16x32_bf16 v[94:97], v[146:149], v[210:213], v[94:97]
	v_mfma_f32_16x16x32_bf16 v[90:93], v[154:157], v[210:213], v[90:93]
	v_mfma_f32_16x16x32_bf16 v[78:81], v[146:149], v[218:221], v[78:81]
	v_mfma_f32_16x16x32_bf16 v[74:77], v[154:157], v[218:221], v[74:77]
	s_setprio 0
	s_setprio 1
	v_mfma_f32_16x16x32_bf16 v[118:121], v[158:161], v[174:177], v[118:121]
	v_mfma_f32_16x16x32_bf16 v[114:117], v[166:169], v[174:177], v[114:117]
	v_mfma_f32_16x16x32_bf16 v[102:105], v[158:161], v[184:187], v[102:105]
	v_mfma_f32_16x16x32_bf16 v[98:101], v[166:169], v[184:187], v[98:101]
	v_mfma_f32_16x16x32_bf16 v[86:89], v[158:161], v[192:195], v[86:89]
	v_mfma_f32_16x16x32_bf16 v[82:85], v[166:169], v[192:195], v[82:85]
	v_mfma_f32_16x16x32_bf16 v[70:73], v[158:161], v[214:217], v[70:73]
	v_mfma_f32_16x16x32_bf16 v[66:69], v[166:169], v[214:217], v[66:69]
	v_mfma_f32_16x16x32_bf16 v[118:121], v[162:165], v[180:183], v[118:121]
	v_mfma_f32_16x16x32_bf16 v[114:117], v[170:173], v[180:183], v[114:117]
	v_mfma_f32_16x16x32_bf16 v[102:105], v[162:165], v[188:191], v[102:105]
	v_mfma_f32_16x16x32_bf16 v[98:101], v[170:173], v[188:191], v[98:101]
	v_mfma_f32_16x16x32_bf16 v[86:89], v[162:165], v[210:213], v[86:89]
	v_mfma_f32_16x16x32_bf16 v[82:85], v[170:173], v[210:213], v[82:85]
	v_mfma_f32_16x16x32_bf16 v[70:73], v[162:165], v[218:221], v[70:73]
	v_mfma_f32_16x16x32_bf16 v[66:69], v[170:173], v[218:221], v[66:69]
	s_setprio 0
	s_barrier
	s_add_i32 s39, s39, s20
	v_lshl_add_u64 v[222:223], s[8:9], 0, v[64:65]
	s_mov_b32 m0, s39
	ds_read_b128 v[174:177], v140 offset:16384
	ds_read_b128 v[180:183], v140 offset:17408
	ds_read_b128 v[184:187], v140 offset:18432
	ds_read_b128 v[188:191], v140 offset:19456
	ds_read_b128 v[192:195], v140 offset:20480
	ds_read_b128 v[210:213], v140 offset:21504
	ds_read_b128 v[214:217], v140 offset:22528
	ds_read_b128 v[218:221], v140 offset:23552
	global_load_lds_dwordx4 v[222:223], off
	s_add_i32 m0, s39, 0x2000
	s_add_u32 s44, s8, 0xb0000
	v_lshl_add_u64 v[230:231], s[8:9], 0, v[130:131]
	s_addc_u32 s45, s9, 0
	s_add_i32 s39, s41, s20
	global_load_lds_dwordx4 v[230:231], off
	v_lshl_add_u64 v[232:233], s[44:45], 0, v[64:65]
	s_mov_b32 m0, s39
	v_lshl_add_u64 v[242:243], s[10:11], 0, v[130:131]
	global_load_lds_dwordx4 v[232:233], off
	v_lshl_add_u64 v[232:233], s[44:45], 0, v[130:131]
	s_add_i32 m0, s39, 0x2000
	s_nop 0
	global_load_lds_dwordx4 v[232:233], off
	v_lshl_add_u64 v[232:233], s[10:11], 0, v[64:65]
	s_mov_b32 m0, s21
	s_nop 0
	global_load_lds_dwordx4 v[232:233], off
	s_mov_b32 m0, s22
	s_nop 0
	global_load_lds_dwordx4 v[242:243], off
	s_waitcnt vmcnt(8)
	s_waitcnt lgkmcnt(0)
	s_barrier
; #define PG8_STAGE(bufoff, gbase, voff) do { _Pragma("unroll") for (int _i = 0; _i < 2; ++_i) \
;         __builtin_amdgcn_global_load_lds((const unsigned*)((const char*)(gbase) + (voff)[_i]), (PG8_LAS unsigned*)(lds + (bufoff) + ldsw + _i * 8192), 16, 0, 0); } while (0)
; #define PG8_LDA(dst, b, h) do { _Pragma("unroll") for (int m = 0; m < 4; ++m) _Pragma("unroll") for (int k = 0; k < 2; ++k) dst[m][k] = *(const PG8_LAS bf16x8*)(lds + PG8_SA(b, h) + aoff + m * 2048 + k * 1024); } while (0)
; #define PG8_LDB(dst, b, h) do { _Pragma("unroll") for (int n = 0; n < 2; ++n) _Pragma("unroll") for (int k = 0; k < 2; ++k) dst[n][k] = *(const PG8_LAS bf16x8*)(lds + PG8_SB(b, h) + boff + n * 2048 + k * 1024); } while (0)
; #define PG8_MMA(ai, bj, At, Bt) do { __builtin_amdgcn_s_setprio(1); _Pragma("unroll") for (int m = 0; m < 4; ++m) _Pragma("unroll") for (int n = 0; n < 2; ++n) _Pragma("unroll") for (int k = 0; k < 2; ++k) \
;         acc[ai][bj][m][n] = __builtin_amdgcn_mfma_f32_16x16x32_bf16(Bt[n][k], At[m][k], acc[ai][bj][m][n], 0, 0, 0); __builtin_amdgcn_s_setprio(0); } while (0)
; #define PG8_WAIT_V(n) asm volatile("s_waitcnt vmcnt(" #n ")" ::: "memory")
; #define PG8_WAIT_L(n) asm volatile("s_waitcnt lgkmcnt(" #n ")" ::: "memory")
; #define PG8_BAR __builtin_amdgcn_s_barrier()
; #define PG8_SCHED __builtin_amdgcn_sched_barrier(0)
; template <class Epi, class Sched, bool ALIGN_EPI = false, bool SP2 = false>
; __device__ __forceinline__ void gemm_phase(PG8_LAS unsigned char* lds, const Gemm g, const Sched& S, const Epi& E) {
;     ...
;             PG8_WAIT_V(8); PG8_WAIT_L(0); PG8_BAR; PG8_MMA(1, 0, At, B0); PG8_MMA(1, 1, At, B1); PG8_BAR; PG8_SCHED;
;             PG8_LDB(B0, 1, 0); PG8_LDB(B1, 1, 1); PG8_SCHED; PG8_LDA(At, 1, 0); PG8_STAGE(PG8_SA(0, 1), a2 + hstepA, voffA);
;             PG8_WAIT_V(8); PG8_WAIT_L(0); PG8_BAR; PG8_MMA(0, 0, At, B0); PG8_MMA(0, 1, At, B1); PG8_BAR; PG8_SCHED;
	s_setprio 1
	v_mfma_f32_16x16x32_bf16 v[60:63], v[142:145], v[174:177], v[60:63]
	v_mfma_f32_16x16x32_bf16 v[56:59], v[150:153], v[174:177], v[56:59]
	v_mfma_f32_16x16x32_bf16 v[44:47], v[142:145], v[184:187], v[44:47]
	v_mfma_f32_16x16x32_bf16 v[40:43], v[150:153], v[184:187], v[40:43]
	v_mfma_f32_16x16x32_bf16 v[28:31], v[142:145], v[192:195], v[28:31]
	v_mfma_f32_16x16x32_bf16 v[24:27], v[150:153], v[192:195], v[24:27]
	v_mfma_f32_16x16x32_bf16 v[12:15], v[142:145], v[214:217], v[12:15]
	v_mfma_f32_16x16x32_bf16 v[8:11], v[150:153], v[214:217], v[8:11]
	v_mfma_f32_16x16x32_bf16 v[60:63], v[146:149], v[180:183], v[60:63]
	v_mfma_f32_16x16x32_bf16 v[56:59], v[154:157], v[180:183], v[56:59]
	v_mfma_f32_16x16x32_bf16 v[44:47], v[146:149], v[188:191], v[44:47]
	v_mfma_f32_16x16x32_bf16 v[40:43], v[154:157], v[188:191], v[40:43]
	v_mfma_f32_16x16x32_bf16 v[28:31], v[146:149], v[210:213], v[28:31]
	v_mfma_f32_16x16x32_bf16 v[24:27], v[154:157], v[210:213], v[24:27]
	v_mfma_f32_16x16x32_bf16 v[12:15], v[146:149], v[218:221], v[12:15]
	v_mfma_f32_16x16x32_bf16 v[8:11], v[154:157], v[218:221], v[8:11]
	s_setprio 0
	s_setprio 1
	v_mfma_f32_16x16x32_bf16 v[52:55], v[158:161], v[174:177], v[52:55]
	v_mfma_f32_16x16x32_bf16 v[48:51], v[166:169], v[174:177], v[48:51]
	v_mfma_f32_16x16x32_bf16 v[36:39], v[158:161], v[184:187], v[36:39]
	v_mfma_f32_16x16x32_bf16 v[32:35], v[166:169], v[184:187], v[32:35]
	v_mfma_f32_16x16x32_bf16 v[20:23], v[158:161], v[192:195], v[20:23]
	v_mfma_f32_16x16x32_bf16 v[16:19], v[166:169], v[192:195], v[16:19]
	v_mfma_f32_16x16x32_bf16 v[4:7], v[158:161], v[214:217], v[4:7]
	v_mfma_f32_16x16x32_bf16 v[0:3], v[166:169], v[214:217], v[0:3]
	v_mfma_f32_16x16x32_bf16 v[52:55], v[162:165], v[180:183], v[52:55]
	v_mfma_f32_16x16x32_bf16 v[48:51], v[170:173], v[180:183], v[48:51]
	v_mfma_f32_16x16x32_bf16 v[36:39], v[162:165], v[188:191], v[36:39]
	v_mfma_f32_16x16x32_bf16 v[32:35], v[170:173], v[188:191], v[32:35]
	v_mfma_f32_16x16x32_bf16 v[20:23], v[162:165], v[210:213], v[20:23]
	v_mfma_f32_16x16x32_bf16 v[16:19], v[170:173], v[210:213], v[16:19]
	v_mfma_f32_16x16x32_bf16 v[4:7], v[162:165], v[218:221], v[4:7]
	v_mfma_f32_16x16x32_bf16 v[0:3], v[170:173], v[218:221], v[0:3]
	s_setprio 0
	s_barrier
	s_add_i32 s39, 0, 0x18000
	v_add_u32_e32 v141, s39, v139
	s_add_i32 s41, 0, 0x1c000
	ds_read_b128 v[142:145], v141
	ds_read_b128 v[146:149], v141 offset:1024
	ds_read_b128 v[150:153], v141 offset:2048
	ds_read_b128 v[154:157], v141 offset:3072
	v_add_u32_e32 v141, s41, v139
	ds_read_b128 v[158:161], v141
	ds_read_b128 v[162:165], v141 offset:1024
	ds_read_b128 v[166:169], v141 offset:2048
	ds_read_b128 v[170:173], v141 offset:3072
	s_add_u32 s10, s10, 0xb0000
	s_addc_u32 s11, s11, 0
	s_mov_b32 m0, s24
	v_lshl_add_u64 v[244:245], s[10:11], 0, v[64:65]
	ds_read_b128 v[174:177], v140 offset:32768
	ds_read_b128 v[180:183], v140 offset:33792
	ds_read_b128 v[184:187], v140 offset:34816
	ds_read_b128 v[188:191], v140 offset:35840
	ds_read_b128 v[192:195], v140 offset:36864
	ds_read_b128 v[210:213], v140 offset:37888
	ds_read_b128 v[214:217], v140 offset:38912
	ds_read_b128 v[218:221], v140 offset:39936
	global_load_lds_dwordx4 v[244:245], off
	v_lshl_add_u64 v[244:245], s[10:11], 0, v[130:131]
	s_mov_b32 m0, s30
	s_nop 0
	global_load_lds_dwordx4 v[244:245], off
	s_waitcnt vmcnt(8)
	s_waitcnt lgkmcnt(0)
	s_barrier
	s_setprio 1
	v_mfma_f32_16x16x32_bf16 v[126:129], v[142:145], v[174:177], v[126:129]
	v_mfma_f32_16x16x32_bf16 v[122:125], v[150:153], v[174:177], v[122:125]
	v_mfma_f32_16x16x32_bf16 v[110:113], v[142:145], v[184:187], v[110:113]
	v_mfma_f32_16x16x32_bf16 v[106:109], v[150:153], v[184:187], v[106:109]
	v_mfma_f32_16x16x32_bf16 v[94:97], v[142:145], v[192:195], v[94:97]
	v_mfma_f32_16x16x32_bf16 v[90:93], v[150:153], v[192:195], v[90:93]
	v_mfma_f32_16x16x32_bf16 v[78:81], v[142:145], v[214:217], v[78:81]
	v_mfma_f32_16x16x32_bf16 v[74:77], v[150:153], v[214:217], v[74:77]
	v_mfma_f32_16x16x32_bf16 v[126:129], v[146:149], v[180:183], v[126:129]
	v_mfma_f32_16x16x32_bf16 v[122:125], v[154:157], v[180:183], v[122:125]
	v_mfma_f32_16x16x32_bf16 v[110:113], v[146:149], v[188:191], v[110:113]
	v_mfma_f32_16x16x32_bf16 v[106:109], v[154:157], v[188:191], v[106:109]
	v_mfma_f32_16x16x32_bf16 v[94:97], v[146:149], v[210:213], v[94:97]
	v_mfma_f32_16x16x32_bf16 v[90:93], v[154:157], v[210:213], v[90:93]
	v_mfma_f32_16x16x32_bf16 v[78:81], v[146:149], v[218:221], v[78:81]
	v_mfma_f32_16x16x32_bf16 v[74:77], v[154:157], v[218:221], v[74:77]
	s_setprio 0
	s_setprio 1
	v_mfma_f32_16x16x32_bf16 v[118:121], v[158:161], v[174:177], v[118:121]
	v_mfma_f32_16x16x32_bf16 v[114:117], v[166:169], v[174:177], v[114:117]
	v_mfma_f32_16x16x32_bf16 v[102:105], v[158:161], v[184:187], v[102:105]
	v_mfma_f32_16x16x32_bf16 v[98:101], v[166:169], v[184:187], v[98:101]
	v_mfma_f32_16x16x32_bf16 v[86:89], v[158:161], v[192:195], v[86:89]
	v_mfma_f32_16x16x32_bf16 v[82:85], v[166:169], v[192:195], v[82:85]
	v_mfma_f32_16x16x32_bf16 v[70:73], v[158:161], v[214:217], v[70:73]
	v_mfma_f32_16x16x32_bf16 v[66:69], v[166:169], v[214:217], v[66:69]
	v_mfma_f32_16x16x32_bf16 v[118:121], v[162:165], v[180:183], v[118:121]
	v_mfma_f32_16x16x32_bf16 v[114:117], v[170:173], v[180:183], v[114:117]
	v_mfma_f32_16x16x32_bf16 v[102:105], v[162:165], v[188:191], v[102:105]
	v_mfma_f32_16x16x32_bf16 v[98:101], v[170:173], v[188:191], v[98:101]
	v_mfma_f32_16x16x32_bf16 v[86:89], v[162:165], v[210:213], v[86:89]
	v_mfma_f32_16x16x32_bf16 v[82:85], v[170:173], v[210:213], v[82:85]
	v_mfma_f32_16x16x32_bf16 v[70:73], v[162:165], v[218:221], v[70:73]
	v_mfma_f32_16x16x32_bf16 v[66:69], v[170:173], v[218:221], v[66:69]
	s_setprio 0
	s_barrier
; #define PG8_STAGE(bufoff, gbase, voff) do { _Pragma("unroll") for (int _i = 0; _i < 2; ++_i) \
;         __builtin_amdgcn_global_load_lds((const unsigned*)((const char*)(gbase) + (voff)[_i]), (PG8_LAS unsigned*)(lds + (bufoff) + ldsw + _i * 8192), 16, 0, 0); } while (0)
; #define PG8_LDA(dst, b, h) do { _Pragma("unroll") for (int m = 0; m < 4; ++m) _Pragma("unroll") for (int k = 0; k < 2; ++k) dst[m][k] = *(const PG8_LAS bf16x8*)(lds + PG8_SA(b, h) + aoff + m * 2048 + k * 1024); } while (0)
; #define PG8_MMA(ai, bj, At, Bt) do { __builtin_amdgcn_s_setprio(1); _Pragma("unroll") for (int m = 0; m < 4; ++m) _Pragma("unroll") for (int n = 0; n < 2; ++n) _Pragma("unroll") for (int k = 0; k < 2; ++k) \
;         acc[ai][bj][m][n] = __builtin_amdgcn_mfma_f32_16x16x32_bf16(Bt[n][k], At[m][k], acc[ai][bj][m][n], 0, 0, 0); __builtin_amdgcn_s_setprio(0); } while (0)
; #define PG8_WAIT_V(n) asm volatile("s_waitcnt vmcnt(" #n ")" ::: "memory")
; #define PG8_WAIT_L(n) asm volatile("s_waitcnt lgkmcnt(" #n ")" ::: "memory")
; #define PG8_BAR __builtin_amdgcn_s_barrier()
; #define PG8_SCHED __builtin_amdgcn_sched_barrier(0)
; template <class Epi, class Sched, bool ALIGN_EPI = false, bool SP2 = false>
; __device__ __forceinline__ void gemm_phase(PG8_LAS unsigned char* lds, const Gemm g, const Sched& S, const Epi& E) {
;     ...
;             PG8_LDA(At, 1, 1); PG8_STAGE(PG8_SB(1, 0), b3, voffB); PG8_STAGE(PG8_SB(1, 1), b3 + hstepB, voffB); PG8_STAGE(PG8_SA(1, 0), a3, voffA);
;             PG8_WAIT_V(8); PG8_WAIT_L(0); PG8_BAR; PG8_MMA(1, 0, At, B0); PG8_MMA(1, 1, At, B1); PG8_BAR; PG8_SCHED;
;     ...
;     PG8_WAIT_V(0);
;     if constexpr (!ALIGN_EPI) { if (wr == 0) PG8_BAR; }
	s_add_i32 s10, s39, s20
	v_lshl_add_u64 v[222:223], v[222:223], 0, s[48:49]
	s_mov_b32 m0, s10
	ds_read_b128 v[174:177], v140 offset:49152
	ds_read_b128 v[180:183], v140 offset:50176
	ds_read_b128 v[184:187], v140 offset:51200
	ds_read_b128 v[188:191], v140 offset:52224
	ds_read_b128 v[192:195], v140 offset:53248
	ds_read_b128 v[210:213], v140 offset:54272
	ds_read_b128 v[214:217], v140 offset:55296
	ds_read_b128 v[218:221], v140 offset:56320
	global_load_lds_dwordx4 v[222:223], off
	s_add_i32 m0, s10, 0x2000
	s_add_u32 s8, s8, 0xb0080
	v_lshl_add_u64 v[222:223], v[230:231], 0, s[48:49]
	s_addc_u32 s9, s9, 0
	s_add_i32 s10, s41, s20
	global_load_lds_dwordx4 v[222:223], off
	v_lshl_add_u64 v[222:223], s[8:9], 0, v[64:65]
	s_mov_b32 m0, s10
	s_nop 0
	global_load_lds_dwordx4 v[222:223], off
	v_lshl_add_u64 v[222:223], s[8:9], 0, v[130:131]
	s_add_i32 m0, s10, 0x2000
	s_nop 0
	global_load_lds_dwordx4 v[222:223], off
	v_lshl_add_u64 v[222:223], v[232:233], 0, s[48:49]
	s_mov_b32 m0, s31
	s_nop 0
	global_load_lds_dwordx4 v[222:223], off
	v_lshl_add_u64 v[222:223], v[242:243], 0, s[48:49]
	s_mov_b32 m0, s34
	s_nop 0
	global_load_lds_dwordx4 v[222:223], off
	s_waitcnt vmcnt(8)
	s_waitcnt lgkmcnt(0)
	s_barrier
	s_setprio 1
	v_mfma_f32_16x16x32_bf16 v[60:63], v[142:145], v[174:177], v[60:63]
	v_mfma_f32_16x16x32_bf16 v[56:59], v[150:153], v[174:177], v[56:59]
	v_mfma_f32_16x16x32_bf16 v[44:47], v[142:145], v[184:187], v[44:47]
	v_mfma_f32_16x16x32_bf16 v[40:43], v[150:153], v[184:187], v[40:43]
	v_mfma_f32_16x16x32_bf16 v[28:31], v[142:145], v[192:195], v[28:31]
	v_mfma_f32_16x16x32_bf16 v[24:27], v[150:153], v[192:195], v[24:27]
	v_mfma_f32_16x16x32_bf16 v[12:15], v[142:145], v[214:217], v[12:15]
	v_mfma_f32_16x16x32_bf16 v[8:11], v[150:153], v[214:217], v[8:11]
	v_mfma_f32_16x16x32_bf16 v[60:63], v[146:149], v[180:183], v[60:63]
	v_mfma_f32_16x16x32_bf16 v[56:59], v[154:157], v[180:183], v[56:59]
	v_mfma_f32_16x16x32_bf16 v[44:47], v[146:149], v[188:191], v[44:47]
	v_mfma_f32_16x16x32_bf16 v[40:43], v[154:157], v[188:191], v[40:43]
	v_mfma_f32_16x16x32_bf16 v[28:31], v[146:149], v[210:213], v[28:31]
	v_mfma_f32_16x16x32_bf16 v[24:27], v[154:157], v[210:213], v[24:27]
	v_mfma_f32_16x16x32_bf16 v[12:15], v[146:149], v[218:221], v[12:15]
	v_mfma_f32_16x16x32_bf16 v[8:11], v[154:157], v[218:221], v[8:11]
	s_setprio 0
	s_setprio 1
	v_mfma_f32_16x16x32_bf16 v[52:55], v[158:161], v[174:177], v[52:55]
	v_mfma_f32_16x16x32_bf16 v[48:51], v[166:169], v[174:177], v[48:51]
	v_mfma_f32_16x16x32_bf16 v[36:39], v[158:161], v[184:187], v[36:39]
	v_mfma_f32_16x16x32_bf16 v[32:35], v[166:169], v[184:187], v[32:35]
	v_mfma_f32_16x16x32_bf16 v[20:23], v[158:161], v[192:195], v[20:23]
	v_mfma_f32_16x16x32_bf16 v[16:19], v[166:169], v[192:195], v[16:19]
	v_mfma_f32_16x16x32_bf16 v[4:7], v[158:161], v[214:217], v[4:7]
	v_mfma_f32_16x16x32_bf16 v[0:3], v[166:169], v[214:217], v[0:3]
	v_mfma_f32_16x16x32_bf16 v[52:55], v[162:165], v[180:183], v[52:55]
	v_mfma_f32_16x16x32_bf16 v[48:51], v[170:173], v[180:183], v[48:51]
	v_mfma_f32_16x16x32_bf16 v[36:39], v[162:165], v[188:191], v[36:39]
	v_mfma_f32_16x16x32_bf16 v[32:35], v[170:173], v[188:191], v[32:35]
	v_mfma_f32_16x16x32_bf16 v[20:23], v[162:165], v[210:213], v[20:23]
	v_mfma_f32_16x16x32_bf16 v[16:19], v[170:173], v[210:213], v[16:19]
	v_mfma_f32_16x16x32_bf16 v[4:7], v[162:165], v[218:221], v[4:7]
	v_mfma_f32_16x16x32_bf16 v[0:3], v[170:173], v[218:221], v[0:3]
	s_setprio 0
	s_barrier
	s_add_i32 s38, s38, 2
	s_add_u32 s6, s6, 0x100
	s_addc_u32 s7, s7, 0
	s_cmp_lt_u32 s38, 42
	s_cbranch_scc1 .LBB0_1522
	s_waitcnt vmcnt(0)
	s_cmpk_gt_u32 s19, 0xff
	s_cbranch_scc1 .LBB0_1525
	s_barrier
